# k19: k17 + MMA-phase tail SALU/VALU and loop back-edge counter block hoisted into the preceding load phase (strategy 9 loop-edge rotation)
# speedup vs baseline: 1.0183x; 1.0048x over previous
; #define PG8_STAGE(bufoff, gbase, voff) do { _Pragma("unroll") for (int _i = 0; _i < 2; ++_i) \
;         __builtin_amdgcn_global_load_lds((const unsigned*)((const char*)(gbase) + (voff)[_i]), (LAS unsigned*)(lds + (bufoff) + ldsw + _i * 8192), 16, 0, 0); } while (0)
; #define PG8_LDA(dst, b, h) do { _Pragma("unroll") for (int m = 0; m < 4; ++m) _Pragma("unroll") for (int k = 0; k < 2; ++k) dst[m][k] = *(const LAS bf16x8*)(lds + PG8_SA(b, h) + aoff + m * 2048 + k * 1024); } while (0)
; #define PG8_LDB(dst, b, h) do { _Pragma("unroll") for (int n = 0; n < 2; ++n) _Pragma("unroll") for (int k = 0; k < 2; ++k) dst[n][k] = *(const LAS bf16x8*)(lds + PG8_SB(b, h) + boff + n * 2048 + k * 1024); } while (0)
; #define PG8_MMA(ai, bj, At, Bt) do { __builtin_amdgcn_s_setprio(1); _Pragma("unroll") for (int m = 0; m < 4; ++m) _Pragma("unroll") for (int n = 0; n < 2; ++n) _Pragma("unroll") for (int k = 0; k < 2; ++k) \
;         acc[ai][bj][m][n] = __builtin_amdgcn_mfma_f32_16x16x32_bf16(Bt[n][k], At[m][k], acc[ai][bj][m][n], 0, 0, 0); __builtin_amdgcn_s_setprio(0); } while (0)
; #define PG8_BAR __builtin_amdgcn_s_barrier()
; template <class Epi>
; __device__ __forceinline__ void gemm_phase(LAS unsigned char* lds, const Gemm g, const Epi& E) {
;     ...
;         const bool has_next = S.next(ui + 1, nxt);
;         const char* nA = has_next ? (const char*)g.A + (size_t)g.mapA.src(nxt.pm) * tstepA + (size_t)nxt.pn * g.a_pn_step : cA;
;         const char* nB = has_next ? (const char*)g.Bt + (size_t)g.mapB.src(nxt.pn) * tstepB : cB;
;         for (int t = 0; t < nt; t += 2) {
;             const bool last = (t == nt - 2);
;             const char* a1 = cA + (size_t)(t + 1) * kstep;
;             const char* a2 = last ? nA : cA + (size_t)(t + 2) * kstep; const char* b2 = last ? nB : cB + (size_t)(t + 2) * kstep;
;             const char* a3 = a2 + kstep; const char* b3 = b2 + kstep;
;             PG8_LDB(B0, 0, 0); PG8_SCHED; PG8_LDA(At, 0, 0); PG8_STAGE(PG8_SA(1, 1), a1 + hstepA, voffA);
;             PG8_WAIT_L(8); PG8_BAR; PG8_WAIT_L(0); PG8_MMA(0, 0, At, B0); PG8_BAR; PG8_SCHED;
;             PG8_LDB(B1, 0, 1); PG8_STAGE(PG8_SB(0, 0), b2, voffB);
;             PG8_BAR; PG8_WAIT_L(0); PG8_MMA(0, 1, At, B1); PG8_BAR;
;             PG8_LDA(At, 0, 1); PG8_STAGE(PG8_SA(0, 0), a2, voffA);
;             PG8_BAR; PG8_WAIT_L(0); PG8_MMA(1, 0, At, B0); PG8_BAR; PG8_SCHED;
.LBB0_296:
	s_add_u32 s9, s16, s5
	s_addc_u32 s18, s17, 0
	s_add_u32 s36, s9, 0x100
	s_addc_u32 s60, s18, 0
	s_and_b64 s[0:1], s[58:59], exec
	s_cselect_b32 s67, s11, s60
	s_cselect_b32 s66, s10, s36
	s_add_u32 s0, s14, s5
	s_addc_u32 s1, s15, 0
	s_add_u32 s5, s0, 0x100
	s_addc_u32 s36, s1, 0
	s_add_i32 s73, 0, 0x10000
	s_and_b64 s[0:1], s[58:59], exec
	s_cselect_b32 s75, s13, s36
	s_cselect_b32 s74, s12, s5
	s_add_u32 s78, s9, 0x40080
	s_addc_u32 s79, s18, 0
	s_add_i32 s72, s73, s30
	s_add_i32 m0, s26, 0xc000
	s_add_i32 s50, s26, 0xe000
	s_add_i32 s27, 0, 0x14000
	s_add_i32 s24, s72, 0x2000
	s_add_u32 s64, s74, 0x10000
	v_add_u32_e32 v142, s73, v159
	s_addc_u32 s65, s75, 0
	s_add_i32 s18, s27, s30
	ds_read_b128 v[130:133], v142
	ds_read_b128 v[134:137], v142 offset:1024
	ds_read_b128 v[138:141], v142 offset:2048
	ds_read_b128 v[142:145], v142 offset:3072
	s_add_i32 s36, s18, 0x2000
	s_add_i32 vcc_hi, 0, 0x18000
	s_add_u32 s60, s66, 0x40000
	s_addc_u32 s61, s67, 0
	s_add_i32 vcc_lo, vcc_hi, s30
	s_add_i32 s9, 0, 0x1c000
	s_add_i32 s5, vcc_lo, 0x2000
	s_add_u32 s58, s74, 0x10080
	s_addc_u32 s59, s75, 0
	s_add_i32 s0, s9, s30
	s_add_i32 s1, s0, 0x2000
	v_lshl_add_u64 v[192:193], s[78:79], 0, v[152:153]
	ds_read_b128 v[154:157], v160
	ds_read_b128 v[162:165], v160 offset:1024
	ds_read_b128 v[166:169], v160 offset:2048
	ds_read_b128 v[170:173], v160 offset:3072
	ds_read_b128 v[174:177], v160 offset:4096
	ds_read_b128 v[180:183], v160 offset:5120
	ds_read_b128 v[184:187], v160 offset:6144
	ds_read_b128 v[188:191], v160 offset:7168
	global_load_lds_dwordx4 v[192:193], off
	v_lshl_add_u64 v[192:193], s[78:79], 0, v[148:149]
	s_mov_b32 m0, s50
	s_nop 0
	global_load_lds_dwordx4 v[192:193], off
	s_waitcnt lgkmcnt(8)
	s_barrier
	s_waitcnt lgkmcnt(0)
	v_mfma_f32_16x16x32_bf16 v[126:129], v[130:133], v[154:157], v[126:129]
	v_mfma_f32_16x16x32_bf16 v[122:125], v[138:141], v[154:157], v[122:125]
	v_mfma_f32_16x16x32_bf16 v[114:117], v[130:133], v[166:169], v[114:117]
	v_mfma_f32_16x16x32_bf16 v[110:113], v[138:141], v[166:169], v[110:113]
	v_mfma_f32_16x16x32_bf16 v[102:105], v[130:133], v[174:177], v[102:105]
	v_mfma_f32_16x16x32_bf16 v[94:97], v[138:141], v[174:177], v[94:97]
	v_mfma_f32_16x16x32_bf16 v[86:89], v[130:133], v[184:187], v[86:89]
	v_mfma_f32_16x16x32_bf16 v[78:81], v[138:141], v[184:187], v[78:81]
	v_mfma_f32_16x16x32_bf16 v[126:129], v[134:137], v[162:165], v[126:129]
	v_mfma_f32_16x16x32_bf16 v[122:125], v[142:145], v[162:165], v[122:125]
	v_mfma_f32_16x16x32_bf16 v[114:117], v[134:137], v[170:173], v[114:117]
	v_mfma_f32_16x16x32_bf16 v[110:113], v[142:145], v[170:173], v[110:113]
	v_mfma_f32_16x16x32_bf16 v[102:105], v[134:137], v[180:183], v[102:105]
	v_mfma_f32_16x16x32_bf16 v[94:97], v[142:145], v[180:183], v[94:97]
	v_mfma_f32_16x16x32_bf16 v[86:89], v[134:137], v[188:191], v[86:89]
	v_mfma_f32_16x16x32_bf16 v[78:81], v[142:145], v[188:191], v[78:81]
	s_barrier
	s_mov_b32 m0, s72
	v_add_u32_e32 v161, s27, v159
	v_lshl_add_u64 v[208:209], s[74:75], 0, v[150:151]
	ds_read_b128 v[192:195], v161
	ds_read_b128 v[196:199], v161 offset:1024
	ds_read_b128 v[200:203], v161 offset:2048
	ds_read_b128 v[204:207], v161 offset:3072
	global_load_lds_dwordx4 v[208:209], off
	v_lshl_add_u64 v[226:227], s[74:75], 0, v[146:147]
	s_mov_b32 m0, s24
	s_nop 0
	global_load_lds_dwordx4 v[226:227], off
	s_nop 1
	s_mov_b32 m0, s26
	v_lshl_add_u64 v[228:229], s[66:67], 0, v[152:153]
	s_barrier
	s_waitcnt lgkmcnt(0)
	v_mfma_f32_16x16x32_bf16 v[118:121], v[192:195], v[154:157], v[118:121]
	v_mfma_f32_16x16x32_bf16 v[106:109], v[200:203], v[154:157], v[106:109]
	v_mfma_f32_16x16x32_bf16 v[98:101], v[192:195], v[166:169], v[98:101]
	v_mfma_f32_16x16x32_bf16 v[90:93], v[200:203], v[166:169], v[90:93]
	v_mfma_f32_16x16x32_bf16 v[82:85], v[192:195], v[174:177], v[82:85]
	v_mfma_f32_16x16x32_bf16 v[74:77], v[200:203], v[174:177], v[74:77]
	v_mfma_f32_16x16x32_bf16 v[70:73], v[192:195], v[184:187], v[70:73]
	v_mfma_f32_16x16x32_bf16 v[66:69], v[200:203], v[184:187], v[66:69]
	v_mfma_f32_16x16x32_bf16 v[118:121], v[196:199], v[162:165], v[118:121]
	v_mfma_f32_16x16x32_bf16 v[106:109], v[204:207], v[162:165], v[106:109]
	v_mfma_f32_16x16x32_bf16 v[98:101], v[196:199], v[170:173], v[98:101]
	v_mfma_f32_16x16x32_bf16 v[90:93], v[204:207], v[170:173], v[90:93]
	v_mfma_f32_16x16x32_bf16 v[82:85], v[196:199], v[180:183], v[82:85]
	v_mfma_f32_16x16x32_bf16 v[74:77], v[204:207], v[180:183], v[74:77]
	v_mfma_f32_16x16x32_bf16 v[70:73], v[196:199], v[188:191], v[70:73]
	v_mfma_f32_16x16x32_bf16 v[66:69], v[204:207], v[188:191], v[66:69]
	s_barrier
	ds_read_b128 v[154:157], v160 offset:16384
	ds_read_b128 v[162:165], v160 offset:17408
	ds_read_b128 v[166:169], v160 offset:18432
	ds_read_b128 v[170:173], v160 offset:19456
	ds_read_b128 v[174:177], v160 offset:20480
	ds_read_b128 v[180:183], v160 offset:21504
	ds_read_b128 v[184:187], v160 offset:22528
	ds_read_b128 v[188:191], v160 offset:23552
	global_load_lds_dwordx4 v[228:229], off
	v_lshl_add_u64 v[230:231], s[66:67], 0, v[148:149]
	s_mov_b32 m0, s52
	s_nop 0
	global_load_lds_dwordx4 v[230:231], off
	s_barrier
; #define PG8_STAGE(bufoff, gbase, voff) do { _Pragma("unroll") for (int _i = 0; _i < 2; ++_i) \
;         __builtin_amdgcn_global_load_lds((const unsigned*)((const char*)(gbase) + (voff)[_i]), (LAS unsigned*)(lds + (bufoff) + ldsw + _i * 8192), 16, 0, 0); } while (0)
; #define PG8_LDA(dst, b, h) do { _Pragma("unroll") for (int m = 0; m < 4; ++m) _Pragma("unroll") for (int k = 0; k < 2; ++k) dst[m][k] = *(const LAS bf16x8*)(lds + PG8_SA(b, h) + aoff + m * 2048 + k * 1024); } while (0)
; #define PG8_LDB(dst, b, h) do { _Pragma("unroll") for (int n = 0; n < 2; ++n) _Pragma("unroll") for (int k = 0; k < 2; ++k) dst[n][k] = *(const LAS bf16x8*)(lds + PG8_SB(b, h) + boff + n * 2048 + k * 1024); } while (0)
; #define PG8_MMA(ai, bj, At, Bt) do { __builtin_amdgcn_s_setprio(1); _Pragma("unroll") for (int m = 0; m < 4; ++m) _Pragma("unroll") for (int n = 0; n < 2; ++n) _Pragma("unroll") for (int k = 0; k < 2; ++k) \
;         acc[ai][bj][m][n] = __builtin_amdgcn_mfma_f32_16x16x32_bf16(Bt[n][k], At[m][k], acc[ai][bj][m][n], 0, 0, 0); __builtin_amdgcn_s_setprio(0); } while (0)
; #define PG8_WAIT_V(n) asm volatile("s_waitcnt vmcnt(" #n ")" ::: "memory")
; #define PG8_WAIT_L(n) asm volatile("s_waitcnt lgkmcnt(" #n ")" ::: "memory")
; #define PG8_BAR __builtin_amdgcn_s_barrier()
; #define PG8_SCHED __builtin_amdgcn_sched_barrier(0)
; template <class Epi>
; __device__ __forceinline__ void gemm_phase(LAS unsigned char* lds, const Gemm g, const Epi& E) {
;     ...
;             PG8_LDB(B1, 0, 1); PG8_STAGE(PG8_SB(0, 0), b2, voffB);
;             PG8_BAR; PG8_WAIT_L(0); PG8_MMA(0, 1, At, B1); PG8_BAR;
;             PG8_LDA(At, 0, 1); PG8_STAGE(PG8_SA(0, 0), a2, voffA);
;             PG8_BAR; PG8_WAIT_L(0); PG8_MMA(1, 0, At, B0); PG8_BAR; PG8_SCHED;
;             PG8_STAGE(PG8_SB(0, 1), b2 + hstepB, voffB);
;             PG8_WAIT_V(6); PG8_BAR; PG8_MMA(1, 1, At, B1); PG8_BAR;
;             PG8_LDB(B0, 1, 0); PG8_SCHED; PG8_LDA(At, 1, 0); PG8_STAGE(PG8_SA(0, 1), a2 + hstepA, voffA);
;             PG8_WAIT_L(8); PG8_BAR; PG8_WAIT_L(0); PG8_MMA(0, 0, At, B0); PG8_BAR; PG8_SCHED;
;             PG8_LDB(B1, 1, 1); PG8_STAGE(PG8_SB(1, 0), b3, voffB);
;             PG8_BAR; PG8_WAIT_L(0); PG8_MMA(0, 1, At, B1); PG8_BAR;
;             PG8_LDA(At, 1, 1); PG8_STAGE(PG8_SA(1, 0), a3, voffA);
;             PG8_BAR; PG8_WAIT_L(0); PG8_MMA(1, 0, At, B0); PG8_BAR; PG8_SCHED;
	s_waitcnt lgkmcnt(0)
	v_mfma_f32_16x16x32_bf16 v[62:65], v[130:133], v[154:157], v[62:65]
	v_mfma_f32_16x16x32_bf16 v[58:61], v[138:141], v[154:157], v[58:61]
	v_mfma_f32_16x16x32_bf16 v[54:57], v[130:133], v[166:169], v[54:57]
	v_mfma_f32_16x16x32_bf16 v[46:49], v[138:141], v[166:169], v[46:49]
	v_mfma_f32_16x16x32_bf16 v[38:41], v[130:133], v[174:177], v[38:41]
	v_mfma_f32_16x16x32_bf16 v[30:33], v[138:141], v[174:177], v[30:33]
	v_mfma_f32_16x16x32_bf16 v[22:25], v[130:133], v[184:187], v[22:25]
	v_mfma_f32_16x16x32_bf16 v[14:17], v[138:141], v[184:187], v[14:17]
	v_mfma_f32_16x16x32_bf16 v[62:65], v[134:137], v[162:165], v[62:65]
	v_mfma_f32_16x16x32_bf16 v[58:61], v[142:145], v[162:165], v[58:61]
	v_mfma_f32_16x16x32_bf16 v[54:57], v[134:137], v[170:173], v[54:57]
	v_mfma_f32_16x16x32_bf16 v[46:49], v[142:145], v[170:173], v[46:49]
	v_mfma_f32_16x16x32_bf16 v[38:41], v[134:137], v[180:183], v[38:41]
	v_mfma_f32_16x16x32_bf16 v[30:33], v[142:145], v[180:183], v[30:33]
	v_mfma_f32_16x16x32_bf16 v[22:25], v[134:137], v[188:191], v[22:25]
	v_mfma_f32_16x16x32_bf16 v[14:17], v[142:145], v[188:191], v[14:17]
	s_barrier
	s_mov_b32 m0, s18
	v_lshl_add_u64 v[130:131], s[64:65], 0, v[150:151]
	global_load_lds_dwordx4 v[130:131], off
	v_lshl_add_u64 v[130:131], s[64:65], 0, v[146:147]
	s_mov_b32 m0, s36
	s_nop 0
	global_load_lds_dwordx4 v[130:131], off
	v_add_u32_e32 v142, vcc_hi, v159
	s_waitcnt vmcnt(6)
	s_barrier
	v_mfma_f32_16x16x32_bf16 v[50:53], v[192:195], v[154:157], v[50:53]
	v_mfma_f32_16x16x32_bf16 v[42:45], v[200:203], v[154:157], v[42:45]
	v_mfma_f32_16x16x32_bf16 v[34:37], v[192:195], v[166:169], v[34:37]
	v_mfma_f32_16x16x32_bf16 v[26:29], v[200:203], v[166:169], v[26:29]
	v_mfma_f32_16x16x32_bf16 v[18:21], v[192:195], v[174:177], v[18:21]
	v_mfma_f32_16x16x32_bf16 v[10:13], v[200:203], v[174:177], v[10:13]
	v_mfma_f32_16x16x32_bf16 v[6:9], v[192:195], v[184:187], v[6:9]
	v_mfma_f32_16x16x32_bf16 v[2:5], v[200:203], v[184:187], v[2:5]
	v_mfma_f32_16x16x32_bf16 v[50:53], v[196:199], v[162:165], v[50:53]
	v_mfma_f32_16x16x32_bf16 v[42:45], v[204:207], v[162:165], v[42:45]
	v_mfma_f32_16x16x32_bf16 v[34:37], v[196:199], v[170:173], v[34:37]
	v_mfma_f32_16x16x32_bf16 v[26:29], v[204:207], v[170:173], v[26:29]
	v_mfma_f32_16x16x32_bf16 v[18:21], v[196:199], v[180:183], v[18:21]
	v_mfma_f32_16x16x32_bf16 v[10:13], v[204:207], v[180:183], v[10:13]
	v_mfma_f32_16x16x32_bf16 v[6:9], v[196:199], v[188:191], v[6:9]
	v_mfma_f32_16x16x32_bf16 v[2:5], v[204:207], v[188:191], v[2:5]
	s_barrier
	ds_read_b128 v[130:133], v142
	ds_read_b128 v[134:137], v142 offset:1024
	ds_read_b128 v[138:141], v142 offset:2048
	ds_read_b128 v[142:145], v142 offset:3072
	s_mov_b32 m0, s53
	v_lshl_add_u64 v[192:193], s[60:61], 0, v[152:153]
	ds_read_b128 v[154:157], v160 offset:32768
	ds_read_b128 v[162:165], v160 offset:33792
	ds_read_b128 v[166:169], v160 offset:34816
	ds_read_b128 v[170:173], v160 offset:35840
	ds_read_b128 v[174:177], v160 offset:36864
	ds_read_b128 v[180:183], v160 offset:37888
	ds_read_b128 v[184:187], v160 offset:38912
	ds_read_b128 v[188:191], v160 offset:39936
	global_load_lds_dwordx4 v[192:193], off
	v_lshl_add_u64 v[192:193], s[60:61], 0, v[148:149]
	s_mov_b32 m0, s68
	s_nop 0
	global_load_lds_dwordx4 v[192:193], off
	s_waitcnt lgkmcnt(8)
	s_barrier
	s_waitcnt lgkmcnt(0)
	v_mfma_f32_16x16x32_bf16 v[126:129], v[130:133], v[154:157], v[126:129]
	v_mfma_f32_16x16x32_bf16 v[122:125], v[138:141], v[154:157], v[122:125]
	v_mfma_f32_16x16x32_bf16 v[114:117], v[130:133], v[166:169], v[114:117]
	v_mfma_f32_16x16x32_bf16 v[110:113], v[138:141], v[166:169], v[110:113]
	v_mfma_f32_16x16x32_bf16 v[102:105], v[130:133], v[174:177], v[102:105]
	v_mfma_f32_16x16x32_bf16 v[94:97], v[138:141], v[174:177], v[94:97]
	v_mfma_f32_16x16x32_bf16 v[86:89], v[130:133], v[184:187], v[86:89]
	v_mfma_f32_16x16x32_bf16 v[78:81], v[138:141], v[184:187], v[78:81]
	v_mfma_f32_16x16x32_bf16 v[126:129], v[134:137], v[162:165], v[126:129]
	v_mfma_f32_16x16x32_bf16 v[122:125], v[142:145], v[162:165], v[122:125]
	v_mfma_f32_16x16x32_bf16 v[114:117], v[134:137], v[170:173], v[114:117]
	v_mfma_f32_16x16x32_bf16 v[110:113], v[142:145], v[170:173], v[110:113]
	v_mfma_f32_16x16x32_bf16 v[102:105], v[134:137], v[180:183], v[102:105]
	v_mfma_f32_16x16x32_bf16 v[94:97], v[142:145], v[180:183], v[94:97]
	v_mfma_f32_16x16x32_bf16 v[86:89], v[134:137], v[188:191], v[86:89]
	v_mfma_f32_16x16x32_bf16 v[78:81], v[142:145], v[188:191], v[78:81]
	s_barrier
	s_mov_b32 m0, vcc_lo
	v_add_u32_e32 v161, s9, v159
	v_lshl_add_u64 v[208:209], v[208:209], 0, s[86:87]
	ds_read_b128 v[192:195], v161
	ds_read_b128 v[196:199], v161 offset:1024
	ds_read_b128 v[200:203], v161 offset:2048
	ds_read_b128 v[204:207], v161 offset:3072
	global_load_lds_dwordx4 v[208:209], off
	v_lshl_add_u64 v[208:209], v[226:227], 0, s[86:87]
	s_mov_b32 m0, s5
	s_nop 0
	global_load_lds_dwordx4 v[208:209], off
	s_nop 1
	s_mov_b32 m0, s71
	v_lshl_add_u64 v[208:209], v[228:229], 0, s[86:87]
	s_barrier
; #define PG8_STAGE(bufoff, gbase, voff) do { _Pragma("unroll") for (int _i = 0; _i < 2; ++_i) \
;         __builtin_amdgcn_global_load_lds((const unsigned*)((const char*)(gbase) + (voff)[_i]), (LAS unsigned*)(lds + (bufoff) + ldsw + _i * 8192), 16, 0, 0); } while (0)
; #define PG8_LDA(dst, b, h) do { _Pragma("unroll") for (int m = 0; m < 4; ++m) _Pragma("unroll") for (int k = 0; k < 2; ++k) dst[m][k] = *(const LAS bf16x8*)(lds + PG8_SA(b, h) + aoff + m * 2048 + k * 1024); } while (0)
; #define PG8_LDB(dst, b, h) do { _Pragma("unroll") for (int n = 0; n < 2; ++n) _Pragma("unroll") for (int k = 0; k < 2; ++k) dst[n][k] = *(const LAS bf16x8*)(lds + PG8_SB(b, h) + boff + n * 2048 + k * 1024); } while (0)
; #define PG8_WAIT_V(n) asm volatile("s_waitcnt vmcnt(" #n ")" ::: "memory")
; #define PG8_BAR __builtin_amdgcn_s_barrier()
; template <class Epi>
; __device__ __forceinline__ void gemm_phase(LAS unsigned char* lds, const Gemm g, const Epi& E) {
;     ...
;             PG8_WAIT_V(6); PG8_BAR; PG8_MMA(1, 1, At, B1); PG8_BAR;
;             PG8_LDB(B0, 1, 0); PG8_SCHED; PG8_LDA(At, 1, 0); PG8_STAGE(PG8_SA(0, 1), a2 + hstepA, voffA);
;             PG8_WAIT_L(8); PG8_BAR; PG8_WAIT_L(0); PG8_MMA(0, 0, At, B0); PG8_BAR; PG8_SCHED;
;             PG8_LDB(B1, 1, 1); PG8_STAGE(PG8_SB(1, 0), b3, voffB);
;             PG8_BAR; PG8_WAIT_L(0); PG8_MMA(0, 1, At, B1); PG8_BAR;
;             PG8_LDA(At, 1, 1); PG8_STAGE(PG8_SA(1, 0), a3, voffA);
;             PG8_BAR; PG8_WAIT_L(0); PG8_MMA(1, 0, At, B0); PG8_BAR; PG8_SCHED;
;             PG8_STAGE(PG8_SB(1, 1), b3 + hstepB, voffB);
;             PG8_WAIT_V(6); PG8_BAR; PG8_MMA(1, 1, At, B1); PG8_BAR;
;         }
;     __device__ __forceinline__ void operator()(const AccT& acc, const Unit& u, int wr, int wc, int fr, int fq) const {
;         asm volatile("" : "+v"(fr), "+v"(fq));
;         const int gpm = mapA.src(u.pm);
;         const int mb = gpm < 32 ? 32 : (gpm - 32) >> 3;
;         const int row0 = gpm * 256 + wr * 64 + fr, col0 = u.pn * 256 + wc * 32 + 4 * fq;
;         const float* gp = modl + ((size_t)mb * 6 + gi) * 1024;
;         f32x4 gv[2][2];
; #pragma unroll
;         for (int bj = 0; bj < 2; ++bj)
; #pragma unroll
;             for (int n = 0; n < 2; ++n) { gv[bj][n] = *(const f32x4*)(gp + col0 + bj * 128 + n * 16); if (scale) gv[bj][n] = gv[bj][n] * *(const f32x4*)(scale + col0 + bj * 128 + n * 16); }
	s_waitcnt lgkmcnt(0)
	v_mfma_f32_16x16x32_bf16 v[118:121], v[192:195], v[154:157], v[118:121]
	v_mfma_f32_16x16x32_bf16 v[106:109], v[200:203], v[154:157], v[106:109]
	v_mfma_f32_16x16x32_bf16 v[98:101], v[192:195], v[166:169], v[98:101]
	v_mfma_f32_16x16x32_bf16 v[90:93], v[200:203], v[166:169], v[90:93]
	v_mfma_f32_16x16x32_bf16 v[82:85], v[192:195], v[174:177], v[82:85]
	v_mfma_f32_16x16x32_bf16 v[74:77], v[200:203], v[174:177], v[74:77]
	v_mfma_f32_16x16x32_bf16 v[70:73], v[192:195], v[184:187], v[70:73]
	v_mfma_f32_16x16x32_bf16 v[66:69], v[200:203], v[184:187], v[66:69]
	v_mfma_f32_16x16x32_bf16 v[118:121], v[196:199], v[162:165], v[118:121]
	v_mfma_f32_16x16x32_bf16 v[106:109], v[204:207], v[162:165], v[106:109]
	v_mfma_f32_16x16x32_bf16 v[98:101], v[196:199], v[170:173], v[98:101]
	v_mfma_f32_16x16x32_bf16 v[90:93], v[204:207], v[170:173], v[90:93]
	v_mfma_f32_16x16x32_bf16 v[82:85], v[196:199], v[180:183], v[82:85]
	v_mfma_f32_16x16x32_bf16 v[74:77], v[204:207], v[180:183], v[74:77]
	v_mfma_f32_16x16x32_bf16 v[70:73], v[196:199], v[188:191], v[70:73]
	v_mfma_f32_16x16x32_bf16 v[66:69], v[204:207], v[188:191], v[66:69]
	s_barrier
	ds_read_b128 v[154:157], v160 offset:49152
	ds_read_b128 v[162:165], v160 offset:50176
	ds_read_b128 v[166:169], v160 offset:51200
	ds_read_b128 v[170:173], v160 offset:52224
	ds_read_b128 v[174:177], v160 offset:53248
	ds_read_b128 v[180:183], v160 offset:54272
	ds_read_b128 v[184:187], v160 offset:55296
	ds_read_b128 v[188:191], v160 offset:56320
	global_load_lds_dwordx4 v[208:209], off
	v_lshl_add_u64 v[208:209], v[230:231], 0, s[86:87]
	s_mov_b32 m0, s80
	s_nop 0
	global_load_lds_dwordx4 v[208:209], off
	s_barrier
	s_waitcnt lgkmcnt(0)
	v_mfma_f32_16x16x32_bf16 v[62:65], v[130:133], v[154:157], v[62:65]
	v_mfma_f32_16x16x32_bf16 v[58:61], v[138:141], v[154:157], v[58:61]
	v_mfma_f32_16x16x32_bf16 v[54:57], v[130:133], v[166:169], v[54:57]
	v_mfma_f32_16x16x32_bf16 v[46:49], v[138:141], v[166:169], v[46:49]
	v_mfma_f32_16x16x32_bf16 v[38:41], v[130:133], v[174:177], v[38:41]
	v_mfma_f32_16x16x32_bf16 v[30:33], v[138:141], v[174:177], v[30:33]
	v_mfma_f32_16x16x32_bf16 v[22:25], v[130:133], v[184:187], v[22:25]
	v_mfma_f32_16x16x32_bf16 v[14:17], v[138:141], v[184:187], v[14:17]
	v_mfma_f32_16x16x32_bf16 v[62:65], v[134:137], v[162:165], v[62:65]
	v_mfma_f32_16x16x32_bf16 v[58:61], v[142:145], v[162:165], v[58:61]
	v_mfma_f32_16x16x32_bf16 v[54:57], v[134:137], v[170:173], v[54:57]
	v_mfma_f32_16x16x32_bf16 v[46:49], v[142:145], v[170:173], v[46:49]
	v_mfma_f32_16x16x32_bf16 v[38:41], v[134:137], v[180:183], v[38:41]
	v_mfma_f32_16x16x32_bf16 v[30:33], v[142:145], v[180:183], v[30:33]
	v_mfma_f32_16x16x32_bf16 v[22:25], v[134:137], v[188:191], v[22:25]
	v_mfma_f32_16x16x32_bf16 v[14:17], v[142:145], v[188:191], v[14:17]
	s_barrier
	s_mov_b32 m0, s0
	v_lshl_add_u64 v[130:131], s[58:59], 0, v[150:151]
	global_load_lds_dwordx4 v[130:131], off
	v_lshl_add_u64 v[130:131], s[58:59], 0, v[146:147]
	s_mov_b32 m0, s1
	s_nop 0
	global_load_lds_dwordx4 v[130:131], off
	s_waitcnt vmcnt(6)
	s_barrier
	v_mfma_f32_16x16x32_bf16 v[50:53], v[192:195], v[154:157], v[50:53]
	v_mfma_f32_16x16x32_bf16 v[42:45], v[200:203], v[154:157], v[42:45]
	v_mfma_f32_16x16x32_bf16 v[34:37], v[192:195], v[166:169], v[34:37]
	v_mfma_f32_16x16x32_bf16 v[26:29], v[200:203], v[166:169], v[26:29]
	v_mfma_f32_16x16x32_bf16 v[18:21], v[192:195], v[174:177], v[18:21]
	v_mfma_f32_16x16x32_bf16 v[10:13], v[200:203], v[174:177], v[10:13]
	v_mfma_f32_16x16x32_bf16 v[6:9], v[192:195], v[184:187], v[6:9]
	v_mfma_f32_16x16x32_bf16 v[2:5], v[200:203], v[184:187], v[2:5]
	v_mfma_f32_16x16x32_bf16 v[50:53], v[196:199], v[162:165], v[50:53]
	v_mfma_f32_16x16x32_bf16 v[42:45], v[204:207], v[162:165], v[42:45]
	v_mfma_f32_16x16x32_bf16 v[34:37], v[196:199], v[170:173], v[34:37]
	v_mfma_f32_16x16x32_bf16 v[26:29], v[204:207], v[170:173], v[26:29]
	v_mfma_f32_16x16x32_bf16 v[18:21], v[196:199], v[180:183], v[18:21]
	v_mfma_f32_16x16x32_bf16 v[10:13], v[204:207], v[180:183], v[10:13]
	v_mfma_f32_16x16x32_bf16 v[6:9], v[196:199], v[188:191], v[6:9]
	v_mfma_f32_16x16x32_bf16 v[2:5], v[204:207], v[188:191], v[2:5]
	s_movk_i32 s5, 0x100
	s_andn2_b64 vcc, exec, s[28:29]
	s_mov_b64 s[58:59], -1
	s_mov_b64 s[28:29], 0
	s_barrier
	s_cbranch_vccz .LBB0_296
	s_cmp_ge_i32 s93, s31
	s_cselect_b32 s0, s44, 0
	s_add_i32 s0, s93, s0
	s_sub_i32 s1, s0, 32
	s_lshl_b32 s4, s4, 8
	s_ashr_i32 s1, s1, 3
	s_or_b32 s4, s4, s70
	v_mov_b32_e32 v130, v1
	v_mov_b32_e32 v161, v158
	s_mul_i32 s1, s1, 6
	s_cmp_gt_i32 s0, 31
	v_readlane_b32 s14, v255, 14
	v_lshl_add_u32 v154, v130, 2, s4
	s_cselect_b32 s4, s1, 0xc0
	s_ashr_i32 s5, s4, 31
	s_lshl_b64 s[4:5], s[4:5], 12
	v_readlane_b32 s15, v255, 15
	s_add_u32 s4, s14, s4
	v_ashrrev_i32_e32 v155, 31, v154
	s_addc_u32 s5, s15, s5
	v_lshlrev_b64 v[136:137], 2, v[154:155]
	v_lshl_add_u64 v[134:135], s[4:5], 0, v[136:137]
	v_add_co_u32_e32 v130, vcc, 0x2000, v134
	v_readlane_b32 s14, v254, 30
	s_nop 0
	v_addc_co_u32_e32 v131, vcc, 0, v135, vcc
	global_load_dwordx4 v[130:133], v[130:131], off
	v_readlane_b32 s15, v254, 31
	s_andn2_b64 vcc, exec, s[14:15]
	v_lshl_add_u64 v[156:157], s[6:7], 0, v[136:137]
	v_cndmask_b32_e64 v138, 0, 1, s[14:15]
	v_cmp_ne_u32_e64 s[4:5], 1, v138
	s_cbranch_vccnz .LBB0_299
	global_load_dwordx4 v[136:139], v[156:157], off
	s_waitcnt vmcnt(0)
	v_pk_mul_f32 v[132:133], v[132:133], v[138:139]
	v_pk_mul_f32 v[130:131], v[130:131], v[136:137]

; #define PG8_STAGE(bufoff, gbase, voff) do { _Pragma("unroll") for (int _i = 0; _i < 2; ++_i) \
;         __builtin_amdgcn_global_load_lds((const unsigned*)((const char*)(gbase) + (voff)[_i]), (LAS unsigned*)(lds + (bufoff) + ldsw + _i * 8192), 16, 0, 0); } while (0)
; #define PG8_LDA(dst, b, h) do { _Pragma("unroll") for (int m = 0; m < 4; ++m) _Pragma("unroll") for (int k = 0; k < 2; ++k) dst[m][k] = *(const LAS bf16x8*)(lds + PG8_SA(b, h) + aoff + m * 2048 + k * 1024); } while (0)
; #define PG8_LDB(dst, b, h) do { _Pragma("unroll") for (int n = 0; n < 2; ++n) _Pragma("unroll") for (int k = 0; k < 2; ++k) dst[n][k] = *(const LAS bf16x8*)(lds + PG8_SB(b, h) + boff + n * 2048 + k * 1024); } while (0)
; #define PG8_MMA(ai, bj, At, Bt) do { __builtin_amdgcn_s_setprio(1); _Pragma("unroll") for (int m = 0; m < 4; ++m) _Pragma("unroll") for (int n = 0; n < 2; ++n) _Pragma("unroll") for (int k = 0; k < 2; ++k) \
;         acc[ai][bj][m][n] = __builtin_amdgcn_mfma_f32_16x16x32_bf16(Bt[n][k], At[m][k], acc[ai][bj][m][n], 0, 0, 0); __builtin_amdgcn_s_setprio(0); } while (0)
; #define PG8_WAIT_L(n) asm volatile("s_waitcnt lgkmcnt(" #n ")" ::: "memory")
; #define PG8_BAR __builtin_amdgcn_s_barrier()
; #define PG8_SCHED __builtin_amdgcn_sched_barrier(0)
; template <class Epi>
; __device__ __forceinline__ void gemm_phase(LAS unsigned char* lds, const Gemm g, const Epi& E) {
;     ...
;         for (int t = 0; t < nt; t += 2) {
;             const bool last = (t == nt - 2);
;             const char* a1 = cA + (size_t)(t + 1) * kstep;
;             const char* a2 = last ? nA : cA + (size_t)(t + 2) * kstep; const char* b2 = last ? nB : cB + (size_t)(t + 2) * kstep;
;             const char* a3 = a2 + kstep; const char* b3 = b2 + kstep;
;             PG8_LDB(B0, 0, 0); PG8_SCHED; PG8_LDA(At, 0, 0); PG8_STAGE(PG8_SA(1, 1), a1 + hstepA, voffA);
;             PG8_WAIT_L(8); PG8_BAR; PG8_WAIT_L(0); PG8_MMA(0, 0, At, B0); PG8_BAR; PG8_SCHED;
;             PG8_LDB(B1, 0, 1); PG8_STAGE(PG8_SB(0, 0), b2, voffB);
;             PG8_BAR; PG8_WAIT_L(0); PG8_MMA(0, 1, At, B1); PG8_BAR;
;             PG8_LDA(At, 0, 1); PG8_STAGE(PG8_SA(0, 0), a2, voffA);
;             PG8_BAR; PG8_WAIT_L(0); PG8_MMA(1, 0, At, B0); PG8_BAR; PG8_SCHED;
.LBB0_331:
	s_add_u32 s60, s4, 0xfffc0080
	s_addc_u32 s61, s5, -1
	s_add_i32 s72, 0, 0x10000
	s_waitcnt vmcnt(0)
	v_add_u32_e32 v94, s72, v201
	ds_read_b128 v[74:77], v94
	ds_read_b128 v[82:85], v94 offset:1024
	ds_read_b128 v[86:89], v94 offset:2048
	ds_read_b128 v[94:97], v94 offset:3072
	s_cmp_eq_u32 s53, 12
	s_cselect_b32 s65, s29, s61
	s_cselect_b32 s64, s28, s60
	s_cselect_b32 s61, s59, s52
	s_cselect_b32 s60, s58, s15
	v_lshl_add_u64 v[192:193], s[4:5], 0, v[188:189]
	s_add_i32 m0, s24, 0xc000
	ds_read_b128 v[106:109], v202
	ds_read_b128 v[110:113], v202 offset:1024
	ds_read_b128 v[130:133], v202 offset:2048
	ds_read_b128 v[134:137], v202 offset:3072
	ds_read_b128 v[154:157], v202 offset:4096
	ds_read_b128 v[158:161], v202 offset:5120
	ds_read_b128 v[170:173], v202 offset:6144
	ds_read_b128 v[174:177], v202 offset:7168
	global_load_lds_dwordx4 v[192:193], off
	v_lshl_add_u64 v[192:193], s[4:5], 0, v[190:191]
	s_add_i32 m0, s24, 0xe000
	s_nop 0
	global_load_lds_dwordx4 v[192:193], off
	s_waitcnt lgkmcnt(8)
	s_barrier
	s_waitcnt lgkmcnt(0)
	v_mfma_f32_16x16x32_bf16 v[166:169], v[74:77], v[106:109], v[166:169]
	v_mfma_f32_16x16x32_bf16 v[162:165], v[86:89], v[106:109], v[162:165]
	v_mfma_f32_16x16x32_bf16 v[142:145], v[74:77], v[130:133], v[142:145]
	v_mfma_f32_16x16x32_bf16 v[138:141], v[86:89], v[130:133], v[138:141]
	v_mfma_f32_16x16x32_bf16 v[118:121], v[74:77], v[154:157], v[118:121]
	v_mfma_f32_16x16x32_bf16 v[114:117], v[86:89], v[154:157], v[114:117]
	v_mfma_f32_16x16x32_bf16 v[90:93], v[74:77], v[170:173], v[90:93]
	v_mfma_f32_16x16x32_bf16 v[78:81], v[86:89], v[170:173], v[78:81]
	v_mfma_f32_16x16x32_bf16 v[166:169], v[82:85], v[110:113], v[166:169]
	v_mfma_f32_16x16x32_bf16 v[162:165], v[94:97], v[110:113], v[162:165]
	v_mfma_f32_16x16x32_bf16 v[142:145], v[82:85], v[134:137], v[142:145]
	v_mfma_f32_16x16x32_bf16 v[138:141], v[94:97], v[134:137], v[138:141]
	v_mfma_f32_16x16x32_bf16 v[118:121], v[82:85], v[158:161], v[118:121]
	v_mfma_f32_16x16x32_bf16 v[114:117], v[94:97], v[158:161], v[114:117]
	v_mfma_f32_16x16x32_bf16 v[90:93], v[82:85], v[174:177], v[90:93]
	v_mfma_f32_16x16x32_bf16 v[78:81], v[94:97], v[174:177], v[78:81]
	s_barrier
	s_add_i32 s74, 0, 0x14000
	s_add_i32 s72, s72, s1
	v_add_u32_e32 v203, s74, v201
	v_lshl_add_u64 v[208:209], s[60:61], 0, v[184:185]
	s_mov_b32 m0, s72
	ds_read_b128 v[192:195], v203
	ds_read_b128 v[196:199], v203 offset:1024
	ds_read_b128 v[204:207], v203 offset:2048
	ds_read_b128 v[226:229], v203 offset:3072
	global_load_lds_dwordx4 v[208:209], off
	v_lshl_add_u64 v[234:235], s[60:61], 0, v[180:181]
	s_add_i32 m0, s72, 0x2000
	s_nop 0
	global_load_lds_dwordx4 v[234:235], off
	s_nop 1
	s_mov_b32 m0, s24
	v_lshl_add_u64 v[236:237], s[64:65], 0, v[186:187]
	s_barrier
	s_waitcnt lgkmcnt(0)
	v_mfma_f32_16x16x32_bf16 v[150:153], v[192:195], v[106:109], v[150:153]
	v_mfma_f32_16x16x32_bf16 v[106:109], v[204:207], v[106:109], v[146:149]
	v_mfma_f32_16x16x32_bf16 v[122:125], v[204:207], v[130:133], v[122:125]
	v_mfma_f32_16x16x32_bf16 v[102:105], v[192:195], v[154:157], v[102:105]
	v_mfma_f32_16x16x32_bf16 v[98:101], v[204:207], v[154:157], v[98:101]
	v_mfma_f32_16x16x32_bf16 v[70:73], v[192:195], v[170:173], v[70:73]
	v_mfma_f32_16x16x32_bf16 v[66:69], v[204:207], v[170:173], v[66:69]
	v_mfma_f32_16x16x32_bf16 v[150:153], v[196:199], v[110:113], v[150:153]
	v_mfma_f32_16x16x32_bf16 v[106:109], v[226:229], v[110:113], v[106:109]
	v_mfma_f32_16x16x32_bf16 v[110:113], v[192:195], v[130:133], v[126:129]
	v_mfma_f32_16x16x32_bf16 v[122:125], v[226:229], v[134:137], v[122:125]
	v_mfma_f32_16x16x32_bf16 v[102:105], v[196:199], v[158:161], v[102:105]
	v_mfma_f32_16x16x32_bf16 v[98:101], v[226:229], v[158:161], v[98:101]
	v_mfma_f32_16x16x32_bf16 v[70:73], v[196:199], v[174:177], v[70:73]
	v_mfma_f32_16x16x32_bf16 v[66:69], v[226:229], v[174:177], v[66:69]
	v_mfma_f32_16x16x32_bf16 v[110:113], v[196:199], v[134:137], v[110:113]
	s_barrier
	ds_read_b128 v[126:129], v202 offset:16384
	ds_read_b128 v[130:133], v202 offset:17408
	ds_read_b128 v[134:137], v202 offset:18432
	ds_read_b128 v[146:149], v202 offset:19456
	ds_read_b128 v[154:157], v202 offset:20480
	ds_read_b128 v[158:161], v202 offset:21504
	ds_read_b128 v[170:173], v202 offset:22528
	ds_read_b128 v[174:177], v202 offset:23552
	global_load_lds_dwordx4 v[236:237], off
	v_lshl_add_u64 v[238:239], s[64:65], 0, v[182:183]
	s_mov_b32 m0, s25
	s_nop 0
	global_load_lds_dwordx4 v[238:239], off
	s_barrier
	s_waitcnt lgkmcnt(0)
	v_mfma_f32_16x16x32_bf16 v[62:65], v[74:77], v[126:129], v[62:65]
	v_mfma_f32_16x16x32_bf16 v[58:61], v[86:89], v[126:129], v[58:61]
	v_mfma_f32_16x16x32_bf16 v[46:49], v[74:77], v[134:137], v[46:49]
	v_mfma_f32_16x16x32_bf16 v[42:45], v[86:89], v[134:137], v[42:45]
	v_mfma_f32_16x16x32_bf16 v[30:33], v[74:77], v[154:157], v[30:33]
	v_mfma_f32_16x16x32_bf16 v[26:29], v[86:89], v[154:157], v[26:29]
	v_mfma_f32_16x16x32_bf16 v[14:17], v[74:77], v[170:173], v[14:17]
	v_mfma_f32_16x16x32_bf16 v[10:13], v[86:89], v[170:173], v[10:13]
	v_mfma_f32_16x16x32_bf16 v[62:65], v[82:85], v[130:133], v[62:65]
	v_mfma_f32_16x16x32_bf16 v[58:61], v[94:97], v[130:133], v[58:61]
	v_mfma_f32_16x16x32_bf16 v[46:49], v[82:85], v[146:149], v[46:49]
	v_mfma_f32_16x16x32_bf16 v[42:45], v[94:97], v[146:149], v[42:45]
	v_mfma_f32_16x16x32_bf16 v[30:33], v[82:85], v[158:161], v[30:33]
	v_mfma_f32_16x16x32_bf16 v[26:29], v[94:97], v[158:161], v[26:29]
	v_mfma_f32_16x16x32_bf16 v[14:17], v[82:85], v[174:177], v[14:17]
	v_mfma_f32_16x16x32_bf16 v[10:13], v[94:97], v[174:177], v[10:13]
	s_barrier
; #define PG8_STAGE(bufoff, gbase, voff) do { _Pragma("unroll") for (int _i = 0; _i < 2; ++_i) \
;         __builtin_amdgcn_global_load_lds((const unsigned*)((const char*)(gbase) + (voff)[_i]), (LAS unsigned*)(lds + (bufoff) + ldsw + _i * 8192), 16, 0, 0); } while (0)
; #define PG8_LDA(dst, b, h) do { _Pragma("unroll") for (int m = 0; m < 4; ++m) _Pragma("unroll") for (int k = 0; k < 2; ++k) dst[m][k] = *(const LAS bf16x8*)(lds + PG8_SA(b, h) + aoff + m * 2048 + k * 1024); } while (0)
; #define PG8_LDB(dst, b, h) do { _Pragma("unroll") for (int n = 0; n < 2; ++n) _Pragma("unroll") for (int k = 0; k < 2; ++k) dst[n][k] = *(const LAS bf16x8*)(lds + PG8_SB(b, h) + boff + n * 2048 + k * 1024); } while (0)
; #define PG8_MMA(ai, bj, At, Bt) do { __builtin_amdgcn_s_setprio(1); _Pragma("unroll") for (int m = 0; m < 4; ++m) _Pragma("unroll") for (int n = 0; n < 2; ++n) _Pragma("unroll") for (int k = 0; k < 2; ++k) \
;         acc[ai][bj][m][n] = __builtin_amdgcn_mfma_f32_16x16x32_bf16(Bt[n][k], At[m][k], acc[ai][bj][m][n], 0, 0, 0); __builtin_amdgcn_s_setprio(0); } while (0)
; #define PG8_WAIT_V(n) asm volatile("s_waitcnt vmcnt(" #n ")" ::: "memory")
; #define PG8_WAIT_L(n) asm volatile("s_waitcnt lgkmcnt(" #n ")" ::: "memory")
; #define PG8_BAR __builtin_amdgcn_s_barrier()
; #define PG8_SCHED __builtin_amdgcn_sched_barrier(0)
; template <class Epi>
; __device__ __forceinline__ void gemm_phase(LAS unsigned char* lds, const Gemm g, const Epi& E) {
;     ...
;             PG8_BAR; PG8_WAIT_L(0); PG8_MMA(1, 0, At, B0); PG8_BAR; PG8_SCHED;
;             PG8_STAGE(PG8_SB(0, 1), b2 + hstepB, voffB);
;             PG8_WAIT_V(6); PG8_BAR; PG8_MMA(1, 1, At, B1); PG8_BAR;
;             PG8_LDB(B0, 1, 0); PG8_SCHED; PG8_LDA(At, 1, 0); PG8_STAGE(PG8_SA(0, 1), a2 + hstepA, voffA);
;             PG8_WAIT_L(8); PG8_BAR; PG8_WAIT_L(0); PG8_MMA(0, 0, At, B0); PG8_BAR; PG8_SCHED;
;             PG8_LDB(B1, 1, 1); PG8_STAGE(PG8_SB(1, 0), b3, voffB);
;             PG8_BAR; PG8_WAIT_L(0); PG8_MMA(0, 1, At, B1); PG8_BAR;
	s_add_u32 s72, s60, 0x40000
	s_addc_u32 s73, s61, 0
	s_add_i32 s74, s74, s1
	v_lshl_add_u64 v[74:75], s[72:73], 0, v[184:185]
	s_mov_b32 m0, s74
	s_nop 0
	global_load_lds_dwordx4 v[74:75], off
	v_lshl_add_u64 v[74:75], s[72:73], 0, v[180:181]
	s_add_i32 m0, s74, 0x2000
	s_nop 0
	global_load_lds_dwordx4 v[74:75], off
	s_add_i32 s72, 0, 0x18000
	v_add_u32_e32 v94, s72, v201
	s_waitcnt vmcnt(6)
	s_barrier
	v_mfma_f32_16x16x32_bf16 v[54:57], v[192:195], v[126:129], v[54:57]
	v_mfma_f32_16x16x32_bf16 v[50:53], v[204:207], v[126:129], v[50:53]
	v_mfma_f32_16x16x32_bf16 v[38:41], v[192:195], v[134:137], v[38:41]
	v_mfma_f32_16x16x32_bf16 v[34:37], v[204:207], v[134:137], v[34:37]
	v_mfma_f32_16x16x32_bf16 v[22:25], v[192:195], v[154:157], v[22:25]
	v_mfma_f32_16x16x32_bf16 v[18:21], v[204:207], v[154:157], v[18:21]
	v_mfma_f32_16x16x32_bf16 v[6:9], v[192:195], v[170:173], v[6:9]
	v_mfma_f32_16x16x32_bf16 v[2:5], v[204:207], v[170:173], v[2:5]
	v_mfma_f32_16x16x32_bf16 v[54:57], v[196:199], v[130:133], v[54:57]
	v_mfma_f32_16x16x32_bf16 v[50:53], v[226:229], v[130:133], v[50:53]
	v_mfma_f32_16x16x32_bf16 v[38:41], v[196:199], v[146:149], v[38:41]
	v_mfma_f32_16x16x32_bf16 v[34:37], v[226:229], v[146:149], v[34:37]
	v_mfma_f32_16x16x32_bf16 v[22:25], v[196:199], v[158:161], v[22:25]
	v_mfma_f32_16x16x32_bf16 v[18:21], v[226:229], v[158:161], v[18:21]
	v_mfma_f32_16x16x32_bf16 v[6:9], v[196:199], v[174:177], v[6:9]
	v_mfma_f32_16x16x32_bf16 v[2:5], v[226:229], v[174:177], v[2:5]
	s_barrier
	ds_read_b128 v[74:77], v94
	ds_read_b128 v[82:85], v94 offset:1024
	ds_read_b128 v[86:89], v94 offset:2048
	ds_read_b128 v[94:97], v94 offset:3072
	s_add_u32 s64, s64, 0x40000
	s_addc_u32 s65, s65, 0
	s_mov_b32 m0, s31
	v_lshl_add_u64 v[146:147], s[64:65], 0, v[186:187]
	ds_read_b128 v[126:129], v202 offset:32768
	ds_read_b128 v[130:133], v202 offset:33792
	ds_read_b128 v[134:137], v202 offset:34816
	ds_read_b128 v[154:157], v202 offset:35840
	ds_read_b128 v[158:161], v202 offset:36864
	ds_read_b128 v[170:173], v202 offset:37888
	ds_read_b128 v[174:177], v202 offset:38912
	ds_read_b128 v[192:195], v202 offset:39936
	global_load_lds_dwordx4 v[146:147], off
	v_lshl_add_u64 v[146:147], s[64:65], 0, v[182:183]
	s_mov_b32 m0, s36
	s_nop 0
	global_load_lds_dwordx4 v[146:147], off
	s_waitcnt lgkmcnt(8)
	s_barrier
	s_waitcnt lgkmcnt(0)
	v_mfma_f32_16x16x32_bf16 v[146:149], v[74:77], v[126:129], v[166:169]
	v_mfma_f32_16x16x32_bf16 v[166:169], v[82:85], v[130:133], v[146:149]
	v_mfma_f32_16x16x32_bf16 v[146:149], v[86:89], v[126:129], v[162:165]
	v_mfma_f32_16x16x32_bf16 v[142:145], v[74:77], v[134:137], v[142:145]
	v_mfma_f32_16x16x32_bf16 v[138:141], v[86:89], v[134:137], v[138:141]
	v_mfma_f32_16x16x32_bf16 v[118:121], v[74:77], v[158:161], v[118:121]
	v_mfma_f32_16x16x32_bf16 v[114:117], v[86:89], v[158:161], v[114:117]
	v_mfma_f32_16x16x32_bf16 v[90:93], v[74:77], v[174:177], v[90:93]
	v_mfma_f32_16x16x32_bf16 v[78:81], v[86:89], v[174:177], v[78:81]
	v_mfma_f32_16x16x32_bf16 v[162:165], v[94:97], v[130:133], v[146:149]
	v_mfma_f32_16x16x32_bf16 v[142:145], v[82:85], v[154:157], v[142:145]
	v_mfma_f32_16x16x32_bf16 v[138:141], v[94:97], v[154:157], v[138:141]
	v_mfma_f32_16x16x32_bf16 v[118:121], v[82:85], v[170:173], v[118:121]
	v_mfma_f32_16x16x32_bf16 v[114:117], v[94:97], v[170:173], v[114:117]
	v_mfma_f32_16x16x32_bf16 v[90:93], v[82:85], v[192:195], v[90:93]
	v_mfma_f32_16x16x32_bf16 v[78:81], v[94:97], v[192:195], v[78:81]
	s_barrier
	s_add_i32 s64, 0, 0x1c000
	v_add_u32_e32 v146, s64, v201
	s_add_i32 s65, s72, s1
	ds_read_b128 v[196:199], v146
	ds_read_b128 v[204:207], v146 offset:1024
	ds_read_b128 v[226:229], v146 offset:2048
	ds_read_b128 v[230:233], v146 offset:3072
	v_lshl_add_u64 v[146:147], v[208:209], 0, s[86:87]
	s_mov_b32 m0, s65
	s_nop 0
	global_load_lds_dwordx4 v[146:147], off
	v_lshl_add_u64 v[146:147], v[234:235], 0, s[86:87]
	s_add_i32 m0, s65, 0x2000
	s_nop 0
	global_load_lds_dwordx4 v[146:147], off
	s_barrier
	s_waitcnt lgkmcnt(0)
	v_mfma_f32_16x16x32_bf16 v[146:149], v[196:199], v[126:129], v[150:153]
	v_mfma_f32_16x16x32_bf16 v[106:109], v[226:229], v[126:129], v[106:109]
	v_mfma_f32_16x16x32_bf16 v[150:153], v[204:207], v[130:133], v[146:149]
	v_mfma_f32_16x16x32_bf16 v[146:149], v[230:233], v[130:133], v[106:109]
	v_mfma_f32_16x16x32_bf16 v[106:109], v[196:199], v[134:137], v[110:113]
	v_mfma_f32_16x16x32_bf16 v[126:129], v[204:207], v[154:157], v[106:109]
	v_mfma_f32_16x16x32_bf16 v[106:109], v[226:229], v[134:137], v[122:125]
	v_mfma_f32_16x16x32_bf16 v[102:105], v[196:199], v[158:161], v[102:105]
	v_mfma_f32_16x16x32_bf16 v[98:101], v[226:229], v[158:161], v[98:101]
	v_mfma_f32_16x16x32_bf16 v[70:73], v[196:199], v[174:177], v[70:73]
	v_mfma_f32_16x16x32_bf16 v[66:69], v[226:229], v[174:177], v[66:69]
	v_mfma_f32_16x16x32_bf16 v[122:125], v[230:233], v[154:157], v[106:109]
	v_mfma_f32_16x16x32_bf16 v[102:105], v[204:207], v[170:173], v[102:105]
	v_mfma_f32_16x16x32_bf16 v[98:101], v[230:233], v[170:173], v[98:101]
	v_mfma_f32_16x16x32_bf16 v[70:73], v[204:207], v[192:195], v[70:73]
	v_mfma_f32_16x16x32_bf16 v[66:69], v[230:233], v[192:195], v[66:69]
	s_mov_b32 m0, s50
	v_lshl_add_u64 v[192:193], v[236:237], 0, s[86:87]
	s_barrier
; #define PG8_STAGE(bufoff, gbase, voff) do { _Pragma("unroll") for (int _i = 0; _i < 2; ++_i) \
;         __builtin_amdgcn_global_load_lds((const unsigned*)((const char*)(gbase) + (voff)[_i]), (LAS unsigned*)(lds + (bufoff) + ldsw + _i * 8192), 16, 0, 0); } while (0)
; #define PG8_LDA(dst, b, h) do { _Pragma("unroll") for (int m = 0; m < 4; ++m) _Pragma("unroll") for (int k = 0; k < 2; ++k) dst[m][k] = *(const LAS bf16x8*)(lds + PG8_SA(b, h) + aoff + m * 2048 + k * 1024); } while (0)
; #define PG8_MMA(ai, bj, At, Bt) do { __builtin_amdgcn_s_setprio(1); _Pragma("unroll") for (int m = 0; m < 4; ++m) _Pragma("unroll") for (int n = 0; n < 2; ++n) _Pragma("unroll") for (int k = 0; k < 2; ++k) \
;         acc[ai][bj][m][n] = __builtin_amdgcn_mfma_f32_16x16x32_bf16(Bt[n][k], At[m][k], acc[ai][bj][m][n], 0, 0, 0); __builtin_amdgcn_s_setprio(0); } while (0)
; #define PG8_WAIT_V(n) asm volatile("s_waitcnt vmcnt(" #n ")" ::: "memory")
; #define PG8_WAIT_L(n) asm volatile("s_waitcnt lgkmcnt(" #n ")" ::: "memory")
; #define PG8_BAR __builtin_amdgcn_s_barrier()
; #define PG8_SCHED __builtin_amdgcn_sched_barrier(0)
; template <class Epi>
; __device__ __forceinline__ void gemm_phase(LAS unsigned char* lds, const Gemm g, const Epi& E) {
;     ...
;             PG8_BAR; PG8_WAIT_L(0); PG8_MMA(0, 1, At, B1); PG8_BAR;
;             PG8_LDA(At, 1, 1); PG8_STAGE(PG8_SA(1, 0), a3, voffA);
;             PG8_BAR; PG8_WAIT_L(0); PG8_MMA(1, 0, At, B0); PG8_BAR; PG8_SCHED;
;             PG8_STAGE(PG8_SB(1, 1), b3 + hstepB, voffB);
;             PG8_WAIT_V(6); PG8_BAR; PG8_MMA(1, 1, At, B1); PG8_BAR;
;         }
;     __device__ __forceinline__ void operator()(const AccT& acc, const Unit& u, int wr, int wc, int fr, int fq) const {
;     ...
;         const int p0 = 16 * wc + 4 * fq;
;         f32x4 ctR[2][2], ctC[4][2];
;         if (lat) {
; #pragma unroll
;             for (int ai = 0; ai < 2; ++ai) { const int pr = ((gpm - 32) * 4 + 2 * ai + wr) & 31;
;                 ctR[ai][0] = *(const f32x4*)(cs + pr * 64 + p0); ctR[ai][1] = *(const f32x4*)(cs + pr * 64 + p0 + 2); }
; #pragma unroll
;             for (int m = 0; m < 4; ++m) { const int pc = m * 16 + fr;
;                 ctC[m][0] = *(const f32x4*)(cs + pc * 64 + p0); ctC[m][1] = *(const f32x4*)(cs + pc * 64 + p0 + 2); }
;         }
	ds_read_b128 v[106:109], v202 offset:49152
	ds_read_b128 v[110:113], v202 offset:50176
	ds_read_b128 v[130:133], v202 offset:51200
	ds_read_b128 v[134:137], v202 offset:52224
	ds_read_b128 v[154:157], v202 offset:53248
	ds_read_b128 v[158:161], v202 offset:54272
	ds_read_b128 v[170:173], v202 offset:55296
	ds_read_b128 v[174:177], v202 offset:56320
	global_load_lds_dwordx4 v[192:193], off
	v_lshl_add_u64 v[192:193], v[238:239], 0, s[86:87]
	s_mov_b32 m0, s66
	s_nop 0
	global_load_lds_dwordx4 v[192:193], off
	s_barrier
	s_waitcnt lgkmcnt(0)
	v_mfma_f32_16x16x32_bf16 v[62:65], v[74:77], v[106:109], v[62:65]
	v_mfma_f32_16x16x32_bf16 v[58:61], v[86:89], v[106:109], v[58:61]
	v_mfma_f32_16x16x32_bf16 v[46:49], v[74:77], v[130:133], v[46:49]
	v_mfma_f32_16x16x32_bf16 v[42:45], v[86:89], v[130:133], v[42:45]
	v_mfma_f32_16x16x32_bf16 v[30:33], v[74:77], v[154:157], v[30:33]
	v_mfma_f32_16x16x32_bf16 v[26:29], v[86:89], v[154:157], v[26:29]
	v_mfma_f32_16x16x32_bf16 v[14:17], v[74:77], v[170:173], v[14:17]
	v_mfma_f32_16x16x32_bf16 v[10:13], v[86:89], v[170:173], v[10:13]
	v_mfma_f32_16x16x32_bf16 v[62:65], v[82:85], v[110:113], v[62:65]
	v_mfma_f32_16x16x32_bf16 v[58:61], v[94:97], v[110:113], v[58:61]
	v_mfma_f32_16x16x32_bf16 v[46:49], v[82:85], v[134:137], v[46:49]
	v_mfma_f32_16x16x32_bf16 v[42:45], v[94:97], v[134:137], v[42:45]
	v_mfma_f32_16x16x32_bf16 v[30:33], v[82:85], v[158:161], v[30:33]
	v_mfma_f32_16x16x32_bf16 v[26:29], v[94:97], v[158:161], v[26:29]
	v_mfma_f32_16x16x32_bf16 v[14:17], v[82:85], v[174:177], v[14:17]
	v_mfma_f32_16x16x32_bf16 v[10:13], v[94:97], v[174:177], v[10:13]
	s_barrier
	s_add_u32 s60, s60, 0x40080
	s_addc_u32 s61, s61, 0
	s_add_i32 s64, s64, s1
	v_lshl_add_u64 v[74:75], s[60:61], 0, v[184:185]
	s_mov_b32 m0, s64
	s_nop 0
	global_load_lds_dwordx4 v[74:75], off
	v_lshl_add_u64 v[74:75], s[60:61], 0, v[180:181]
	s_add_i32 m0, s64, 0x2000
	s_nop 0
	global_load_lds_dwordx4 v[74:75], off
	s_add_i32 s53, s53, 2
	s_add_u32 s4, s4, 0x100
	s_addc_u32 s5, s5, 0
	s_add_u32 s15, s15, 0x100
	s_addc_u32 s52, s52, 0
	s_cmp_gt_u32 s53, 13
	s_waitcnt vmcnt(6)
	s_barrier
	v_mfma_f32_16x16x32_bf16 v[54:57], v[196:199], v[106:109], v[54:57]
	v_mfma_f32_16x16x32_bf16 v[50:53], v[226:229], v[106:109], v[50:53]
	v_mfma_f32_16x16x32_bf16 v[38:41], v[196:199], v[130:133], v[38:41]
	v_mfma_f32_16x16x32_bf16 v[34:37], v[226:229], v[130:133], v[34:37]
	v_mfma_f32_16x16x32_bf16 v[22:25], v[196:199], v[154:157], v[22:25]
	v_mfma_f32_16x16x32_bf16 v[18:21], v[226:229], v[154:157], v[18:21]
	v_mfma_f32_16x16x32_bf16 v[6:9], v[196:199], v[170:173], v[6:9]
	v_mfma_f32_16x16x32_bf16 v[2:5], v[226:229], v[170:173], v[2:5]
	v_mfma_f32_16x16x32_bf16 v[54:57], v[204:207], v[110:113], v[54:57]
	v_mfma_f32_16x16x32_bf16 v[50:53], v[230:233], v[110:113], v[50:53]
	v_mfma_f32_16x16x32_bf16 v[38:41], v[204:207], v[134:137], v[38:41]
	v_mfma_f32_16x16x32_bf16 v[34:37], v[230:233], v[134:137], v[34:37]
	v_mfma_f32_16x16x32_bf16 v[22:25], v[204:207], v[158:161], v[22:25]
	v_mfma_f32_16x16x32_bf16 v[18:21], v[230:233], v[158:161], v[18:21]
	v_mfma_f32_16x16x32_bf16 v[6:9], v[204:207], v[174:177], v[6:9]
	v_mfma_f32_16x16x32_bf16 v[2:5], v[230:233], v[174:177], v[2:5]
	s_barrier
	s_cbranch_scc0 .LBB0_331
	s_cmp_lt_i32 s10, 16
	s_cselect_b32 s4, s68, s18
	s_add_i32 s15, s10, s4
	s_cmp_lt_i32 s11, 8
	s_cselect_b64 s[60:61], -1, 0
	s_cmp_gt_i32 s15, 31
	s_cselect_b64 s[4:5], -1, 0
	s_and_b64 s[52:53], s[60:61], s[4:5]
	v_cndmask_b32_e64 v74, 0, 1, s[52:53]
	v_mov_b32_e32 v194, v200
	v_mov_b32_e32 v193, v1
	v_cmp_ne_u32_e64 s[4:5], 1, v74
	s_andn2_b64 vcc, exec, s[52:53]
	s_cbranch_vccnz .LBB0_334
	v_lshl_add_u32 v74, v193, 2, s67
	v_readlane_b32 s52, v254, 2
	s_lshl_b32 s15, s15, 8
	v_ashrrev_i32_e32 v75, 31, v74
	v_readlane_b32 s53, v254, 3
	s_add_i32 s15, s15, s44
	s_nop 0
	v_lshl_add_u64 v[74:75], v[74:75], 3, s[52:53]
	s_and_b32 s52, s15, 0x7c0
	s_addk_i32 s15, 0x80
	s_lshl_b32 s76, s52, 3
	s_and_b32 s15, s15, 0x7c0
	v_lshl_add_u64 v[76:77], v[74:75], 0, s[76:77]
	s_lshl_b32 s76, s15, 3
	global_load_dwordx4 v[170:173], v[76:77], off offset:16
	global_load_dwordx4 v[174:177], v[76:77], off
	v_lshl_add_u64 v[76:77], v[74:75], 0, s[76:77]
	global_load_dwordx4 v[86:89], v[76:77], off offset:16
	global_load_dwordx4 v[94:97], v[76:77], off
	v_lshlrev_b32_e32 v76, 6, v194
	v_ashrrev_i32_e32 v77, 31, v76
	v_lshl_add_u64 v[82:83], v[76:77], 3, v[74:75]
	global_load_dwordx4 v[154:157], v[82:83], off offset:16
	global_load_dwordx4 v[158:161], v[82:83], off
	v_add_u32_e32 v82, 0x400, v76
	v_ashrrev_i32_e32 v83, 31, v82
	v_lshl_add_u64 v[82:83], v[82:83], 3, v[74:75]
	global_load_dwordx4 v[130:133], v[82:83], off offset:16
	global_load_dwordx4 v[134:137], v[82:83], off
	v_add_u32_e32 v82, 0x800, v76
	v_ashrrev_i32_e32 v83, 31, v82
	v_add_u32_e32 v76, 0xc00, v76
	v_lshl_add_u64 v[82:83], v[82:83], 3, v[74:75]
	v_ashrrev_i32_e32 v77, 31, v76
	global_load_dwordx4 v[106:109], v[82:83], off offset:16
	global_load_dwordx4 v[110:113], v[82:83], off
	v_lshl_add_u64 v[82:83], v[76:77], 3, v[74:75]
	global_load_dwordx4 v[74:77], v[82:83], off offset:16
	s_nop 0
	global_load_dwordx4 v[82:85], v[82:83], off

; #define PG8_STAGE(bufoff, gbase, voff) do { _Pragma("unroll") for (int _i = 0; _i < 2; ++_i) \
;         __builtin_amdgcn_global_load_lds((const unsigned*)((const char*)(gbase) + (voff)[_i]), (LAS unsigned*)(lds + (bufoff) + ldsw + _i * 8192), 16, 0, 0); } while (0)
; #define PG8_LDA(dst, b, h) do { _Pragma("unroll") for (int m = 0; m < 4; ++m) _Pragma("unroll") for (int k = 0; k < 2; ++k) dst[m][k] = *(const LAS bf16x8*)(lds + PG8_SA(b, h) + aoff + m * 2048 + k * 1024); } while (0)
; #define PG8_LDB(dst, b, h) do { _Pragma("unroll") for (int n = 0; n < 2; ++n) _Pragma("unroll") for (int k = 0; k < 2; ++k) dst[n][k] = *(const LAS bf16x8*)(lds + PG8_SB(b, h) + boff + n * 2048 + k * 1024); } while (0)
; #define PG8_MMA(ai, bj, At, Bt) do { __builtin_amdgcn_s_setprio(1); _Pragma("unroll") for (int m = 0; m < 4; ++m) _Pragma("unroll") for (int n = 0; n < 2; ++n) _Pragma("unroll") for (int k = 0; k < 2; ++k) \
;         acc[ai][bj][m][n] = __builtin_amdgcn_mfma_f32_16x16x32_bf16(Bt[n][k], At[m][k], acc[ai][bj][m][n], 0, 0, 0); __builtin_amdgcn_s_setprio(0); } while (0)
; #define PG8_WAIT_L(n) asm volatile("s_waitcnt lgkmcnt(" #n ")" ::: "memory")
; #define PG8_BAR __builtin_amdgcn_s_barrier()
; #define PG8_SCHED __builtin_amdgcn_sched_barrier(0)
; template <class Epi>
; __device__ __forceinline__ void gemm_phase(LAS unsigned char* lds, const Gemm g, const Epi& E) {
;     ...
;         for (int t = 0; t < nt; t += 2) {
;             const bool last = (t == nt - 2);
;             const char* a1 = cA + (size_t)(t + 1) * kstep;
;             const char* a2 = last ? nA : cA + (size_t)(t + 2) * kstep; const char* b2 = last ? nB : cB + (size_t)(t + 2) * kstep;
;             const char* a3 = a2 + kstep; const char* b3 = b2 + kstep;
;             PG8_LDB(B0, 0, 0); PG8_SCHED; PG8_LDA(At, 0, 0); PG8_STAGE(PG8_SA(1, 1), a1 + hstepA, voffA);
;             PG8_WAIT_L(8); PG8_BAR; PG8_WAIT_L(0); PG8_MMA(0, 0, At, B0); PG8_BAR; PG8_SCHED;
;             PG8_LDB(B1, 0, 1); PG8_STAGE(PG8_SB(0, 0), b2, voffB);
;             PG8_BAR; PG8_WAIT_L(0); PG8_MMA(0, 1, At, B1); PG8_BAR;
;             PG8_LDA(At, 0, 1); PG8_STAGE(PG8_SA(0, 0), a2, voffA);
;             PG8_BAR; PG8_WAIT_L(0); PG8_MMA(1, 0, At, B0); PG8_BAR; PG8_SCHED;
.LBB0_475:
	s_add_u32 s16, s14, 0xfffc0080
	s_addc_u32 s17, s15, -1
	s_add_i32 s66, 0, 0x10000
	v_add_u32_e32 v86, s66, v226
	ds_read_b128 v[66:69], v86
	ds_read_b128 v[70:73], v86 offset:1024
	ds_read_b128 v[82:85], v86 offset:2048
	ds_read_b128 v[86:89], v86 offset:3072
	s_cmp_eq_u32 s65, 12
	s_cselect_b32 s29, s11, s17
	s_cselect_b32 s28, s10, s16
	s_cselect_b32 s17, s5, s53
	s_cselect_b32 s16, s4, s9
	v_lshl_add_u64 v[192:193], s[14:15], 0, v[174:175]
	s_add_i32 m0, s13, 0xc000
	ds_read_b128 v[146:149], v227
	ds_read_b128 v[150:153], v227 offset:1024
	ds_read_b128 v[154:157], v227 offset:2048
	ds_read_b128 v[158:161], v227 offset:3072
	ds_read_b128 v[162:165], v227 offset:4096
	ds_read_b128 v[180:183], v227 offset:5120
	ds_read_b128 v[184:187], v227 offset:6144
	ds_read_b128 v[188:191], v227 offset:7168
	global_load_lds_dwordx4 v[192:193], off
	v_lshl_add_u64 v[192:193], s[14:15], 0, v[176:177]
	s_add_i32 m0, s13, 0xe000
	s_nop 0
	global_load_lds_dwordx4 v[192:193], off
	s_waitcnt lgkmcnt(8)
	s_barrier
	s_waitcnt lgkmcnt(0)
	v_mfma_f32_16x16x32_bf16 v[142:145], v[66:69], v[146:149], v[142:145]
	v_mfma_f32_16x16x32_bf16 v[138:141], v[82:85], v[146:149], v[138:141]
	v_mfma_f32_16x16x32_bf16 v[126:129], v[66:69], v[154:157], v[126:129]
	v_mfma_f32_16x16x32_bf16 v[122:125], v[82:85], v[154:157], v[122:125]
	v_mfma_f32_16x16x32_bf16 v[110:113], v[66:69], v[162:165], v[110:113]
	v_mfma_f32_16x16x32_bf16 v[106:109], v[82:85], v[162:165], v[106:109]
	v_mfma_f32_16x16x32_bf16 v[94:97], v[66:69], v[184:187], v[94:97]
	v_mfma_f32_16x16x32_bf16 v[90:93], v[82:85], v[184:187], v[90:93]
	v_mfma_f32_16x16x32_bf16 v[142:145], v[70:73], v[150:153], v[142:145]
	v_mfma_f32_16x16x32_bf16 v[138:141], v[86:89], v[150:153], v[138:141]
	v_mfma_f32_16x16x32_bf16 v[126:129], v[70:73], v[158:161], v[126:129]
	v_mfma_f32_16x16x32_bf16 v[122:125], v[86:89], v[158:161], v[122:125]
	v_mfma_f32_16x16x32_bf16 v[110:113], v[70:73], v[180:183], v[110:113]
	v_mfma_f32_16x16x32_bf16 v[106:109], v[86:89], v[180:183], v[106:109]
	v_mfma_f32_16x16x32_bf16 v[94:97], v[70:73], v[188:191], v[94:97]
	v_mfma_f32_16x16x32_bf16 v[90:93], v[86:89], v[188:191], v[90:93]
	s_barrier
	s_add_i32 s68, 0, 0x14000
	s_add_i32 s66, s66, s18
	v_add_u32_e32 v204, s68, v226
	v_lshl_add_u64 v[208:209], s[16:17], 0, v[170:171]
	s_mov_b32 m0, s66
	ds_read_b128 v[192:195], v204
	ds_read_b128 v[196:199], v204 offset:1024
	ds_read_b128 v[200:203], v204 offset:2048
	ds_read_b128 v[204:207], v204 offset:3072
	global_load_lds_dwordx4 v[208:209], off
	v_lshl_add_u64 v[228:229], s[16:17], 0, v[166:167]
	s_add_i32 m0, s66, 0x2000
	s_nop 0
	global_load_lds_dwordx4 v[228:229], off
	s_nop 1
	s_mov_b32 m0, s13
	v_lshl_add_u64 v[230:231], s[28:29], 0, v[172:173]
	s_barrier
	s_waitcnt lgkmcnt(0)
	v_mfma_f32_16x16x32_bf16 v[134:137], v[192:195], v[146:149], v[134:137]
	v_mfma_f32_16x16x32_bf16 v[130:133], v[200:203], v[146:149], v[130:133]
	v_mfma_f32_16x16x32_bf16 v[118:121], v[192:195], v[154:157], v[118:121]
	v_mfma_f32_16x16x32_bf16 v[114:117], v[200:203], v[154:157], v[114:117]
	v_mfma_f32_16x16x32_bf16 v[102:105], v[192:195], v[162:165], v[102:105]
	v_mfma_f32_16x16x32_bf16 v[98:101], v[200:203], v[162:165], v[98:101]
	v_mfma_f32_16x16x32_bf16 v[78:81], v[192:195], v[184:187], v[78:81]
	v_mfma_f32_16x16x32_bf16 v[74:77], v[200:203], v[184:187], v[74:77]
	v_mfma_f32_16x16x32_bf16 v[134:137], v[196:199], v[150:153], v[134:137]
	v_mfma_f32_16x16x32_bf16 v[130:133], v[204:207], v[150:153], v[130:133]
	v_mfma_f32_16x16x32_bf16 v[118:121], v[196:199], v[158:161], v[118:121]
	v_mfma_f32_16x16x32_bf16 v[114:117], v[204:207], v[158:161], v[114:117]
	v_mfma_f32_16x16x32_bf16 v[102:105], v[196:199], v[180:183], v[102:105]
	v_mfma_f32_16x16x32_bf16 v[98:101], v[204:207], v[180:183], v[98:101]
	v_mfma_f32_16x16x32_bf16 v[78:81], v[196:199], v[188:191], v[78:81]
	v_mfma_f32_16x16x32_bf16 v[74:77], v[204:207], v[188:191], v[74:77]
	s_barrier
	ds_read_b128 v[146:149], v227 offset:16384
	ds_read_b128 v[150:153], v227 offset:17408
	ds_read_b128 v[154:157], v227 offset:18432
	ds_read_b128 v[158:161], v227 offset:19456
	ds_read_b128 v[162:165], v227 offset:20480
	ds_read_b128 v[180:183], v227 offset:21504
	ds_read_b128 v[184:187], v227 offset:22528
	ds_read_b128 v[188:191], v227 offset:23552
	global_load_lds_dwordx4 v[230:231], off
	v_lshl_add_u64 v[232:233], s[28:29], 0, v[168:169]
	s_mov_b32 m0, s31
	s_nop 0
	global_load_lds_dwordx4 v[232:233], off
	s_barrier
	s_waitcnt lgkmcnt(0)
	v_mfma_f32_16x16x32_bf16 v[62:65], v[66:69], v[146:149], v[62:65]
	v_mfma_f32_16x16x32_bf16 v[58:61], v[82:85], v[146:149], v[58:61]
	v_mfma_f32_16x16x32_bf16 v[46:49], v[66:69], v[154:157], v[46:49]
	v_mfma_f32_16x16x32_bf16 v[42:45], v[82:85], v[154:157], v[42:45]
	v_mfma_f32_16x16x32_bf16 v[30:33], v[66:69], v[162:165], v[30:33]
	v_mfma_f32_16x16x32_bf16 v[26:29], v[82:85], v[162:165], v[26:29]
	v_mfma_f32_16x16x32_bf16 v[14:17], v[66:69], v[184:187], v[14:17]
	v_mfma_f32_16x16x32_bf16 v[10:13], v[82:85], v[184:187], v[10:13]
	v_mfma_f32_16x16x32_bf16 v[62:65], v[70:73], v[150:153], v[62:65]
	v_mfma_f32_16x16x32_bf16 v[58:61], v[86:89], v[150:153], v[58:61]
	v_mfma_f32_16x16x32_bf16 v[46:49], v[70:73], v[158:161], v[46:49]
	v_mfma_f32_16x16x32_bf16 v[42:45], v[86:89], v[158:161], v[42:45]
	v_mfma_f32_16x16x32_bf16 v[30:33], v[70:73], v[180:183], v[30:33]
	v_mfma_f32_16x16x32_bf16 v[26:29], v[86:89], v[180:183], v[26:29]
	v_mfma_f32_16x16x32_bf16 v[14:17], v[70:73], v[188:191], v[14:17]
	v_mfma_f32_16x16x32_bf16 v[10:13], v[86:89], v[188:191], v[10:13]
	s_barrier
; #define PG8_STAGE(bufoff, gbase, voff) do { _Pragma("unroll") for (int _i = 0; _i < 2; ++_i) \
;         __builtin_amdgcn_global_load_lds((const unsigned*)((const char*)(gbase) + (voff)[_i]), (LAS unsigned*)(lds + (bufoff) + ldsw + _i * 8192), 16, 0, 0); } while (0)
; #define PG8_LDA(dst, b, h) do { _Pragma("unroll") for (int m = 0; m < 4; ++m) _Pragma("unroll") for (int k = 0; k < 2; ++k) dst[m][k] = *(const LAS bf16x8*)(lds + PG8_SA(b, h) + aoff + m * 2048 + k * 1024); } while (0)
; #define PG8_LDB(dst, b, h) do { _Pragma("unroll") for (int n = 0; n < 2; ++n) _Pragma("unroll") for (int k = 0; k < 2; ++k) dst[n][k] = *(const LAS bf16x8*)(lds + PG8_SB(b, h) + boff + n * 2048 + k * 1024); } while (0)
; #define PG8_MMA(ai, bj, At, Bt) do { __builtin_amdgcn_s_setprio(1); _Pragma("unroll") for (int m = 0; m < 4; ++m) _Pragma("unroll") for (int n = 0; n < 2; ++n) _Pragma("unroll") for (int k = 0; k < 2; ++k) \
;         acc[ai][bj][m][n] = __builtin_amdgcn_mfma_f32_16x16x32_bf16(Bt[n][k], At[m][k], acc[ai][bj][m][n], 0, 0, 0); __builtin_amdgcn_s_setprio(0); } while (0)
; #define PG8_WAIT_V(n) asm volatile("s_waitcnt vmcnt(" #n ")" ::: "memory")
; #define PG8_WAIT_L(n) asm volatile("s_waitcnt lgkmcnt(" #n ")" ::: "memory")
; #define PG8_BAR __builtin_amdgcn_s_barrier()
; #define PG8_SCHED __builtin_amdgcn_sched_barrier(0)
; template <class Epi>
; __device__ __forceinline__ void gemm_phase(LAS unsigned char* lds, const Gemm g, const Epi& E) {
;     ...
;             PG8_BAR; PG8_WAIT_L(0); PG8_MMA(1, 0, At, B0); PG8_BAR; PG8_SCHED;
;             PG8_STAGE(PG8_SB(0, 1), b2 + hstepB, voffB);
;             PG8_WAIT_V(6); PG8_BAR; PG8_MMA(1, 1, At, B1); PG8_BAR;
;             PG8_LDB(B0, 1, 0); PG8_SCHED; PG8_LDA(At, 1, 0); PG8_STAGE(PG8_SA(0, 1), a2 + hstepA, voffA);
;             PG8_WAIT_L(8); PG8_BAR; PG8_WAIT_L(0); PG8_MMA(0, 0, At, B0); PG8_BAR; PG8_SCHED;
;             PG8_LDB(B1, 1, 1); PG8_STAGE(PG8_SB(1, 0), b3, voffB);
;             PG8_BAR; PG8_WAIT_L(0); PG8_MMA(0, 1, At, B1); PG8_BAR;
	s_add_u32 s66, s16, 0x40000
	s_addc_u32 s67, s17, 0
	s_add_i32 s68, s68, s18
	v_lshl_add_u64 v[66:67], s[66:67], 0, v[170:171]
	s_mov_b32 m0, s68
	s_nop 0
	global_load_lds_dwordx4 v[66:67], off
	v_lshl_add_u64 v[66:67], s[66:67], 0, v[166:167]
	s_add_i32 m0, s68, 0x2000
	s_nop 0
	global_load_lds_dwordx4 v[66:67], off
	s_add_i32 s66, 0, 0x18000
	v_add_u32_e32 v86, s66, v226
	s_waitcnt vmcnt(6)
	s_barrier
	v_mfma_f32_16x16x32_bf16 v[54:57], v[192:195], v[146:149], v[54:57]
	v_mfma_f32_16x16x32_bf16 v[50:53], v[200:203], v[146:149], v[50:53]
	v_mfma_f32_16x16x32_bf16 v[38:41], v[192:195], v[154:157], v[38:41]
	v_mfma_f32_16x16x32_bf16 v[34:37], v[200:203], v[154:157], v[34:37]
	v_mfma_f32_16x16x32_bf16 v[22:25], v[192:195], v[162:165], v[22:25]
	v_mfma_f32_16x16x32_bf16 v[18:21], v[200:203], v[162:165], v[18:21]
	v_mfma_f32_16x16x32_bf16 v[6:9], v[192:195], v[184:187], v[6:9]
	v_mfma_f32_16x16x32_bf16 v[2:5], v[200:203], v[184:187], v[2:5]
	v_mfma_f32_16x16x32_bf16 v[54:57], v[196:199], v[150:153], v[54:57]
	v_mfma_f32_16x16x32_bf16 v[50:53], v[204:207], v[150:153], v[50:53]
	v_mfma_f32_16x16x32_bf16 v[38:41], v[196:199], v[158:161], v[38:41]
	v_mfma_f32_16x16x32_bf16 v[34:37], v[204:207], v[158:161], v[34:37]
	v_mfma_f32_16x16x32_bf16 v[22:25], v[196:199], v[180:183], v[22:25]
	v_mfma_f32_16x16x32_bf16 v[18:21], v[204:207], v[180:183], v[18:21]
	v_mfma_f32_16x16x32_bf16 v[6:9], v[196:199], v[188:191], v[6:9]
	v_mfma_f32_16x16x32_bf16 v[2:5], v[204:207], v[188:191], v[2:5]
	s_barrier
	ds_read_b128 v[66:69], v86
	ds_read_b128 v[70:73], v86 offset:1024
	ds_read_b128 v[82:85], v86 offset:2048
	ds_read_b128 v[86:89], v86 offset:3072
	s_add_u32 s28, s28, 0x40000
	s_addc_u32 s29, s29, 0
	s_mov_b32 m0, s36
	v_lshl_add_u64 v[192:193], s[28:29], 0, v[172:173]
	ds_read_b128 v[146:149], v227 offset:32768
	ds_read_b128 v[150:153], v227 offset:33792
	ds_read_b128 v[154:157], v227 offset:34816
	ds_read_b128 v[158:161], v227 offset:35840
	ds_read_b128 v[162:165], v227 offset:36864
	ds_read_b128 v[180:183], v227 offset:37888
	ds_read_b128 v[184:187], v227 offset:38912
	ds_read_b128 v[188:191], v227 offset:39936
	global_load_lds_dwordx4 v[192:193], off
	v_lshl_add_u64 v[192:193], s[28:29], 0, v[168:169]
	s_mov_b32 m0, s44
	s_nop 0
	global_load_lds_dwordx4 v[192:193], off
	s_waitcnt lgkmcnt(8)
	s_barrier
	s_waitcnt lgkmcnt(0)
	v_mfma_f32_16x16x32_bf16 v[142:145], v[66:69], v[146:149], v[142:145]
	v_mfma_f32_16x16x32_bf16 v[138:141], v[82:85], v[146:149], v[138:141]
	v_mfma_f32_16x16x32_bf16 v[126:129], v[66:69], v[154:157], v[126:129]
	v_mfma_f32_16x16x32_bf16 v[122:125], v[82:85], v[154:157], v[122:125]
	v_mfma_f32_16x16x32_bf16 v[110:113], v[66:69], v[162:165], v[110:113]
	v_mfma_f32_16x16x32_bf16 v[106:109], v[82:85], v[162:165], v[106:109]
	v_mfma_f32_16x16x32_bf16 v[94:97], v[66:69], v[184:187], v[94:97]
	v_mfma_f32_16x16x32_bf16 v[90:93], v[82:85], v[184:187], v[90:93]
	v_mfma_f32_16x16x32_bf16 v[142:145], v[70:73], v[150:153], v[142:145]
	v_mfma_f32_16x16x32_bf16 v[138:141], v[86:89], v[150:153], v[138:141]
	v_mfma_f32_16x16x32_bf16 v[126:129], v[70:73], v[158:161], v[126:129]
	v_mfma_f32_16x16x32_bf16 v[122:125], v[86:89], v[158:161], v[122:125]
	v_mfma_f32_16x16x32_bf16 v[110:113], v[70:73], v[180:183], v[110:113]
	v_mfma_f32_16x16x32_bf16 v[106:109], v[86:89], v[180:183], v[106:109]
	v_mfma_f32_16x16x32_bf16 v[94:97], v[70:73], v[188:191], v[94:97]
	v_mfma_f32_16x16x32_bf16 v[90:93], v[86:89], v[188:191], v[90:93]
	s_barrier
	s_add_i32 s28, 0, 0x1c000
	s_add_i32 s29, s66, s18
	v_add_u32_e32 v204, s28, v226
	v_lshl_add_u64 v[208:209], v[208:209], 0, s[86:87]
	s_mov_b32 m0, s29
	ds_read_b128 v[192:195], v204
	ds_read_b128 v[196:199], v204 offset:1024
	ds_read_b128 v[200:203], v204 offset:2048
	ds_read_b128 v[204:207], v204 offset:3072
	global_load_lds_dwordx4 v[208:209], off
	v_lshl_add_u64 v[208:209], v[228:229], 0, s[86:87]
	s_add_i32 m0, s29, 0x2000
	s_nop 0
	global_load_lds_dwordx4 v[208:209], off
	s_nop 1
	s_mov_b32 m0, s59
	v_lshl_add_u64 v[208:209], v[230:231], 0, s[86:87]
	s_barrier
	s_waitcnt lgkmcnt(0)
	v_mfma_f32_16x16x32_bf16 v[134:137], v[192:195], v[146:149], v[134:137]
	v_mfma_f32_16x16x32_bf16 v[130:133], v[200:203], v[146:149], v[130:133]
	v_mfma_f32_16x16x32_bf16 v[118:121], v[192:195], v[154:157], v[118:121]
	v_mfma_f32_16x16x32_bf16 v[114:117], v[200:203], v[154:157], v[114:117]
	v_mfma_f32_16x16x32_bf16 v[102:105], v[192:195], v[162:165], v[102:105]
	v_mfma_f32_16x16x32_bf16 v[98:101], v[200:203], v[162:165], v[98:101]
	v_mfma_f32_16x16x32_bf16 v[78:81], v[192:195], v[184:187], v[78:81]
	v_mfma_f32_16x16x32_bf16 v[74:77], v[200:203], v[184:187], v[74:77]
	v_mfma_f32_16x16x32_bf16 v[134:137], v[196:199], v[150:153], v[134:137]
	v_mfma_f32_16x16x32_bf16 v[130:133], v[204:207], v[150:153], v[130:133]
	v_mfma_f32_16x16x32_bf16 v[118:121], v[196:199], v[158:161], v[118:121]
	v_mfma_f32_16x16x32_bf16 v[114:117], v[204:207], v[158:161], v[114:117]
	v_mfma_f32_16x16x32_bf16 v[102:105], v[196:199], v[180:183], v[102:105]
	v_mfma_f32_16x16x32_bf16 v[98:101], v[204:207], v[180:183], v[98:101]
	v_mfma_f32_16x16x32_bf16 v[78:81], v[196:199], v[188:191], v[78:81]
	v_mfma_f32_16x16x32_bf16 v[74:77], v[204:207], v[188:191], v[74:77]
	s_barrier
	ds_read_b128 v[146:149], v227 offset:49152
	ds_read_b128 v[150:153], v227 offset:50176
	ds_read_b128 v[154:157], v227 offset:51200
	ds_read_b128 v[158:161], v227 offset:52224
	ds_read_b128 v[162:165], v227 offset:53248
	ds_read_b128 v[180:183], v227 offset:54272
	ds_read_b128 v[184:187], v227 offset:55296
	ds_read_b128 v[188:191], v227 offset:56320
	global_load_lds_dwordx4 v[208:209], off
	v_lshl_add_u64 v[208:209], v[232:233], 0, s[86:87]
	s_mov_b32 m0, s60
	s_nop 0
	global_load_lds_dwordx4 v[208:209], off
	s_barrier
; #define PG8_STAGE(bufoff, gbase, voff) do { _Pragma("unroll") for (int _i = 0; _i < 2; ++_i) \
;         __builtin_amdgcn_global_load_lds((const unsigned*)((const char*)(gbase) + (voff)[_i]), (LAS unsigned*)(lds + (bufoff) + ldsw + _i * 8192), 16, 0, 0); } while (0)
; #define PG8_LDA(dst, b, h) do { _Pragma("unroll") for (int m = 0; m < 4; ++m) _Pragma("unroll") for (int k = 0; k < 2; ++k) dst[m][k] = *(const LAS bf16x8*)(lds + PG8_SA(b, h) + aoff + m * 2048 + k * 1024); } while (0)
; #define PG8_MMA(ai, bj, At, Bt) do { __builtin_amdgcn_s_setprio(1); _Pragma("unroll") for (int m = 0; m < 4; ++m) _Pragma("unroll") for (int n = 0; n < 2; ++n) _Pragma("unroll") for (int k = 0; k < 2; ++k) \
;         acc[ai][bj][m][n] = __builtin_amdgcn_mfma_f32_16x16x32_bf16(Bt[n][k], At[m][k], acc[ai][bj][m][n], 0, 0, 0); __builtin_amdgcn_s_setprio(0); } while (0)
; #define PG8_WAIT_V(n) asm volatile("s_waitcnt vmcnt(" #n ")" ::: "memory")
; #define PG8_WAIT_L(n) asm volatile("s_waitcnt lgkmcnt(" #n ")" ::: "memory")
; template <class Epi>
; __device__ __forceinline__ void gemm_phase(LAS unsigned char* lds, const Gemm g, const Epi& E) {
;     ...
;             PG8_LDA(At, 1, 1); PG8_STAGE(PG8_SA(1, 0), a3, voffA);
;             PG8_BAR; PG8_WAIT_L(0); PG8_MMA(1, 0, At, B0); PG8_BAR; PG8_SCHED;
;             PG8_STAGE(PG8_SB(1, 1), b3 + hstepB, voffB);
;             PG8_WAIT_V(6); PG8_BAR; PG8_MMA(1, 1, At, B1); PG8_BAR;
;         }
;     __device__ __forceinline__ void operator()(const AccT& acc, const Unit& u, int wr, int wc, int fr, int fq) const {
;     ...
;         const int row0 = mapA.src(u.pm) * 256 + wr * 64 + fr, col0 = u.pn * 256 + wc * 32 + 8 * fq;
;         const int hd = u.pn >> 1;
;         f32x4 gw[2][2]; f32x2 st[2][4];
; #pragma unroll
;         for (int bj = 0; bj < 2; ++bj) { gw[bj][0] = *(const f32x4*)(gnw + col0 + bj * 128); gw[bj][1] = *(const f32x4*)(gnw + col0 + bj * 128 + 4); }
; #pragma unroll
;         for (int ai = 0; ai < 2; ++ai)
; #pragma unroll
;             for (int m = 0; m < 4; ++m) st[ai][m] = ST[(size_t)(row0 + ai * 128 + m * 16) * 4 + hd];
; #pragma unroll
;         for (int ai = 0; ai < 2; ++ai) {
;             u32x4 yv[4][2];
; #pragma unroll
;             for (int m = 0; m < 4; ++m)
; #pragma unroll
;                 for (int bj = 0; bj < 2; ++bj) yv[m][bj] = *(const u32x4*)(Y + (size_t)(row0 + ai * 128 + m * 16) * 2048 + col0 + bj * 128);
	s_waitcnt lgkmcnt(0)
	v_mfma_f32_16x16x32_bf16 v[62:65], v[66:69], v[146:149], v[62:65]
	v_mfma_f32_16x16x32_bf16 v[58:61], v[82:85], v[146:149], v[58:61]
	v_mfma_f32_16x16x32_bf16 v[46:49], v[66:69], v[154:157], v[46:49]
	v_mfma_f32_16x16x32_bf16 v[42:45], v[82:85], v[154:157], v[42:45]
	v_mfma_f32_16x16x32_bf16 v[30:33], v[66:69], v[162:165], v[30:33]
	v_mfma_f32_16x16x32_bf16 v[26:29], v[82:85], v[162:165], v[26:29]
	v_mfma_f32_16x16x32_bf16 v[14:17], v[66:69], v[184:187], v[14:17]
	v_mfma_f32_16x16x32_bf16 v[10:13], v[82:85], v[184:187], v[10:13]
	v_mfma_f32_16x16x32_bf16 v[62:65], v[70:73], v[150:153], v[62:65]
	v_mfma_f32_16x16x32_bf16 v[58:61], v[86:89], v[150:153], v[58:61]
	v_mfma_f32_16x16x32_bf16 v[46:49], v[70:73], v[158:161], v[46:49]
	v_mfma_f32_16x16x32_bf16 v[42:45], v[86:89], v[158:161], v[42:45]
	v_mfma_f32_16x16x32_bf16 v[30:33], v[70:73], v[180:183], v[30:33]
	v_mfma_f32_16x16x32_bf16 v[26:29], v[86:89], v[180:183], v[26:29]
	v_mfma_f32_16x16x32_bf16 v[14:17], v[70:73], v[188:191], v[14:17]
	v_mfma_f32_16x16x32_bf16 v[10:13], v[86:89], v[188:191], v[10:13]
	s_barrier
	s_add_u32 s16, s16, 0x40080
	s_addc_u32 s17, s17, 0
	s_add_i32 s28, s28, s18
	v_lshl_add_u64 v[66:67], s[16:17], 0, v[170:171]
	s_mov_b32 m0, s28
	s_nop 0
	global_load_lds_dwordx4 v[66:67], off
	v_lshl_add_u64 v[66:67], s[16:17], 0, v[166:167]
	s_add_i32 m0, s28, 0x2000
	s_nop 0
	global_load_lds_dwordx4 v[66:67], off
	s_add_i32 s65, s65, 2
	s_add_u32 s14, s14, 0x100
	s_addc_u32 s15, s15, 0
	s_add_u32 s9, s9, 0x100
	s_addc_u32 s53, s53, 0
	s_cmp_gt_u32 s65, 13
	s_waitcnt vmcnt(6)
	s_barrier
	v_mfma_f32_16x16x32_bf16 v[54:57], v[192:195], v[146:149], v[54:57]
	v_mfma_f32_16x16x32_bf16 v[50:53], v[200:203], v[146:149], v[50:53]
	v_mfma_f32_16x16x32_bf16 v[38:41], v[192:195], v[154:157], v[38:41]
	v_mfma_f32_16x16x32_bf16 v[34:37], v[200:203], v[154:157], v[34:37]
	v_mfma_f32_16x16x32_bf16 v[22:25], v[192:195], v[162:165], v[22:25]
	v_mfma_f32_16x16x32_bf16 v[18:21], v[200:203], v[162:165], v[18:21]
	v_mfma_f32_16x16x32_bf16 v[6:9], v[192:195], v[184:187], v[6:9]
	v_mfma_f32_16x16x32_bf16 v[2:5], v[200:203], v[184:187], v[2:5]
	v_mfma_f32_16x16x32_bf16 v[54:57], v[196:199], v[150:153], v[54:57]
	v_mfma_f32_16x16x32_bf16 v[50:53], v[204:207], v[150:153], v[50:53]
	v_mfma_f32_16x16x32_bf16 v[38:41], v[196:199], v[158:161], v[38:41]
	v_mfma_f32_16x16x32_bf16 v[34:37], v[204:207], v[158:161], v[34:37]
	v_mfma_f32_16x16x32_bf16 v[22:25], v[196:199], v[180:183], v[22:25]
	v_mfma_f32_16x16x32_bf16 v[18:21], v[204:207], v[180:183], v[18:21]
	v_mfma_f32_16x16x32_bf16 v[6:9], v[196:199], v[188:191], v[6:9]
	v_mfma_f32_16x16x32_bf16 v[2:5], v[204:207], v[188:191], v[2:5]
	s_barrier
	s_cbranch_scc0 .LBB0_475
	v_readlane_b32 s9, v255, 27
	s_cmp_ge_i32 s52, s9
	s_cselect_b32 s9, s25, 0
	s_lshl_b32 s14, s12, 8
	v_mov_b32_e32 v148, v225
	v_mov_b32_e32 v66, v1
	s_add_i32 s9, s52, s9
	s_or_b32 s14, s14, s58
	s_lshl_b32 s9, s9, 8
	v_lshl_add_u32 v146, v66, 3, s14
	s_ashr_i32 s14, s12, 1
	s_add_i32 s9, s9, s50
	s_ashr_i32 s15, s14, 31
	v_add_u32_e32 v148, s9, v148
	s_lshl_b64 s[14:15], s[14:15], 3
	s_add_u32 s14, s26, s14
	v_ashrrev_i32_e32 v149, 31, v148
	v_add_u32_e32 v152, 16, v148
	v_add_u32_e32 v156, 32, v148
	v_add_u32_e32 v202, 48, v148
	v_ashrrev_i32_e32 v147, 31, v146
	s_addc_u32 s15, s27, s15
	v_lshlrev_b64 v[150:151], 5, v[148:149]
	v_ashrrev_i32_e32 v153, 31, v152
	v_ashrrev_i32_e32 v157, 31, v156
	v_ashrrev_i32_e32 v203, 31, v202
	v_add_u32_e32 v190, 0x80, v148
	v_lshl_add_u64 v[70:71], v[146:147], 2, s[6:7]
	v_lshl_add_u64 v[150:151], s[14:15], 0, v[150:151]
	v_lshlrev_b64 v[154:155], 5, v[152:153]
	v_lshlrev_b64 v[158:159], 5, v[156:157]
	v_lshlrev_b64 v[160:161], 5, v[202:203]
	v_ashrrev_i32_e32 v191, 31, v190
	v_add_u32_e32 v192, 0x90, v148
	v_add_u32_e32 v194, 0xa0, v148
	v_add_u32_e32 v196, 0xb0, v148
	v_lshlrev_b64 v[182:183], 1, v[146:147]
	global_load_dwordx4 v[82:85], v[70:71], off offset:16
	global_load_dwordx4 v[86:89], v[70:71], off
	global_load_dwordx4 v[66:69], v[70:71], off offset:528
	s_nop 0
	global_load_dwordx4 v[70:73], v[70:71], off offset:512
	v_lshl_add_u64 v[154:155], s[14:15], 0, v[154:155]
	v_lshl_add_u64 v[158:159], s[14:15], 0, v[158:159]
	v_lshl_add_u64 v[160:161], s[14:15], 0, v[160:161]
	global_load_dwordx2 v[240:241], v[150:151], off
	global_load_dwordx2 v[208:209], v[154:155], off
	global_load_dwordx2 v[204:205], v[158:159], off
	global_load_dwordx2 v[200:201], v[160:161], off
	v_lshlrev_b64 v[150:151], 5, v[190:191]
	v_ashrrev_i32_e32 v193, 31, v192
	v_ashrrev_i32_e32 v195, 31, v194
	v_ashrrev_i32_e32 v197, 31, v196
	v_lshl_add_u64 v[198:199], s[38:39], 0, v[182:183]
	v_lshlrev_b64 v[242:243], 12, v[148:149]
	v_lshl_add_u64 v[150:151], s[14:15], 0, v[150:151]
	v_lshlrev_b64 v[154:155], 5, v[192:193]
	v_lshlrev_b64 v[158:159], 5, v[194:195]
	v_lshlrev_b64 v[160:161], 5, v[196:197]
	v_lshl_add_u64 v[146:147], v[198:199], 0, v[242:243]
	v_lshlrev_b64 v[244:245], 12, v[152:153]
	v_lshl_add_u64 v[154:155], s[14:15], 0, v[154:155]
	v_lshl_add_u64 v[158:159], s[14:15], 0, v[158:159]
	v_lshl_add_u64 v[160:161], s[14:15], 0, v[160:161]
	global_load_dwordx2 v[188:189], v[150:151], off
	global_load_dwordx2 v[186:187], v[154:155], off
	global_load_dwordx2 v[184:185], v[158:159], off
	global_load_dwordx2 v[180:181], v[160:161], off
	global_load_dwordx4 v[228:231], v[146:147], off
	global_load_dwordx4 v[232:235], v[146:147], off offset:256
	v_lshl_add_u64 v[146:147], v[198:199], 0, v[244:245]
	v_lshlrev_b64 v[206:207], 12, v[156:157]
	global_load_dwordx4 v[236:239], v[146:147], off
	global_load_dwordx4 v[162:165], v[146:147], off offset:256
	v_lshl_add_u64 v[146:147], v[198:199], 0, v[206:207]
	v_lshlrev_b64 v[202:203], 12, v[202:203]
	global_load_dwordx4 v[158:161], v[146:147], off
	global_load_dwordx4 v[154:157], v[146:147], off offset:256
	v_lshl_add_u64 v[146:147], v[198:199], 0, v[202:203]
	global_load_dwordx4 v[150:153], v[146:147], off
	s_nop 0
	global_load_dwordx4 v[146:149], v[146:147], off offset:256
	s_waitcnt vmcnt(0)
; __device__ __forceinline__ unsigned cvt_pk_bf16(float lo, float hi) { unsigned r; asm("v_cvt_pk_bf16_f32 %0, %1, %2" : "=v"(r) : "v"(lo), "v"(hi)); return r; }
; __device__ __forceinline__ float bf_lo(unsigned u) { return __uint_as_float(u << 16); }
; __device__ __forceinline__ float bf_hi(unsigned u) { return __uint_as_float(u & 0xffff0000u); }
; __device__ __forceinline__ f32x4 silu4(f32x4 v) {
;     f32x4 e, r;
; #pragma unroll
;     for (int j = 0; j < 4; ++j) e[j] = __builtin_amdgcn_exp2f(v[j] * -1.4426950408889634f);
; #pragma unroll
;     for (int j = 0; j < 4; ++j) r[j] = __builtin_amdgcn_rcpf(1.0f + e[j]);
;     return v * r;
; }
;     __device__ __forceinline__ void operator()(const AccT& acc, const Unit& u, int wr, int wc, int fr, int fq) const {
;     ...
;                 for (int bj = 0; bj < 2; ++bj) yv[m][bj] = *(const u32x4*)(Y + (size_t)(row0 + ai * 128 + m * 16) * 2048 + col0 + bj * 128);
;             __builtin_amdgcn_sched_barrier(0);
; #pragma unroll
;             for (int m = 0; m < 4; ++m) { bf16_t* rowp = A2 + (size_t)(row0 + ai * 128 + m * 16) * 2048 + col0;
;                 const float mu = st[ai][m][0], rs = st[ai][m][1];
; #pragma unroll
;                 for (int bj = 0; bj < 2; ++bj) { const f32x4 v0 = acc[ai][bj][m][0], v1 = acc[ai][bj][m][1]; const u32x4 yw = yv[m][bj];
;                     const f32x4 y0 = (f32x4){bf_lo(yw.x), bf_hi(yw.x), bf_lo(yw.y), bf_hi(yw.y)}, y1 = (f32x4){bf_lo(yw.z), bf_hi(yw.z), bf_lo(yw.w), bf_hi(yw.w)};
;                     const f32x4 n0 = (y0 - mu) * rs * gw[bj][0], n1 = (y1 - mu) * rs * gw[bj][1];
;                     const f32x4 s0 = silu4(v0) * n0, s1 = silu4(v1) * n1;
;                     u32x4 w; w.x = cvt_pk_bf16(s0[0], s0[1]); w.y = cvt_pk_bf16(s0[2], s0[3]); w.z = cvt_pk_bf16(s1[0], s1[1]); w.w = cvt_pk_bf16(s1[2], s1[3]);
;                     *(u32x4*)(rowp + bj * 128) = w; } }
	v_lshlrev_b32_e32 v246, 16, v228
	v_and_b32_e32 v228, 0xffff0000, v228
	v_lshlrev_b32_e32 v247, 16, v229
	v_and_b32_e32 v248, 0xffff0000, v229
	v_lshlrev_b32_e32 v249, 16, v230
	v_and_b32_e32 v250, 0xffff0000, v230
	v_lshlrev_b32_e32 v251, 16, v231
	v_and_b32_e32 v252, 0xffff0000, v231
	v_sub_f32_e32 v229, v228, v240
	v_sub_f32_e32 v228, v246, v240
	v_sub_f32_e32 v231, v248, v240
	v_sub_f32_e32 v230, v247, v240
	v_sub_f32_e32 v247, v250, v240
	v_sub_f32_e32 v246, v249, v240
	v_sub_f32_e32 v249, v252, v240
	v_sub_f32_e32 v248, v251, v240
	v_mul_f32_e32 v250, 0xbfb8aa3b, v142
	v_mul_f32_e32 v251, 0xbfb8aa3b, v143
	v_mul_f32_e32 v252, 0xbfb8aa3b, v144
	v_mul_f32_e32 v253, 0xbfb8aa3b, v145
	v_exp_f32_e32 v250, v250
	v_exp_f32_e32 v251, v251
	v_exp_f32_e32 v252, v252
	v_exp_f32_e32 v253, v253
	v_add_f32_e32 v250, 1.0, v250
	v_add_f32_e32 v251, 1.0, v251
	v_add_f32_e32 v252, 1.0, v252
	v_add_f32_e32 v253, 1.0, v253
	v_rcp_f32_e32 v250, v250
	v_rcp_f32_e32 v251, v251
	v_rcp_f32_e32 v252, v252
	v_rcp_f32_e32 v253, v253
	v_pk_mul_f32 v[228:229], v[240:241], v[228:229] op_sel:[1,0]
	v_pk_mul_f32 v[142:143], v[142:143], v[250:251]
	v_mul_f32_e32 v250, 0xbfb8aa3b, v138
	v_pk_mul_f32 v[144:145], v[144:145], v[252:253]
	v_mul_f32_e32 v251, 0xbfb8aa3b, v139
	v_mul_f32_e32 v252, 0xbfb8aa3b, v140
	v_mul_f32_e32 v253, 0xbfb8aa3b, v141
	v_exp_f32_e32 v250, v250
	v_exp_f32_e32 v251, v251
	v_exp_f32_e32 v252, v252
	v_exp_f32_e32 v253, v253
	v_add_f32_e32 v250, 1.0, v250
	v_add_f32_e32 v251, 1.0, v251
	v_add_f32_e32 v252, 1.0, v252
	v_add_f32_e32 v253, 1.0, v253
	v_rcp_f32_e32 v250, v250
	v_rcp_f32_e32 v251, v251
	v_rcp_f32_e32 v252, v252
	v_rcp_f32_e32 v253, v253
	v_pk_mul_f32 v[248:249], v[240:241], v[248:249] op_sel:[1,0]
	v_pk_mul_f32 v[246:247], v[240:241], v[246:247] op_sel:[1,0]
	v_pk_mul_f32 v[230:231], v[240:241], v[230:231] op_sel:[1,0]
	v_pk_mul_f32 v[228:229], v[86:87], v[228:229]
	v_pk_mul_f32 v[246:247], v[82:83], v[246:247]
	v_pk_mul_f32 v[248:249], v[84:85], v[248:249]
	v_pk_mul_f32 v[138:139], v[138:139], v[250:251]
	v_pk_mul_f32 v[140:141], v[140:141], v[252:253]
	v_pk_mul_f32 v[230:231], v[88:89], v[230:231]
	v_pk_mul_f32 v[142:143], v[142:143], v[228:229]
	v_pk_mul_f32 v[228:229], v[140:141], v[248:249]
	v_pk_mul_f32 v[140:141], v[138:139], v[246:247]
	v_pk_mul_f32 v[144:145], v[144:145], v[230:231]
	v_cvt_pk_bf16_f32 v140, v140, v141
	v_cvt_pk_bf16_f32 v141, v228, v229
	v_mul_f32_e32 v228, 0xbfb8aa3b, v134
	v_mul_f32_e32 v229, 0xbfb8aa3b, v135
	v_mul_f32_e32 v230, 0xbfb8aa3b, v136
	v_mul_f32_e32 v231, 0xbfb8aa3b, v137
	v_exp_f32_e32 v228, v228
	v_exp_f32_e32 v229, v229
	v_exp_f32_e32 v230, v230
	v_exp_f32_e32 v231, v231
	v_add_f32_e32 v228, 1.0, v228
	v_add_f32_e32 v229, 1.0, v229
	v_add_f32_e32 v230, 1.0, v230
	v_add_f32_e32 v231, 1.0, v231
	v_rcp_f32_e32 v228, v228
	v_rcp_f32_e32 v229, v229
	v_rcp_f32_e32 v230, v230
	v_rcp_f32_e32 v231, v231
	v_lshl_add_u64 v[242:243], s[34:35], 0, v[242:243]
	v_pk_mul_f32 v[134:135], v[134:135], v[228:229]
	v_mul_f32_e32 v228, 0xbfb8aa3b, v130
	v_pk_mul_f32 v[136:137], v[136:137], v[230:231]
	v_mul_f32_e32 v229, 0xbfb8aa3b, v131
	v_mul_f32_e32 v230, 0xbfb8aa3b, v132
	v_mul_f32_e32 v231, 0xbfb8aa3b, v133
	v_exp_f32_e32 v228, v228
	v_exp_f32_e32 v229, v229
	v_exp_f32_e32 v230, v230
	v_exp_f32_e32 v231, v231
	v_add_f32_e32 v228, 1.0, v228
	v_add_f32_e32 v229, 1.0, v229
	v_add_f32_e32 v230, 1.0, v230
	v_add_f32_e32 v231, 1.0, v231
	v_lshl_add_u64 v[242:243], v[242:243], 0, v[182:183]
	v_cvt_pk_bf16_f32 v138, v142, v143
	v_cvt_pk_bf16_f32 v139, v144, v145
	v_rcp_f32_e32 v228, v228
	v_rcp_f32_e32 v229, v229
	v_rcp_f32_e32 v230, v230
	v_rcp_f32_e32 v231, v231
	global_store_dwordx4 v[242:243], v[138:141], off
	v_lshlrev_b32_e32 v142, 16, v234
	v_and_b32_e32 v143, 0xffff0000, v234
	v_lshlrev_b32_e32 v138, 16, v232
	v_and_b32_e32 v139, 0xffff0000, v232
	v_lshlrev_b32_e32 v140, 16, v233
	v_and_b32_e32 v141, 0xffff0000, v233
	v_lshlrev_b32_e32 v144, 16, v235
	v_and_b32_e32 v145, 0xffff0000, v235
	v_sub_f32_e32 v139, v139, v240
	v_sub_f32_e32 v138, v138, v240
	v_sub_f32_e32 v141, v141, v240
	v_sub_f32_e32 v140, v140, v240
	v_sub_f32_e32 v143, v143, v240
	v_sub_f32_e32 v142, v142, v240
	v_sub_f32_e32 v145, v145, v240
	v_sub_f32_e32 v144, v144, v240
	v_pk_mul_f32 v[140:141], v[240:241], v[140:141] op_sel:[1,0]
	v_pk_mul_f32 v[138:139], v[240:241], v[138:139] op_sel:[1,0]
	v_pk_mul_f32 v[144:145], v[240:241], v[144:145] op_sel:[1,0]
	v_pk_mul_f32 v[142:143], v[240:241], v[142:143] op_sel:[1,0]
	v_pk_mul_f32 v[138:139], v[70:71], v[138:139]
	v_pk_mul_f32 v[140:141], v[72:73], v[140:141]
	v_pk_mul_f32 v[142:143], v[66:67], v[142:143]
	v_pk_mul_f32 v[144:145], v[68:69], v[144:145]
	v_pk_mul_f32 v[130:131], v[130:131], v[228:229]
	v_pk_mul_f32 v[132:133], v[132:133], v[230:231]
	v_pk_mul_f32 v[136:137], v[136:137], v[140:141]
	v_pk_mul_f32 v[134:135], v[134:135], v[138:139]
	v_pk_mul_f32 v[138:139], v[132:133], v[144:145]
	v_pk_mul_f32 v[132:133], v[130:131], v[142:143]
	v_mul_f32_e32 v140, 0xbfb8aa3b, v126
	v_mul_f32_e32 v141, 0xbfb8aa3b, v127
	v_mul_f32_e32 v142, 0xbfb8aa3b, v128
	v_mul_f32_e32 v143, 0xbfb8aa3b, v129
	v_exp_f32_e32 v140, v140
	v_exp_f32_e32 v141, v141
	v_exp_f32_e32 v142, v142
	v_exp_f32_e32 v143, v143
	v_add_f32_e32 v140, 1.0, v140
	v_add_f32_e32 v141, 1.0, v141
	v_add_f32_e32 v142, 1.0, v142
	v_add_f32_e32 v143, 1.0, v143
	v_rcp_f32_e32 v140, v140
	v_rcp_f32_e32 v141, v141
	v_rcp_f32_e32 v142, v142
	v_rcp_f32_e32 v143, v143
	v_cvt_pk_bf16_f32 v132, v132, v133
	v_pk_mul_f32 v[126:127], v[126:127], v[140:141]
	v_mul_f32_e32 v140, 0xbfb8aa3b, v122
	v_pk_mul_f32 v[128:129], v[128:129], v[142:143]
; __device__ __forceinline__ unsigned cvt_pk_bf16(float lo, float hi) { unsigned r; asm("v_cvt_pk_bf16_f32 %0, %1, %2" : "=v"(r) : "v"(lo), "v"(hi)); return r; }
; __device__ __forceinline__ float bf_lo(unsigned u) { return __uint_as_float(u << 16); }
; __device__ __forceinline__ float bf_hi(unsigned u) { return __uint_as_float(u & 0xffff0000u); }
; __device__ __forceinline__ f32x4 silu4(f32x4 v) {
;     f32x4 e, r;
; #pragma unroll
;     for (int j = 0; j < 4; ++j) e[j] = __builtin_amdgcn_exp2f(v[j] * -1.4426950408889634f);
; #pragma unroll
;     for (int j = 0; j < 4; ++j) r[j] = __builtin_amdgcn_rcpf(1.0f + e[j]);
;     return v * r;
; }
;     __device__ __forceinline__ void operator()(const AccT& acc, const Unit& u, int wr, int wc, int fr, int fq) const {
;     ...
;                 for (int bj = 0; bj < 2; ++bj) yv[m][bj] = *(const u32x4*)(Y + (size_t)(row0 + ai * 128 + m * 16) * 2048 + col0 + bj * 128);
;             __builtin_amdgcn_sched_barrier(0);
; #pragma unroll
;             for (int m = 0; m < 4; ++m) { bf16_t* rowp = A2 + (size_t)(row0 + ai * 128 + m * 16) * 2048 + col0;
;                 const float mu = st[ai][m][0], rs = st[ai][m][1];
; #pragma unroll
;                 for (int bj = 0; bj < 2; ++bj) { const f32x4 v0 = acc[ai][bj][m][0], v1 = acc[ai][bj][m][1]; const u32x4 yw = yv[m][bj];
;                     const f32x4 y0 = (f32x4){bf_lo(yw.x), bf_hi(yw.x), bf_lo(yw.y), bf_hi(yw.y)}, y1 = (f32x4){bf_lo(yw.z), bf_hi(yw.z), bf_lo(yw.w), bf_hi(yw.w)};
;                     const f32x4 n0 = (y0 - mu) * rs * gw[bj][0], n1 = (y1 - mu) * rs * gw[bj][1];
;                     const f32x4 s0 = silu4(v0) * n0, s1 = silu4(v1) * n1;
;                     u32x4 w; w.x = cvt_pk_bf16(s0[0], s0[1]); w.y = cvt_pk_bf16(s0[2], s0[3]); w.z = cvt_pk_bf16(s1[0], s1[1]); w.w = cvt_pk_bf16(s1[2], s1[3]);
;                     *(u32x4*)(rowp + bj * 128) = w; } }
	v_mul_f32_e32 v141, 0xbfb8aa3b, v123
	v_mul_f32_e32 v142, 0xbfb8aa3b, v124
	v_mul_f32_e32 v143, 0xbfb8aa3b, v125
	v_exp_f32_e32 v140, v140
	v_exp_f32_e32 v141, v141
	v_exp_f32_e32 v142, v142
	v_exp_f32_e32 v143, v143
	v_add_f32_e32 v140, 1.0, v140
	v_add_f32_e32 v141, 1.0, v141
	v_add_f32_e32 v142, 1.0, v142
	v_add_f32_e32 v143, 1.0, v143
	v_cvt_pk_bf16_f32 v133, v138, v139
	v_rcp_f32_e32 v140, v140
	v_rcp_f32_e32 v141, v141
	v_rcp_f32_e32 v142, v142
	v_rcp_f32_e32 v143, v143
	v_cvt_pk_bf16_f32 v130, v134, v135
	v_cvt_pk_bf16_f32 v131, v136, v137
	global_store_dwordx4 v[242:243], v[130:133], off offset:256
	v_lshlrev_b32_e32 v136, 16, v238
	v_and_b32_e32 v137, 0xffff0000, v238
	v_lshlrev_b32_e32 v132, 16, v236
	v_and_b32_e32 v133, 0xffff0000, v236
	v_lshlrev_b32_e32 v138, 16, v239
	v_and_b32_e32 v139, 0xffff0000, v239
	v_lshlrev_b32_e32 v134, 16, v237
	v_and_b32_e32 v135, 0xffff0000, v237
	v_sub_f32_e32 v133, v133, v208
	v_sub_f32_e32 v132, v132, v208
	v_sub_f32_e32 v137, v137, v208
	v_sub_f32_e32 v136, v136, v208
	v_sub_f32_e32 v139, v139, v208
	v_sub_f32_e32 v138, v138, v208
	v_sub_f32_e32 v135, v135, v208
	v_sub_f32_e32 v134, v134, v208
	v_pk_mul_f32 v[132:133], v[208:209], v[132:133] op_sel:[1,0]
	v_pk_mul_f32 v[138:139], v[208:209], v[138:139] op_sel:[1,0]
	v_pk_mul_f32 v[136:137], v[208:209], v[136:137] op_sel:[1,0]
	v_pk_mul_f32 v[134:135], v[208:209], v[134:135] op_sel:[1,0]
	v_pk_mul_f32 v[132:133], v[86:87], v[132:133]
	v_pk_mul_f32 v[136:137], v[82:83], v[136:137]
	v_pk_mul_f32 v[138:139], v[84:85], v[138:139]
	v_pk_mul_f32 v[122:123], v[122:123], v[140:141]
	v_pk_mul_f32 v[124:125], v[124:125], v[142:143]
	v_pk_mul_f32 v[134:135], v[88:89], v[134:135]
	v_pk_mul_f32 v[126:127], v[126:127], v[132:133]
	v_pk_mul_f32 v[132:133], v[124:125], v[138:139]
	v_pk_mul_f32 v[124:125], v[122:123], v[136:137]
	v_pk_mul_f32 v[128:129], v[128:129], v[134:135]
	v_cvt_pk_bf16_f32 v124, v124, v125
	v_cvt_pk_bf16_f32 v125, v132, v133
	v_mul_f32_e32 v132, 0xbfb8aa3b, v118
	v_mul_f32_e32 v133, 0xbfb8aa3b, v119
	v_mul_f32_e32 v134, 0xbfb8aa3b, v120
	v_mul_f32_e32 v135, 0xbfb8aa3b, v121
	v_exp_f32_e32 v132, v132
	v_exp_f32_e32 v133, v133
	v_exp_f32_e32 v134, v134
	v_exp_f32_e32 v135, v135
	v_add_f32_e32 v132, 1.0, v132
	v_add_f32_e32 v133, 1.0, v133
	v_add_f32_e32 v134, 1.0, v134
	v_add_f32_e32 v135, 1.0, v135
	v_rcp_f32_e32 v132, v132
	v_rcp_f32_e32 v133, v133
	v_rcp_f32_e32 v134, v134
	v_rcp_f32_e32 v135, v135
	v_lshl_add_u64 v[130:131], s[34:35], 0, v[244:245]
	v_pk_mul_f32 v[118:119], v[118:119], v[132:133]
	v_mul_f32_e32 v132, 0xbfb8aa3b, v114
	v_pk_mul_f32 v[120:121], v[120:121], v[134:135]
	v_mul_f32_e32 v133, 0xbfb8aa3b, v115
	v_mul_f32_e32 v134, 0xbfb8aa3b, v116
	v_mul_f32_e32 v135, 0xbfb8aa3b, v117
	v_exp_f32_e32 v132, v132
	v_exp_f32_e32 v133, v133
	v_exp_f32_e32 v134, v134
	v_exp_f32_e32 v135, v135
	v_add_f32_e32 v132, 1.0, v132
	v_add_f32_e32 v133, 1.0, v133
	v_add_f32_e32 v134, 1.0, v134
	v_add_f32_e32 v135, 1.0, v135
	v_lshl_add_u64 v[130:131], v[130:131], 0, v[182:183]
	v_cvt_pk_bf16_f32 v122, v126, v127
	v_cvt_pk_bf16_f32 v123, v128, v129
	v_rcp_f32_e32 v132, v132
	v_rcp_f32_e32 v133, v133
	v_rcp_f32_e32 v134, v134
	v_rcp_f32_e32 v135, v135
	global_store_dwordx4 v[130:131], v[122:125], off
	v_lshlrev_b32_e32 v126, 16, v164
	v_and_b32_e32 v127, 0xffff0000, v164
	v_lshlrev_b32_e32 v122, 16, v162
	v_and_b32_e32 v123, 0xffff0000, v162
	v_lshlrev_b32_e32 v124, 16, v163
	v_and_b32_e32 v125, 0xffff0000, v163
	v_lshlrev_b32_e32 v128, 16, v165
	v_and_b32_e32 v129, 0xffff0000, v165
	v_sub_f32_e32 v123, v123, v208
	v_sub_f32_e32 v122, v122, v208
	v_sub_f32_e32 v125, v125, v208
	v_sub_f32_e32 v124, v124, v208
	v_sub_f32_e32 v127, v127, v208
	v_sub_f32_e32 v126, v126, v208
	v_sub_f32_e32 v129, v129, v208
	v_sub_f32_e32 v128, v128, v208
	v_pk_mul_f32 v[124:125], v[208:209], v[124:125] op_sel:[1,0]
	v_pk_mul_f32 v[122:123], v[208:209], v[122:123] op_sel:[1,0]
	v_pk_mul_f32 v[128:129], v[208:209], v[128:129] op_sel:[1,0]
	v_pk_mul_f32 v[126:127], v[208:209], v[126:127] op_sel:[1,0]
	v_pk_mul_f32 v[122:123], v[70:71], v[122:123]
	v_pk_mul_f32 v[124:125], v[72:73], v[124:125]
	v_pk_mul_f32 v[126:127], v[66:67], v[126:127]
	v_pk_mul_f32 v[128:129], v[68:69], v[128:129]
	v_pk_mul_f32 v[114:115], v[114:115], v[132:133]
	v_pk_mul_f32 v[116:117], v[116:117], v[134:135]
	v_pk_mul_f32 v[120:121], v[120:121], v[124:125]
	v_pk_mul_f32 v[118:119], v[118:119], v[122:123]
	v_pk_mul_f32 v[122:123], v[116:117], v[128:129]
	v_pk_mul_f32 v[116:117], v[114:115], v[126:127]
	v_mul_f32_e32 v124, 0xbfb8aa3b, v110
	v_mul_f32_e32 v125, 0xbfb8aa3b, v111
	v_mul_f32_e32 v126, 0xbfb8aa3b, v112
	v_mul_f32_e32 v127, 0xbfb8aa3b, v113
	v_exp_f32_e32 v124, v124
	v_exp_f32_e32 v125, v125
	v_exp_f32_e32 v126, v126
	v_exp_f32_e32 v127, v127
	v_add_f32_e32 v124, 1.0, v124
	v_add_f32_e32 v125, 1.0, v125
	v_add_f32_e32 v126, 1.0, v126
	v_add_f32_e32 v127, 1.0, v127
	v_rcp_f32_e32 v124, v124
	v_rcp_f32_e32 v125, v125
	v_rcp_f32_e32 v126, v126
	v_rcp_f32_e32 v127, v127
	v_cvt_pk_bf16_f32 v116, v116, v117
	v_pk_mul_f32 v[110:111], v[110:111], v[124:125]
	v_mul_f32_e32 v124, 0xbfb8aa3b, v106
	v_pk_mul_f32 v[112:113], v[112:113], v[126:127]
	v_mul_f32_e32 v125, 0xbfb8aa3b, v107
	v_mul_f32_e32 v126, 0xbfb8aa3b, v108
	v_mul_f32_e32 v127, 0xbfb8aa3b, v109
	v_exp_f32_e32 v124, v124
	v_exp_f32_e32 v125, v125
	v_exp_f32_e32 v126, v126
	v_exp_f32_e32 v127, v127
	v_add_f32_e32 v124, 1.0, v124
	v_add_f32_e32 v125, 1.0, v125
	v_add_f32_e32 v126, 1.0, v126
	v_add_f32_e32 v127, 1.0, v127
	v_cvt_pk_bf16_f32 v117, v122, v123
	v_rcp_f32_e32 v124, v124
	v_rcp_f32_e32 v125, v125
	v_rcp_f32_e32 v126, v126
; __device__ __forceinline__ unsigned cvt_pk_bf16(float lo, float hi) { unsigned r; asm("v_cvt_pk_bf16_f32 %0, %1, %2" : "=v"(r) : "v"(lo), "v"(hi)); return r; }
; __device__ __forceinline__ float bf_lo(unsigned u) { return __uint_as_float(u << 16); }
; __device__ __forceinline__ float bf_hi(unsigned u) { return __uint_as_float(u & 0xffff0000u); }
; __device__ __forceinline__ f32x4 silu4(f32x4 v) {
;     f32x4 e, r;
; #pragma unroll
;     for (int j = 0; j < 4; ++j) e[j] = __builtin_amdgcn_exp2f(v[j] * -1.4426950408889634f);
; #pragma unroll
;     for (int j = 0; j < 4; ++j) r[j] = __builtin_amdgcn_rcpf(1.0f + e[j]);
;     return v * r;
; }
;     __device__ __forceinline__ void operator()(const AccT& acc, const Unit& u, int wr, int wc, int fr, int fq) const {
;     ...
;                 for (int bj = 0; bj < 2; ++bj) yv[m][bj] = *(const u32x4*)(Y + (size_t)(row0 + ai * 128 + m * 16) * 2048 + col0 + bj * 128);
;             __builtin_amdgcn_sched_barrier(0);
; #pragma unroll
;             for (int m = 0; m < 4; ++m) { bf16_t* rowp = A2 + (size_t)(row0 + ai * 128 + m * 16) * 2048 + col0;
;                 const float mu = st[ai][m][0], rs = st[ai][m][1];
; #pragma unroll
;                 for (int bj = 0; bj < 2; ++bj) { const f32x4 v0 = acc[ai][bj][m][0], v1 = acc[ai][bj][m][1]; const u32x4 yw = yv[m][bj];
;                     const f32x4 y0 = (f32x4){bf_lo(yw.x), bf_hi(yw.x), bf_lo(yw.y), bf_hi(yw.y)}, y1 = (f32x4){bf_lo(yw.z), bf_hi(yw.z), bf_lo(yw.w), bf_hi(yw.w)};
;                     const f32x4 n0 = (y0 - mu) * rs * gw[bj][0], n1 = (y1 - mu) * rs * gw[bj][1];
;                     const f32x4 s0 = silu4(v0) * n0, s1 = silu4(v1) * n1;
;                     u32x4 w; w.x = cvt_pk_bf16(s0[0], s0[1]); w.y = cvt_pk_bf16(s0[2], s0[3]); w.z = cvt_pk_bf16(s1[0], s1[1]); w.w = cvt_pk_bf16(s1[2], s1[3]);
;                     *(u32x4*)(rowp + bj * 128) = w; } }
	v_rcp_f32_e32 v127, v127
	v_cvt_pk_bf16_f32 v114, v118, v119
	v_cvt_pk_bf16_f32 v115, v120, v121
	global_store_dwordx4 v[130:131], v[114:117], off offset:256
	v_lshlrev_b32_e32 v120, 16, v160
	v_and_b32_e32 v121, 0xffff0000, v160
	v_lshlrev_b32_e32 v116, 16, v158
	v_and_b32_e32 v117, 0xffff0000, v158
	v_lshlrev_b32_e32 v122, 16, v161
	v_and_b32_e32 v123, 0xffff0000, v161
	v_lshlrev_b32_e32 v118, 16, v159
	v_and_b32_e32 v119, 0xffff0000, v159
	v_sub_f32_e32 v117, v117, v204
	v_sub_f32_e32 v116, v116, v204
	v_sub_f32_e32 v121, v121, v204
	v_sub_f32_e32 v120, v120, v204
	v_sub_f32_e32 v123, v123, v204
	v_sub_f32_e32 v122, v122, v204
	v_sub_f32_e32 v119, v119, v204
	v_sub_f32_e32 v118, v118, v204
	v_pk_mul_f32 v[116:117], v[204:205], v[116:117] op_sel:[1,0]
	v_pk_mul_f32 v[122:123], v[204:205], v[122:123] op_sel:[1,0]
	v_pk_mul_f32 v[120:121], v[204:205], v[120:121] op_sel:[1,0]
	v_pk_mul_f32 v[118:119], v[204:205], v[118:119] op_sel:[1,0]
	v_pk_mul_f32 v[116:117], v[86:87], v[116:117]
	v_pk_mul_f32 v[120:121], v[82:83], v[120:121]
	v_pk_mul_f32 v[122:123], v[84:85], v[122:123]
	v_pk_mul_f32 v[106:107], v[106:107], v[124:125]
	v_pk_mul_f32 v[108:109], v[108:109], v[126:127]
	v_pk_mul_f32 v[118:119], v[88:89], v[118:119]
	v_pk_mul_f32 v[110:111], v[110:111], v[116:117]
	v_pk_mul_f32 v[116:117], v[108:109], v[122:123]
	v_pk_mul_f32 v[108:109], v[106:107], v[120:121]
	v_pk_mul_f32 v[112:113], v[112:113], v[118:119]
	v_cvt_pk_bf16_f32 v108, v108, v109
	v_cvt_pk_bf16_f32 v109, v116, v117
	v_mul_f32_e32 v116, 0xbfb8aa3b, v102
	v_mul_f32_e32 v117, 0xbfb8aa3b, v103
	v_mul_f32_e32 v118, 0xbfb8aa3b, v104
	v_mul_f32_e32 v119, 0xbfb8aa3b, v105
	v_exp_f32_e32 v116, v116
	v_exp_f32_e32 v117, v117
	v_exp_f32_e32 v118, v118
	v_exp_f32_e32 v119, v119
	v_add_f32_e32 v116, 1.0, v116
	v_add_f32_e32 v117, 1.0, v117
	v_add_f32_e32 v118, 1.0, v118
	v_add_f32_e32 v119, 1.0, v119
	v_rcp_f32_e32 v116, v116
	v_rcp_f32_e32 v117, v117
	v_rcp_f32_e32 v118, v118
	v_rcp_f32_e32 v119, v119
	v_lshl_add_u64 v[114:115], s[34:35], 0, v[206:207]
	v_pk_mul_f32 v[102:103], v[102:103], v[116:117]
	v_mul_f32_e32 v116, 0xbfb8aa3b, v98
	v_pk_mul_f32 v[104:105], v[104:105], v[118:119]
	v_mul_f32_e32 v117, 0xbfb8aa3b, v99
	v_mul_f32_e32 v118, 0xbfb8aa3b, v100
	v_mul_f32_e32 v119, 0xbfb8aa3b, v101
	v_exp_f32_e32 v116, v116
	v_exp_f32_e32 v117, v117
	v_exp_f32_e32 v118, v118
	v_exp_f32_e32 v119, v119
	v_add_f32_e32 v116, 1.0, v116
	v_add_f32_e32 v117, 1.0, v117
	v_add_f32_e32 v118, 1.0, v118
	v_add_f32_e32 v119, 1.0, v119
	v_lshl_add_u64 v[114:115], v[114:115], 0, v[182:183]
	v_cvt_pk_bf16_f32 v106, v110, v111
	v_cvt_pk_bf16_f32 v107, v112, v113
	v_rcp_f32_e32 v116, v116
	v_rcp_f32_e32 v117, v117
	v_rcp_f32_e32 v118, v118
	v_rcp_f32_e32 v119, v119
	global_store_dwordx4 v[114:115], v[106:109], off
	v_lshlrev_b32_e32 v110, 16, v156
	v_and_b32_e32 v111, 0xffff0000, v156
	v_lshlrev_b32_e32 v106, 16, v154
	v_and_b32_e32 v107, 0xffff0000, v154
	v_lshlrev_b32_e32 v108, 16, v155
	v_and_b32_e32 v109, 0xffff0000, v155
	v_lshlrev_b32_e32 v112, 16, v157
	v_and_b32_e32 v113, 0xffff0000, v157
	v_sub_f32_e32 v107, v107, v204
	v_sub_f32_e32 v106, v106, v204
	v_sub_f32_e32 v109, v109, v204
	v_sub_f32_e32 v108, v108, v204
	v_sub_f32_e32 v111, v111, v204
	v_sub_f32_e32 v110, v110, v204
	v_sub_f32_e32 v113, v113, v204
	v_sub_f32_e32 v112, v112, v204
	v_pk_mul_f32 v[108:109], v[204:205], v[108:109] op_sel:[1,0]
	v_pk_mul_f32 v[106:107], v[204:205], v[106:107] op_sel:[1,0]
	v_pk_mul_f32 v[112:113], v[204:205], v[112:113] op_sel:[1,0]
	v_pk_mul_f32 v[110:111], v[204:205], v[110:111] op_sel:[1,0]
	v_pk_mul_f32 v[106:107], v[70:71], v[106:107]
	v_pk_mul_f32 v[108:109], v[72:73], v[108:109]
	v_pk_mul_f32 v[110:111], v[66:67], v[110:111]
	v_pk_mul_f32 v[112:113], v[68:69], v[112:113]
	v_pk_mul_f32 v[98:99], v[98:99], v[116:117]
	v_pk_mul_f32 v[100:101], v[100:101], v[118:119]
	v_pk_mul_f32 v[104:105], v[104:105], v[108:109]
	v_pk_mul_f32 v[102:103], v[102:103], v[106:107]
	v_pk_mul_f32 v[106:107], v[100:101], v[112:113]
	v_pk_mul_f32 v[100:101], v[98:99], v[110:111]
	v_mul_f32_e32 v108, 0xbfb8aa3b, v94
	v_mul_f32_e32 v109, 0xbfb8aa3b, v95
	v_mul_f32_e32 v110, 0xbfb8aa3b, v96
	v_mul_f32_e32 v111, 0xbfb8aa3b, v97
	v_exp_f32_e32 v108, v108
	v_exp_f32_e32 v109, v109
	v_exp_f32_e32 v110, v110
	v_exp_f32_e32 v111, v111
	v_add_f32_e32 v108, 1.0, v108
	v_add_f32_e32 v109, 1.0, v109
	v_add_f32_e32 v110, 1.0, v110
	v_add_f32_e32 v111, 1.0, v111
	v_rcp_f32_e32 v108, v108
	v_rcp_f32_e32 v109, v109
	v_rcp_f32_e32 v110, v110
	v_rcp_f32_e32 v111, v111
	v_cvt_pk_bf16_f32 v100, v100, v101
	v_pk_mul_f32 v[94:95], v[94:95], v[108:109]
	v_mul_f32_e32 v108, 0xbfb8aa3b, v90
	v_pk_mul_f32 v[96:97], v[96:97], v[110:111]
	v_mul_f32_e32 v109, 0xbfb8aa3b, v91
	v_mul_f32_e32 v110, 0xbfb8aa3b, v92
	v_mul_f32_e32 v111, 0xbfb8aa3b, v93
	v_exp_f32_e32 v108, v108
	v_exp_f32_e32 v109, v109
	v_exp_f32_e32 v110, v110
	v_exp_f32_e32 v111, v111
	v_add_f32_e32 v108, 1.0, v108
	v_add_f32_e32 v109, 1.0, v109
	v_add_f32_e32 v110, 1.0, v110
	v_add_f32_e32 v111, 1.0, v111
	v_cvt_pk_bf16_f32 v101, v106, v107
	v_rcp_f32_e32 v108, v108
	v_rcp_f32_e32 v109, v109
	v_rcp_f32_e32 v110, v110
	v_rcp_f32_e32 v111, v111
	v_cvt_pk_bf16_f32 v98, v102, v103
	v_cvt_pk_bf16_f32 v99, v104, v105
	global_store_dwordx4 v[114:115], v[98:101], off offset:256
	v_lshlrev_b32_e32 v104, 16, v152
	v_and_b32_e32 v105, 0xffff0000, v152
	v_lshlrev_b32_e32 v100, 16, v150
	v_and_b32_e32 v101, 0xffff0000, v150
	v_lshlrev_b32_e32 v106, 16, v153
	v_and_b32_e32 v107, 0xffff0000, v153
	v_lshlrev_b32_e32 v102, 16, v151
	v_and_b32_e32 v103, 0xffff0000, v151
	v_sub_f32_e32 v101, v101, v200
; __device__ __forceinline__ unsigned cvt_pk_bf16(float lo, float hi) { unsigned r; asm("v_cvt_pk_bf16_f32 %0, %1, %2" : "=v"(r) : "v"(lo), "v"(hi)); return r; }
; __device__ __forceinline__ float bf_lo(unsigned u) { return __uint_as_float(u << 16); }
; __device__ __forceinline__ float bf_hi(unsigned u) { return __uint_as_float(u & 0xffff0000u); }
;     __device__ __forceinline__ void operator()(const AccT& acc, const Unit& u, int wr, int wc, int fr, int fq) const {
;     ...
;         for (int ai = 0; ai < 2; ++ai) {
;             u32x4 yv[4][2];
; #pragma unroll
;             for (int m = 0; m < 4; ++m)
; #pragma unroll
;                 for (int bj = 0; bj < 2; ++bj) yv[m][bj] = *(const u32x4*)(Y + (size_t)(row0 + ai * 128 + m * 16) * 2048 + col0 + bj * 128);
;             __builtin_amdgcn_sched_barrier(0);
; #pragma unroll
;             for (int m = 0; m < 4; ++m) { bf16_t* rowp = A2 + (size_t)(row0 + ai * 128 + m * 16) * 2048 + col0;
;                 const float mu = st[ai][m][0], rs = st[ai][m][1];
; #pragma unroll
;                 for (int bj = 0; bj < 2; ++bj) { const f32x4 v0 = acc[ai][bj][m][0], v1 = acc[ai][bj][m][1]; const u32x4 yw = yv[m][bj];
;                     const f32x4 y0 = (f32x4){bf_lo(yw.x), bf_hi(yw.x), bf_lo(yw.y), bf_hi(yw.y)}, y1 = (f32x4){bf_lo(yw.z), bf_hi(yw.z), bf_lo(yw.w), bf_hi(yw.w)};
;                     const f32x4 n0 = (y0 - mu) * rs * gw[bj][0], n1 = (y1 - mu) * rs * gw[bj][1];
;                     const f32x4 s0 = silu4(v0) * n0, s1 = silu4(v1) * n1;
;                     u32x4 w; w.x = cvt_pk_bf16(s0[0], s0[1]); w.y = cvt_pk_bf16(s0[2], s0[3]); w.z = cvt_pk_bf16(s1[0], s1[1]); w.w = cvt_pk_bf16(s1[2], s1[3]);
;                     *(u32x4*)(rowp + bj * 128) = w; } }
;             __builtin_amdgcn_sched_barrier(0);
	v_sub_f32_e32 v100, v100, v200
	v_sub_f32_e32 v105, v105, v200
	v_sub_f32_e32 v104, v104, v200
	v_sub_f32_e32 v107, v107, v200
	v_sub_f32_e32 v106, v106, v200
	v_sub_f32_e32 v103, v103, v200
	v_sub_f32_e32 v102, v102, v200
	v_pk_mul_f32 v[100:101], v[200:201], v[100:101] op_sel:[1,0]
	v_pk_mul_f32 v[106:107], v[200:201], v[106:107] op_sel:[1,0]
	v_pk_mul_f32 v[104:105], v[200:201], v[104:105] op_sel:[1,0]
	v_pk_mul_f32 v[102:103], v[200:201], v[102:103] op_sel:[1,0]
	v_pk_mul_f32 v[100:101], v[86:87], v[100:101]
	v_pk_mul_f32 v[104:105], v[82:83], v[104:105]
	v_pk_mul_f32 v[106:107], v[84:85], v[106:107]
	v_pk_mul_f32 v[90:91], v[90:91], v[108:109]
	v_pk_mul_f32 v[92:93], v[92:93], v[110:111]
	v_pk_mul_f32 v[102:103], v[88:89], v[102:103]
	v_pk_mul_f32 v[94:95], v[94:95], v[100:101]
	v_pk_mul_f32 v[100:101], v[92:93], v[106:107]
	v_pk_mul_f32 v[92:93], v[90:91], v[104:105]
	v_pk_mul_f32 v[96:97], v[96:97], v[102:103]
	v_cvt_pk_bf16_f32 v92, v92, v93
	v_cvt_pk_bf16_f32 v93, v100, v101
	v_mul_f32_e32 v100, 0xbfb8aa3b, v78
	v_mul_f32_e32 v101, 0xbfb8aa3b, v79
	v_mul_f32_e32 v102, 0xbfb8aa3b, v80
	v_mul_f32_e32 v103, 0xbfb8aa3b, v81
	v_exp_f32_e32 v100, v100
	v_exp_f32_e32 v101, v101
	v_exp_f32_e32 v102, v102
	v_exp_f32_e32 v103, v103
	v_add_f32_e32 v100, 1.0, v100
	v_add_f32_e32 v101, 1.0, v101
	v_add_f32_e32 v102, 1.0, v102
	v_add_f32_e32 v103, 1.0, v103
	v_rcp_f32_e32 v100, v100
	v_rcp_f32_e32 v101, v101
	v_rcp_f32_e32 v102, v102
	v_rcp_f32_e32 v103, v103
	v_lshl_add_u64 v[98:99], s[34:35], 0, v[202:203]
	v_pk_mul_f32 v[78:79], v[78:79], v[100:101]
	v_mul_f32_e32 v100, 0xbfb8aa3b, v74
	v_pk_mul_f32 v[80:81], v[80:81], v[102:103]
	v_mul_f32_e32 v101, 0xbfb8aa3b, v75
	v_mul_f32_e32 v102, 0xbfb8aa3b, v76
	v_mul_f32_e32 v103, 0xbfb8aa3b, v77
	v_exp_f32_e32 v100, v100
	v_exp_f32_e32 v101, v101
	v_exp_f32_e32 v102, v102
	v_exp_f32_e32 v103, v103
	v_add_f32_e32 v100, 1.0, v100
	v_add_f32_e32 v101, 1.0, v101
	v_add_f32_e32 v102, 1.0, v102
	v_add_f32_e32 v103, 1.0, v103
	v_lshl_add_u64 v[98:99], v[98:99], 0, v[182:183]
	v_cvt_pk_bf16_f32 v90, v94, v95
	v_cvt_pk_bf16_f32 v91, v96, v97
	v_rcp_f32_e32 v100, v100
	v_rcp_f32_e32 v101, v101
	v_rcp_f32_e32 v102, v102
	v_rcp_f32_e32 v103, v103
	global_store_dwordx4 v[98:99], v[90:93], off
	v_lshlrev_b32_e32 v94, 16, v148
	v_and_b32_e32 v95, 0xffff0000, v148
	v_lshlrev_b32_e32 v90, 16, v146
	v_and_b32_e32 v91, 0xffff0000, v146
	v_lshlrev_b32_e32 v96, 16, v149
	v_and_b32_e32 v97, 0xffff0000, v149
	v_lshlrev_b32_e32 v92, 16, v147
	v_and_b32_e32 v93, 0xffff0000, v147
	v_sub_f32_e32 v91, v91, v200
	v_sub_f32_e32 v90, v90, v200
	v_sub_f32_e32 v95, v95, v200
	v_sub_f32_e32 v94, v94, v200
	v_sub_f32_e32 v97, v97, v200
	v_sub_f32_e32 v96, v96, v200
	v_sub_f32_e32 v93, v93, v200
	v_sub_f32_e32 v92, v92, v200
	v_pk_mul_f32 v[90:91], v[200:201], v[90:91] op_sel:[1,0]
	v_pk_mul_f32 v[96:97], v[200:201], v[96:97] op_sel:[1,0]
	v_pk_mul_f32 v[94:95], v[200:201], v[94:95] op_sel:[1,0]
	v_pk_mul_f32 v[92:93], v[200:201], v[92:93] op_sel:[1,0]
	v_pk_mul_f32 v[90:91], v[70:71], v[90:91]
	v_pk_mul_f32 v[94:95], v[66:67], v[94:95]
	v_pk_mul_f32 v[96:97], v[68:69], v[96:97]
	v_pk_mul_f32 v[74:75], v[74:75], v[100:101]
	v_pk_mul_f32 v[76:77], v[76:77], v[102:103]
	v_pk_mul_f32 v[92:93], v[72:73], v[92:93]
	v_pk_mul_f32 v[78:79], v[78:79], v[90:91]
	v_pk_mul_f32 v[90:91], v[76:77], v[96:97]
	v_pk_mul_f32 v[76:77], v[74:75], v[94:95]
	v_pk_mul_f32 v[80:81], v[80:81], v[92:93]
	v_cvt_pk_bf16_f32 v74, v78, v79
	v_cvt_pk_bf16_f32 v76, v76, v77
	v_cvt_pk_bf16_f32 v77, v90, v91
	s_nop 0
	v_cvt_pk_bf16_f32 v75, v80, v81
	global_store_dwordx4 v[98:99], v[74:77], off offset:256
	v_lshlrev_b64 v[118:119], 12, v[190:191]
	s_nop 0
	v_lshl_add_u64 v[74:75], v[198:199], 0, v[118:119]
	v_lshlrev_b64 v[120:121], 12, v[192:193]
	global_load_dwordx4 v[106:109], v[74:75], off
	global_load_dwordx4 v[110:113], v[74:75], off offset:256
	v_lshl_add_u64 v[74:75], v[198:199], 0, v[120:121]
	v_lshlrev_b64 v[104:105], 12, v[194:195]
	global_load_dwordx4 v[114:117], v[74:75], off
	global_load_dwordx4 v[98:101], v[74:75], off offset:256
	v_lshl_add_u64 v[74:75], v[198:199], 0, v[104:105]
	v_lshlrev_b64 v[102:103], 12, v[196:197]
	global_load_dwordx4 v[94:97], v[74:75], off
	global_load_dwordx4 v[90:93], v[74:75], off offset:256
	v_lshl_add_u64 v[74:75], v[198:199], 0, v[102:103]
	global_load_dwordx4 v[78:81], v[74:75], off
	s_nop 0
	global_load_dwordx4 v[74:77], v[74:75], off offset:256
	s_waitcnt vmcnt(0)
; __device__ __forceinline__ unsigned cvt_pk_bf16(float lo, float hi) { unsigned r; asm("v_cvt_pk_bf16_f32 %0, %1, %2" : "=v"(r) : "v"(lo), "v"(hi)); return r; }
; __device__ __forceinline__ float bf_lo(unsigned u) { return __uint_as_float(u << 16); }
; __device__ __forceinline__ float bf_hi(unsigned u) { return __uint_as_float(u & 0xffff0000u); }
; __device__ __forceinline__ f32x4 silu4(f32x4 v) {
;     f32x4 e, r;
; #pragma unroll
;     for (int j = 0; j < 4; ++j) e[j] = __builtin_amdgcn_exp2f(v[j] * -1.4426950408889634f);
; #pragma unroll
;     for (int j = 0; j < 4; ++j) r[j] = __builtin_amdgcn_rcpf(1.0f + e[j]);
;     return v * r;
; }
;     __device__ __forceinline__ void operator()(const AccT& acc, const Unit& u, int wr, int wc, int fr, int fq) const {
;     ...
;                 for (int bj = 0; bj < 2; ++bj) yv[m][bj] = *(const u32x4*)(Y + (size_t)(row0 + ai * 128 + m * 16) * 2048 + col0 + bj * 128);
;             __builtin_amdgcn_sched_barrier(0);
; #pragma unroll
;             for (int m = 0; m < 4; ++m) { bf16_t* rowp = A2 + (size_t)(row0 + ai * 128 + m * 16) * 2048 + col0;
;                 const float mu = st[ai][m][0], rs = st[ai][m][1];
; #pragma unroll
;                 for (int bj = 0; bj < 2; ++bj) { const f32x4 v0 = acc[ai][bj][m][0], v1 = acc[ai][bj][m][1]; const u32x4 yw = yv[m][bj];
;                     const f32x4 y0 = (f32x4){bf_lo(yw.x), bf_hi(yw.x), bf_lo(yw.y), bf_hi(yw.y)}, y1 = (f32x4){bf_lo(yw.z), bf_hi(yw.z), bf_lo(yw.w), bf_hi(yw.w)};
;                     const f32x4 n0 = (y0 - mu) * rs * gw[bj][0], n1 = (y1 - mu) * rs * gw[bj][1];
;                     const f32x4 s0 = silu4(v0) * n0, s1 = silu4(v1) * n1;
;                     u32x4 w; w.x = cvt_pk_bf16(s0[0], s0[1]); w.y = cvt_pk_bf16(s0[2], s0[3]); w.z = cvt_pk_bf16(s1[0], s1[1]); w.w = cvt_pk_bf16(s1[2], s1[3]);
;                     *(u32x4*)(rowp + bj * 128) = w; } }
	v_lshlrev_b32_e32 v122, 16, v106
	v_and_b32_e32 v106, 0xffff0000, v106
	v_lshlrev_b32_e32 v123, 16, v107
	v_and_b32_e32 v124, 0xffff0000, v107
	v_lshlrev_b32_e32 v125, 16, v108
	v_and_b32_e32 v126, 0xffff0000, v108
	v_lshlrev_b32_e32 v127, 16, v109
	v_and_b32_e32 v128, 0xffff0000, v109
	v_sub_f32_e32 v107, v106, v188
	v_sub_f32_e32 v106, v122, v188
	v_sub_f32_e32 v109, v124, v188
	v_sub_f32_e32 v108, v123, v188
	v_sub_f32_e32 v123, v126, v188
	v_sub_f32_e32 v122, v125, v188
	v_sub_f32_e32 v125, v128, v188
	v_sub_f32_e32 v124, v127, v188
	v_mul_f32_e32 v126, 0xbfb8aa3b, v62
	v_mul_f32_e32 v127, 0xbfb8aa3b, v63
	v_mul_f32_e32 v128, 0xbfb8aa3b, v64
	v_mul_f32_e32 v129, 0xbfb8aa3b, v65
	v_exp_f32_e32 v126, v126
	v_exp_f32_e32 v127, v127
	v_exp_f32_e32 v128, v128
	v_exp_f32_e32 v129, v129
	v_add_f32_e32 v126, 1.0, v126
	v_add_f32_e32 v127, 1.0, v127
	v_add_f32_e32 v128, 1.0, v128
	v_add_f32_e32 v129, 1.0, v129
	v_rcp_f32_e32 v126, v126
	v_rcp_f32_e32 v127, v127
	v_rcp_f32_e32 v128, v128
	v_rcp_f32_e32 v129, v129
	v_pk_mul_f32 v[106:107], v[188:189], v[106:107] op_sel:[1,0]
	v_pk_mul_f32 v[62:63], v[62:63], v[126:127]
	v_mul_f32_e32 v126, 0xbfb8aa3b, v58
	v_pk_mul_f32 v[64:65], v[64:65], v[128:129]
	v_mul_f32_e32 v127, 0xbfb8aa3b, v59
	v_mul_f32_e32 v128, 0xbfb8aa3b, v60
	v_mul_f32_e32 v129, 0xbfb8aa3b, v61
	v_exp_f32_e32 v126, v126
	v_exp_f32_e32 v127, v127
	v_exp_f32_e32 v128, v128
	v_exp_f32_e32 v129, v129
	v_add_f32_e32 v126, 1.0, v126
	v_add_f32_e32 v127, 1.0, v127
	v_add_f32_e32 v128, 1.0, v128
	v_add_f32_e32 v129, 1.0, v129
	v_rcp_f32_e32 v126, v126
	v_rcp_f32_e32 v127, v127
	v_rcp_f32_e32 v128, v128
	v_rcp_f32_e32 v129, v129
	v_pk_mul_f32 v[124:125], v[188:189], v[124:125] op_sel:[1,0]
	v_pk_mul_f32 v[122:123], v[188:189], v[122:123] op_sel:[1,0]
	v_pk_mul_f32 v[108:109], v[188:189], v[108:109] op_sel:[1,0]
	v_pk_mul_f32 v[106:107], v[86:87], v[106:107]
	v_pk_mul_f32 v[122:123], v[82:83], v[122:123]
	v_pk_mul_f32 v[124:125], v[84:85], v[124:125]
	v_pk_mul_f32 v[58:59], v[58:59], v[126:127]
	v_pk_mul_f32 v[60:61], v[60:61], v[128:129]
	v_pk_mul_f32 v[108:109], v[88:89], v[108:109]
	v_pk_mul_f32 v[62:63], v[62:63], v[106:107]
	v_pk_mul_f32 v[106:107], v[60:61], v[124:125]
	v_pk_mul_f32 v[60:61], v[58:59], v[122:123]
	v_pk_mul_f32 v[64:65], v[64:65], v[108:109]
	v_cvt_pk_bf16_f32 v60, v60, v61
	v_cvt_pk_bf16_f32 v61, v106, v107
	v_mul_f32_e32 v106, 0xbfb8aa3b, v54
	v_mul_f32_e32 v107, 0xbfb8aa3b, v55
	v_mul_f32_e32 v108, 0xbfb8aa3b, v56
	v_mul_f32_e32 v109, 0xbfb8aa3b, v57
	v_exp_f32_e32 v106, v106
	v_exp_f32_e32 v107, v107
	v_exp_f32_e32 v108, v108
	v_exp_f32_e32 v109, v109
	v_add_f32_e32 v106, 1.0, v106
	v_add_f32_e32 v107, 1.0, v107
	v_add_f32_e32 v108, 1.0, v108
	v_add_f32_e32 v109, 1.0, v109
	v_rcp_f32_e32 v106, v106
	v_rcp_f32_e32 v107, v107
	v_rcp_f32_e32 v108, v108
	v_rcp_f32_e32 v109, v109
	v_lshl_add_u64 v[118:119], s[34:35], 0, v[118:119]
	v_pk_mul_f32 v[54:55], v[54:55], v[106:107]
	v_mul_f32_e32 v106, 0xbfb8aa3b, v50
	v_pk_mul_f32 v[56:57], v[56:57], v[108:109]
	v_mul_f32_e32 v107, 0xbfb8aa3b, v51
	v_mul_f32_e32 v108, 0xbfb8aa3b, v52
	v_mul_f32_e32 v109, 0xbfb8aa3b, v53
	v_exp_f32_e32 v106, v106
	v_exp_f32_e32 v107, v107
	v_exp_f32_e32 v108, v108
	v_exp_f32_e32 v109, v109
	v_add_f32_e32 v106, 1.0, v106
	v_add_f32_e32 v107, 1.0, v107
	v_add_f32_e32 v108, 1.0, v108
	v_add_f32_e32 v109, 1.0, v109
	v_lshl_add_u64 v[118:119], v[118:119], 0, v[182:183]
	v_cvt_pk_bf16_f32 v58, v62, v63
	v_cvt_pk_bf16_f32 v59, v64, v65
	v_rcp_f32_e32 v106, v106
	v_rcp_f32_e32 v107, v107
	v_rcp_f32_e32 v108, v108
	v_rcp_f32_e32 v109, v109
	global_store_dwordx4 v[118:119], v[58:61], off
	v_lshlrev_b32_e32 v62, 16, v112
	v_and_b32_e32 v63, 0xffff0000, v112
	v_lshlrev_b32_e32 v58, 16, v110
	v_and_b32_e32 v59, 0xffff0000, v110
	v_lshlrev_b32_e32 v60, 16, v111
	v_and_b32_e32 v61, 0xffff0000, v111
	v_lshlrev_b32_e32 v64, 16, v113
	v_and_b32_e32 v65, 0xffff0000, v113
	v_sub_f32_e32 v59, v59, v188
	v_sub_f32_e32 v58, v58, v188
	v_sub_f32_e32 v61, v61, v188
	v_sub_f32_e32 v60, v60, v188
	v_sub_f32_e32 v63, v63, v188
	v_sub_f32_e32 v62, v62, v188
	v_sub_f32_e32 v65, v65, v188
	v_sub_f32_e32 v64, v64, v188
	v_pk_mul_f32 v[60:61], v[188:189], v[60:61] op_sel:[1,0]
	v_pk_mul_f32 v[58:59], v[188:189], v[58:59] op_sel:[1,0]
	v_pk_mul_f32 v[64:65], v[188:189], v[64:65] op_sel:[1,0]
	v_pk_mul_f32 v[62:63], v[188:189], v[62:63] op_sel:[1,0]
	v_pk_mul_f32 v[58:59], v[70:71], v[58:59]
	v_pk_mul_f32 v[60:61], v[72:73], v[60:61]
	v_pk_mul_f32 v[62:63], v[66:67], v[62:63]
	v_pk_mul_f32 v[64:65], v[68:69], v[64:65]
	v_pk_mul_f32 v[50:51], v[50:51], v[106:107]
	v_pk_mul_f32 v[52:53], v[52:53], v[108:109]
	v_pk_mul_f32 v[56:57], v[56:57], v[60:61]
	v_pk_mul_f32 v[54:55], v[54:55], v[58:59]
	v_pk_mul_f32 v[58:59], v[52:53], v[64:65]
	v_pk_mul_f32 v[52:53], v[50:51], v[62:63]
	v_mul_f32_e32 v60, 0xbfb8aa3b, v46
	v_mul_f32_e32 v61, 0xbfb8aa3b, v47
	v_mul_f32_e32 v62, 0xbfb8aa3b, v48
	v_mul_f32_e32 v63, 0xbfb8aa3b, v49
	v_exp_f32_e32 v60, v60
	v_exp_f32_e32 v61, v61
	v_exp_f32_e32 v62, v62
	v_exp_f32_e32 v63, v63
	v_add_f32_e32 v60, 1.0, v60
	v_add_f32_e32 v61, 1.0, v61
	v_add_f32_e32 v62, 1.0, v62
	v_add_f32_e32 v63, 1.0, v63
	v_rcp_f32_e32 v60, v60
	v_rcp_f32_e32 v61, v61
	v_rcp_f32_e32 v62, v62
	v_rcp_f32_e32 v63, v63
	v_cvt_pk_bf16_f32 v52, v52, v53
	v_pk_mul_f32 v[46:47], v[46:47], v[60:61]
	v_mul_f32_e32 v60, 0xbfb8aa3b, v42
	v_pk_mul_f32 v[48:49], v[48:49], v[62:63]
	v_mul_f32_e32 v61, 0xbfb8aa3b, v43
	v_mul_f32_e32 v62, 0xbfb8aa3b, v44
	v_mul_f32_e32 v63, 0xbfb8aa3b, v45
	v_exp_f32_e32 v60, v60
	v_exp_f32_e32 v61, v61
	v_exp_f32_e32 v62, v62
	v_exp_f32_e32 v63, v63
; __device__ __forceinline__ unsigned cvt_pk_bf16(float lo, float hi) { unsigned r; asm("v_cvt_pk_bf16_f32 %0, %1, %2" : "=v"(r) : "v"(lo), "v"(hi)); return r; }
; __device__ __forceinline__ float bf_lo(unsigned u) { return __uint_as_float(u << 16); }
; __device__ __forceinline__ float bf_hi(unsigned u) { return __uint_as_float(u & 0xffff0000u); }
; __device__ __forceinline__ f32x4 silu4(f32x4 v) {
;     f32x4 e, r;
; #pragma unroll
;     for (int j = 0; j < 4; ++j) e[j] = __builtin_amdgcn_exp2f(v[j] * -1.4426950408889634f);
; #pragma unroll
;     for (int j = 0; j < 4; ++j) r[j] = __builtin_amdgcn_rcpf(1.0f + e[j]);
;     return v * r;
; }
;     __device__ __forceinline__ void operator()(const AccT& acc, const Unit& u, int wr, int wc, int fr, int fq) const {
;     ...
;                 for (int bj = 0; bj < 2; ++bj) yv[m][bj] = *(const u32x4*)(Y + (size_t)(row0 + ai * 128 + m * 16) * 2048 + col0 + bj * 128);
;             __builtin_amdgcn_sched_barrier(0);
; #pragma unroll
;             for (int m = 0; m < 4; ++m) { bf16_t* rowp = A2 + (size_t)(row0 + ai * 128 + m * 16) * 2048 + col0;
;                 const float mu = st[ai][m][0], rs = st[ai][m][1];
; #pragma unroll
;                 for (int bj = 0; bj < 2; ++bj) { const f32x4 v0 = acc[ai][bj][m][0], v1 = acc[ai][bj][m][1]; const u32x4 yw = yv[m][bj];
;                     const f32x4 y0 = (f32x4){bf_lo(yw.x), bf_hi(yw.x), bf_lo(yw.y), bf_hi(yw.y)}, y1 = (f32x4){bf_lo(yw.z), bf_hi(yw.z), bf_lo(yw.w), bf_hi(yw.w)};
;                     const f32x4 n0 = (y0 - mu) * rs * gw[bj][0], n1 = (y1 - mu) * rs * gw[bj][1];
;                     const f32x4 s0 = silu4(v0) * n0, s1 = silu4(v1) * n1;
;                     u32x4 w; w.x = cvt_pk_bf16(s0[0], s0[1]); w.y = cvt_pk_bf16(s0[2], s0[3]); w.z = cvt_pk_bf16(s1[0], s1[1]); w.w = cvt_pk_bf16(s1[2], s1[3]);
;                     *(u32x4*)(rowp + bj * 128) = w; } }
	v_add_f32_e32 v60, 1.0, v60
	v_add_f32_e32 v61, 1.0, v61
	v_add_f32_e32 v62, 1.0, v62
	v_add_f32_e32 v63, 1.0, v63
	v_cvt_pk_bf16_f32 v53, v58, v59
	v_rcp_f32_e32 v60, v60
	v_rcp_f32_e32 v61, v61
	v_rcp_f32_e32 v62, v62
	v_rcp_f32_e32 v63, v63
	v_cvt_pk_bf16_f32 v50, v54, v55
	v_cvt_pk_bf16_f32 v51, v56, v57
	global_store_dwordx4 v[118:119], v[50:53], off offset:256
	v_lshlrev_b32_e32 v56, 16, v116
	v_and_b32_e32 v57, 0xffff0000, v116
	v_lshlrev_b32_e32 v52, 16, v114
	v_and_b32_e32 v53, 0xffff0000, v114
	v_lshlrev_b32_e32 v58, 16, v117
	v_and_b32_e32 v59, 0xffff0000, v117
	v_lshlrev_b32_e32 v54, 16, v115
	v_and_b32_e32 v55, 0xffff0000, v115
	v_sub_f32_e32 v53, v53, v186
	v_sub_f32_e32 v52, v52, v186
	v_sub_f32_e32 v57, v57, v186
	v_sub_f32_e32 v56, v56, v186
	v_sub_f32_e32 v59, v59, v186
	v_sub_f32_e32 v58, v58, v186
	v_sub_f32_e32 v55, v55, v186
	v_sub_f32_e32 v54, v54, v186
	v_pk_mul_f32 v[52:53], v[186:187], v[52:53] op_sel:[1,0]
	v_pk_mul_f32 v[58:59], v[186:187], v[58:59] op_sel:[1,0]
	v_pk_mul_f32 v[56:57], v[186:187], v[56:57] op_sel:[1,0]
	v_pk_mul_f32 v[54:55], v[186:187], v[54:55] op_sel:[1,0]
	v_pk_mul_f32 v[52:53], v[86:87], v[52:53]
	v_pk_mul_f32 v[56:57], v[82:83], v[56:57]
	v_pk_mul_f32 v[58:59], v[84:85], v[58:59]
	v_pk_mul_f32 v[42:43], v[42:43], v[60:61]
	v_pk_mul_f32 v[44:45], v[44:45], v[62:63]
	v_pk_mul_f32 v[54:55], v[88:89], v[54:55]
	v_pk_mul_f32 v[46:47], v[46:47], v[52:53]
	v_pk_mul_f32 v[52:53], v[44:45], v[58:59]
	v_pk_mul_f32 v[44:45], v[42:43], v[56:57]
	v_pk_mul_f32 v[48:49], v[48:49], v[54:55]
	v_cvt_pk_bf16_f32 v44, v44, v45
	v_cvt_pk_bf16_f32 v45, v52, v53
	v_mul_f32_e32 v52, 0xbfb8aa3b, v38
	v_mul_f32_e32 v53, 0xbfb8aa3b, v39
	v_mul_f32_e32 v54, 0xbfb8aa3b, v40
	v_mul_f32_e32 v55, 0xbfb8aa3b, v41
	v_exp_f32_e32 v52, v52
	v_exp_f32_e32 v53, v53
	v_exp_f32_e32 v54, v54
	v_exp_f32_e32 v55, v55
	v_add_f32_e32 v52, 1.0, v52
	v_add_f32_e32 v53, 1.0, v53
	v_add_f32_e32 v54, 1.0, v54
	v_add_f32_e32 v55, 1.0, v55
	v_rcp_f32_e32 v52, v52
	v_rcp_f32_e32 v53, v53
	v_rcp_f32_e32 v54, v54
	v_rcp_f32_e32 v55, v55
	v_lshl_add_u64 v[50:51], s[34:35], 0, v[120:121]
	v_pk_mul_f32 v[38:39], v[38:39], v[52:53]
	v_mul_f32_e32 v52, 0xbfb8aa3b, v34
	v_pk_mul_f32 v[40:41], v[40:41], v[54:55]
	v_mul_f32_e32 v53, 0xbfb8aa3b, v35
	v_mul_f32_e32 v54, 0xbfb8aa3b, v36
	v_mul_f32_e32 v55, 0xbfb8aa3b, v37
	v_exp_f32_e32 v52, v52
	v_exp_f32_e32 v53, v53
	v_exp_f32_e32 v54, v54
	v_exp_f32_e32 v55, v55
	v_add_f32_e32 v52, 1.0, v52
	v_add_f32_e32 v53, 1.0, v53
	v_add_f32_e32 v54, 1.0, v54
	v_add_f32_e32 v55, 1.0, v55
	v_lshl_add_u64 v[50:51], v[50:51], 0, v[182:183]
	v_cvt_pk_bf16_f32 v42, v46, v47
	v_cvt_pk_bf16_f32 v43, v48, v49
	v_rcp_f32_e32 v52, v52
	v_rcp_f32_e32 v53, v53
	v_rcp_f32_e32 v54, v54
	v_rcp_f32_e32 v55, v55
	global_store_dwordx4 v[50:51], v[42:45], off
	v_lshlrev_b32_e32 v46, 16, v100
	v_and_b32_e32 v47, 0xffff0000, v100
	v_lshlrev_b32_e32 v42, 16, v98
	v_and_b32_e32 v43, 0xffff0000, v98
	v_lshlrev_b32_e32 v44, 16, v99
	v_and_b32_e32 v45, 0xffff0000, v99
	v_lshlrev_b32_e32 v48, 16, v101
	v_and_b32_e32 v49, 0xffff0000, v101
	v_sub_f32_e32 v43, v43, v186
	v_sub_f32_e32 v42, v42, v186
	v_sub_f32_e32 v45, v45, v186
	v_sub_f32_e32 v44, v44, v186
	v_sub_f32_e32 v47, v47, v186
	v_sub_f32_e32 v46, v46, v186
	v_sub_f32_e32 v49, v49, v186
	v_sub_f32_e32 v48, v48, v186
	v_pk_mul_f32 v[44:45], v[186:187], v[44:45] op_sel:[1,0]
	v_pk_mul_f32 v[42:43], v[186:187], v[42:43] op_sel:[1,0]
	v_pk_mul_f32 v[48:49], v[186:187], v[48:49] op_sel:[1,0]
	v_pk_mul_f32 v[46:47], v[186:187], v[46:47] op_sel:[1,0]
	v_pk_mul_f32 v[42:43], v[70:71], v[42:43]
	v_pk_mul_f32 v[44:45], v[72:73], v[44:45]
	v_pk_mul_f32 v[46:47], v[66:67], v[46:47]
	v_pk_mul_f32 v[48:49], v[68:69], v[48:49]
	v_pk_mul_f32 v[34:35], v[34:35], v[52:53]
	v_pk_mul_f32 v[36:37], v[36:37], v[54:55]
	v_pk_mul_f32 v[40:41], v[40:41], v[44:45]
	v_pk_mul_f32 v[38:39], v[38:39], v[42:43]
	v_pk_mul_f32 v[42:43], v[36:37], v[48:49]
	v_pk_mul_f32 v[36:37], v[34:35], v[46:47]
	v_mul_f32_e32 v44, 0xbfb8aa3b, v30
	v_mul_f32_e32 v45, 0xbfb8aa3b, v31
	v_mul_f32_e32 v46, 0xbfb8aa3b, v32
	v_mul_f32_e32 v47, 0xbfb8aa3b, v33
	v_exp_f32_e32 v44, v44
	v_exp_f32_e32 v45, v45
	v_exp_f32_e32 v46, v46
	v_exp_f32_e32 v47, v47
	v_add_f32_e32 v44, 1.0, v44
	v_add_f32_e32 v45, 1.0, v45
	v_add_f32_e32 v46, 1.0, v46
	v_add_f32_e32 v47, 1.0, v47
	v_rcp_f32_e32 v44, v44
	v_rcp_f32_e32 v45, v45
	v_rcp_f32_e32 v46, v46
	v_rcp_f32_e32 v47, v47
	v_cvt_pk_bf16_f32 v36, v36, v37
	v_pk_mul_f32 v[30:31], v[30:31], v[44:45]
	v_mul_f32_e32 v44, 0xbfb8aa3b, v26
	v_pk_mul_f32 v[32:33], v[32:33], v[46:47]
	v_mul_f32_e32 v45, 0xbfb8aa3b, v27
	v_mul_f32_e32 v46, 0xbfb8aa3b, v28
	v_mul_f32_e32 v47, 0xbfb8aa3b, v29
	v_exp_f32_e32 v44, v44
	v_exp_f32_e32 v45, v45
	v_exp_f32_e32 v46, v46
	v_exp_f32_e32 v47, v47
	v_add_f32_e32 v44, 1.0, v44
	v_add_f32_e32 v45, 1.0, v45
	v_add_f32_e32 v46, 1.0, v46
	v_add_f32_e32 v47, 1.0, v47
	v_cvt_pk_bf16_f32 v37, v42, v43
	v_rcp_f32_e32 v44, v44
	v_rcp_f32_e32 v45, v45
	v_rcp_f32_e32 v46, v46
	v_rcp_f32_e32 v47, v47
	v_cvt_pk_bf16_f32 v34, v38, v39
	v_cvt_pk_bf16_f32 v35, v40, v41
	global_store_dwordx4 v[50:51], v[34:37], off offset:256
	v_lshlrev_b32_e32 v40, 16, v96
	v_and_b32_e32 v41, 0xffff0000, v96
	v_lshlrev_b32_e32 v36, 16, v94
	v_and_b32_e32 v37, 0xffff0000, v94
	v_lshlrev_b32_e32 v42, 16, v97
	v_and_b32_e32 v43, 0xffff0000, v97
	v_lshlrev_b32_e32 v38, 16, v95
	v_and_b32_e32 v39, 0xffff0000, v95
	v_sub_f32_e32 v37, v37, v184
	v_sub_f32_e32 v36, v36, v184
	v_sub_f32_e32 v41, v41, v184
	v_sub_f32_e32 v40, v40, v184
	v_sub_f32_e32 v43, v43, v184
	v_sub_f32_e32 v42, v42, v184
; __device__ __forceinline__ unsigned cvt_pk_bf16(float lo, float hi) { unsigned r; asm("v_cvt_pk_bf16_f32 %0, %1, %2" : "=v"(r) : "v"(lo), "v"(hi)); return r; }
; __device__ __forceinline__ float bf_lo(unsigned u) { return __uint_as_float(u << 16); }
; __device__ __forceinline__ float bf_hi(unsigned u) { return __uint_as_float(u & 0xffff0000u); }
; __device__ __forceinline__ f32x4 silu4(f32x4 v) {
;     f32x4 e, r;
; #pragma unroll
;     for (int j = 0; j < 4; ++j) e[j] = __builtin_amdgcn_exp2f(v[j] * -1.4426950408889634f);
; #pragma unroll
;     for (int j = 0; j < 4; ++j) r[j] = __builtin_amdgcn_rcpf(1.0f + e[j]);
;     return v * r;
; }
;     __device__ __forceinline__ void operator()(const AccT& acc, const Unit& u, int wr, int wc, int fr, int fq) const {
;     ...
;                 for (int bj = 0; bj < 2; ++bj) yv[m][bj] = *(const u32x4*)(Y + (size_t)(row0 + ai * 128 + m * 16) * 2048 + col0 + bj * 128);
;             __builtin_amdgcn_sched_barrier(0);
; #pragma unroll
;             for (int m = 0; m < 4; ++m) { bf16_t* rowp = A2 + (size_t)(row0 + ai * 128 + m * 16) * 2048 + col0;
;                 const float mu = st[ai][m][0], rs = st[ai][m][1];
; #pragma unroll
;                 for (int bj = 0; bj < 2; ++bj) { const f32x4 v0 = acc[ai][bj][m][0], v1 = acc[ai][bj][m][1]; const u32x4 yw = yv[m][bj];
;                     const f32x4 y0 = (f32x4){bf_lo(yw.x), bf_hi(yw.x), bf_lo(yw.y), bf_hi(yw.y)}, y1 = (f32x4){bf_lo(yw.z), bf_hi(yw.z), bf_lo(yw.w), bf_hi(yw.w)};
;                     const f32x4 n0 = (y0 - mu) * rs * gw[bj][0], n1 = (y1 - mu) * rs * gw[bj][1];
;                     const f32x4 s0 = silu4(v0) * n0, s1 = silu4(v1) * n1;
;                     u32x4 w; w.x = cvt_pk_bf16(s0[0], s0[1]); w.y = cvt_pk_bf16(s0[2], s0[3]); w.z = cvt_pk_bf16(s1[0], s1[1]); w.w = cvt_pk_bf16(s1[2], s1[3]);
;                     *(u32x4*)(rowp + bj * 128) = w; } }
	v_sub_f32_e32 v39, v39, v184
	v_sub_f32_e32 v38, v38, v184
	v_pk_mul_f32 v[36:37], v[184:185], v[36:37] op_sel:[1,0]
	v_pk_mul_f32 v[42:43], v[184:185], v[42:43] op_sel:[1,0]
	v_pk_mul_f32 v[40:41], v[184:185], v[40:41] op_sel:[1,0]
	v_pk_mul_f32 v[38:39], v[184:185], v[38:39] op_sel:[1,0]
	v_pk_mul_f32 v[36:37], v[86:87], v[36:37]
	v_pk_mul_f32 v[40:41], v[82:83], v[40:41]
	v_pk_mul_f32 v[42:43], v[84:85], v[42:43]
	v_pk_mul_f32 v[26:27], v[26:27], v[44:45]
	v_pk_mul_f32 v[28:29], v[28:29], v[46:47]
	v_pk_mul_f32 v[38:39], v[88:89], v[38:39]
	v_pk_mul_f32 v[30:31], v[30:31], v[36:37]
	v_pk_mul_f32 v[36:37], v[28:29], v[42:43]
	v_pk_mul_f32 v[28:29], v[26:27], v[40:41]
	v_pk_mul_f32 v[32:33], v[32:33], v[38:39]
	v_cvt_pk_bf16_f32 v28, v28, v29
	v_cvt_pk_bf16_f32 v29, v36, v37
	v_mul_f32_e32 v36, 0xbfb8aa3b, v22
	v_mul_f32_e32 v37, 0xbfb8aa3b, v23
	v_mul_f32_e32 v38, 0xbfb8aa3b, v24
	v_mul_f32_e32 v39, 0xbfb8aa3b, v25
	v_exp_f32_e32 v36, v36
	v_exp_f32_e32 v37, v37
	v_exp_f32_e32 v38, v38
	v_exp_f32_e32 v39, v39
	v_add_f32_e32 v36, 1.0, v36
	v_add_f32_e32 v37, 1.0, v37
	v_add_f32_e32 v38, 1.0, v38
	v_add_f32_e32 v39, 1.0, v39
	v_rcp_f32_e32 v36, v36
	v_rcp_f32_e32 v37, v37
	v_rcp_f32_e32 v38, v38
	v_rcp_f32_e32 v39, v39
	v_lshl_add_u64 v[34:35], s[34:35], 0, v[104:105]
	v_pk_mul_f32 v[22:23], v[22:23], v[36:37]
	v_mul_f32_e32 v36, 0xbfb8aa3b, v18
	v_pk_mul_f32 v[24:25], v[24:25], v[38:39]
	v_mul_f32_e32 v37, 0xbfb8aa3b, v19
	v_mul_f32_e32 v38, 0xbfb8aa3b, v20
	v_mul_f32_e32 v39, 0xbfb8aa3b, v21
	v_exp_f32_e32 v36, v36
	v_exp_f32_e32 v37, v37
	v_exp_f32_e32 v38, v38
	v_exp_f32_e32 v39, v39
	v_add_f32_e32 v36, 1.0, v36
	v_add_f32_e32 v37, 1.0, v37
	v_add_f32_e32 v38, 1.0, v38
	v_add_f32_e32 v39, 1.0, v39
	v_lshl_add_u64 v[34:35], v[34:35], 0, v[182:183]
	v_cvt_pk_bf16_f32 v26, v30, v31
	v_cvt_pk_bf16_f32 v27, v32, v33
	v_rcp_f32_e32 v36, v36
	v_rcp_f32_e32 v37, v37
	v_rcp_f32_e32 v38, v38
	v_rcp_f32_e32 v39, v39
	global_store_dwordx4 v[34:35], v[26:29], off
	v_lshlrev_b32_e32 v30, 16, v92
	v_and_b32_e32 v31, 0xffff0000, v92
	v_lshlrev_b32_e32 v26, 16, v90
	v_and_b32_e32 v27, 0xffff0000, v90
	v_lshlrev_b32_e32 v28, 16, v91
	v_and_b32_e32 v29, 0xffff0000, v91
	v_lshlrev_b32_e32 v32, 16, v93
	v_and_b32_e32 v33, 0xffff0000, v93
	v_sub_f32_e32 v27, v27, v184
	v_sub_f32_e32 v26, v26, v184
	v_sub_f32_e32 v29, v29, v184
	v_sub_f32_e32 v28, v28, v184
	v_sub_f32_e32 v31, v31, v184
	v_sub_f32_e32 v30, v30, v184
	v_sub_f32_e32 v33, v33, v184
	v_sub_f32_e32 v32, v32, v184
	v_pk_mul_f32 v[28:29], v[184:185], v[28:29] op_sel:[1,0]
	v_pk_mul_f32 v[26:27], v[184:185], v[26:27] op_sel:[1,0]
	v_pk_mul_f32 v[32:33], v[184:185], v[32:33] op_sel:[1,0]
	v_pk_mul_f32 v[30:31], v[184:185], v[30:31] op_sel:[1,0]
	v_pk_mul_f32 v[26:27], v[70:71], v[26:27]
	v_pk_mul_f32 v[28:29], v[72:73], v[28:29]
	v_pk_mul_f32 v[30:31], v[66:67], v[30:31]
	v_pk_mul_f32 v[32:33], v[68:69], v[32:33]
	v_pk_mul_f32 v[18:19], v[18:19], v[36:37]
	v_pk_mul_f32 v[20:21], v[20:21], v[38:39]
	v_pk_mul_f32 v[24:25], v[24:25], v[28:29]
	v_pk_mul_f32 v[22:23], v[22:23], v[26:27]
	v_pk_mul_f32 v[26:27], v[20:21], v[32:33]
	v_pk_mul_f32 v[20:21], v[18:19], v[30:31]
	v_mul_f32_e32 v28, 0xbfb8aa3b, v14
	v_mul_f32_e32 v29, 0xbfb8aa3b, v15
	v_mul_f32_e32 v30, 0xbfb8aa3b, v16
	v_mul_f32_e32 v31, 0xbfb8aa3b, v17
	v_exp_f32_e32 v28, v28
	v_exp_f32_e32 v29, v29
	v_exp_f32_e32 v30, v30
	v_exp_f32_e32 v31, v31
	v_add_f32_e32 v28, 1.0, v28
	v_add_f32_e32 v29, 1.0, v29
	v_add_f32_e32 v30, 1.0, v30
	v_add_f32_e32 v31, 1.0, v31
	v_rcp_f32_e32 v28, v28
	v_rcp_f32_e32 v29, v29
	v_rcp_f32_e32 v30, v30
	v_rcp_f32_e32 v31, v31
	v_cvt_pk_bf16_f32 v20, v20, v21
	v_pk_mul_f32 v[14:15], v[14:15], v[28:29]
	v_mul_f32_e32 v28, 0xbfb8aa3b, v10
	v_pk_mul_f32 v[16:17], v[16:17], v[30:31]
	v_mul_f32_e32 v29, 0xbfb8aa3b, v11
	v_mul_f32_e32 v30, 0xbfb8aa3b, v12
	v_mul_f32_e32 v31, 0xbfb8aa3b, v13
	v_exp_f32_e32 v28, v28
	v_exp_f32_e32 v29, v29
	v_exp_f32_e32 v30, v30
	v_exp_f32_e32 v31, v31
	v_add_f32_e32 v28, 1.0, v28
	v_add_f32_e32 v29, 1.0, v29
	v_add_f32_e32 v30, 1.0, v30
	v_add_f32_e32 v31, 1.0, v31
	v_cvt_pk_bf16_f32 v21, v26, v27
	v_rcp_f32_e32 v28, v28
	v_rcp_f32_e32 v29, v29
; __device__ __forceinline__ unsigned cvt_pk_bf16(float lo, float hi) { unsigned r; asm("v_cvt_pk_bf16_f32 %0, %1, %2" : "=v"(r) : "v"(lo), "v"(hi)); return r; }
; __device__ __forceinline__ float bf_lo(unsigned u) { return __uint_as_float(u << 16); }
; __device__ __forceinline__ float bf_hi(unsigned u) { return __uint_as_float(u & 0xffff0000u); }
; template <class Epi>
; __device__ __forceinline__ void gemm_phase(LAS unsigned char* lds, const Gemm g, const Epi& E) {
;     ...
;         E(acc, cur, wr, wc, fr, fq);
;         if (!has_next) break;
; #pragma unroll
;         for (int a = 0; a < 2; ++a)
; #pragma unroll
;             for (int b = 0; b < 2; ++b)
; #pragma unroll
;                 for (int m = 0; m < 4; ++m)
; #pragma unroll
;                     for (int n = 0; n < 2; ++n) acc[a][b][m][n] = (f32x4){0.f, 0.f, 0.f, 0.f};
;         cur = nxt; cA = nA; cB = nB; ++ui;
;     }
;     __device__ __forceinline__ void operator()(const AccT& acc, const Unit& u, int wr, int wc, int fr, int fq) const {
;     ...
;                 for (int bj = 0; bj < 2; ++bj) yv[m][bj] = *(const u32x4*)(Y + (size_t)(row0 + ai * 128 + m * 16) * 2048 + col0 + bj * 128);
;             __builtin_amdgcn_sched_barrier(0);
; #pragma unroll
;             for (int m = 0; m < 4; ++m) { bf16_t* rowp = A2 + (size_t)(row0 + ai * 128 + m * 16) * 2048 + col0;
;                 const float mu = st[ai][m][0], rs = st[ai][m][1];
; #pragma unroll
;                 for (int bj = 0; bj < 2; ++bj) { const f32x4 v0 = acc[ai][bj][m][0], v1 = acc[ai][bj][m][1]; const u32x4 yw = yv[m][bj];
;                     const f32x4 y0 = (f32x4){bf_lo(yw.x), bf_hi(yw.x), bf_lo(yw.y), bf_hi(yw.y)}, y1 = (f32x4){bf_lo(yw.z), bf_hi(yw.z), bf_lo(yw.w), bf_hi(yw.w)};
;                     const f32x4 n0 = (y0 - mu) * rs * gw[bj][0], n1 = (y1 - mu) * rs * gw[bj][1];
;                     const f32x4 s0 = silu4(v0) * n0, s1 = silu4(v1) * n1;
;                     u32x4 w; w.x = cvt_pk_bf16(s0[0], s0[1]); w.y = cvt_pk_bf16(s0[2], s0[3]); w.z = cvt_pk_bf16(s1[0], s1[1]); w.w = cvt_pk_bf16(s1[2], s1[3]);
;                     *(u32x4*)(rowp + bj * 128) = w; } }
	v_rcp_f32_e32 v30, v30
	v_rcp_f32_e32 v31, v31
	v_cvt_pk_bf16_f32 v18, v22, v23
	v_cvt_pk_bf16_f32 v19, v24, v25
	global_store_dwordx4 v[34:35], v[18:21], off offset:256
	v_lshlrev_b32_e32 v24, 16, v80
	v_and_b32_e32 v25, 0xffff0000, v80
	v_lshlrev_b32_e32 v20, 16, v78
	v_and_b32_e32 v21, 0xffff0000, v78
	v_lshlrev_b32_e32 v26, 16, v81
	v_and_b32_e32 v27, 0xffff0000, v81
	v_lshlrev_b32_e32 v22, 16, v79
	v_and_b32_e32 v23, 0xffff0000, v79
	v_sub_f32_e32 v21, v21, v180
	v_sub_f32_e32 v20, v20, v180
	v_sub_f32_e32 v25, v25, v180
	v_sub_f32_e32 v24, v24, v180
	v_sub_f32_e32 v27, v27, v180
	v_sub_f32_e32 v26, v26, v180
	v_sub_f32_e32 v23, v23, v180
	v_sub_f32_e32 v22, v22, v180
	v_pk_mul_f32 v[20:21], v[180:181], v[20:21] op_sel:[1,0]
	v_pk_mul_f32 v[26:27], v[180:181], v[26:27] op_sel:[1,0]
	v_pk_mul_f32 v[24:25], v[180:181], v[24:25] op_sel:[1,0]
	v_pk_mul_f32 v[22:23], v[180:181], v[22:23] op_sel:[1,0]
	v_pk_mul_f32 v[20:21], v[86:87], v[20:21]
	v_pk_mul_f32 v[24:25], v[82:83], v[24:25]
	v_pk_mul_f32 v[26:27], v[84:85], v[26:27]
	v_pk_mul_f32 v[10:11], v[10:11], v[28:29]
	v_pk_mul_f32 v[12:13], v[12:13], v[30:31]
	v_pk_mul_f32 v[22:23], v[88:89], v[22:23]
	v_pk_mul_f32 v[14:15], v[14:15], v[20:21]
	v_pk_mul_f32 v[20:21], v[12:13], v[26:27]
	v_pk_mul_f32 v[12:13], v[10:11], v[24:25]
	v_pk_mul_f32 v[16:17], v[16:17], v[22:23]
	v_cvt_pk_bf16_f32 v12, v12, v13
	v_cvt_pk_bf16_f32 v13, v20, v21
	v_mul_f32_e32 v20, 0xbfb8aa3b, v6
	v_mul_f32_e32 v21, 0xbfb8aa3b, v7
	v_mul_f32_e32 v22, 0xbfb8aa3b, v8
	v_mul_f32_e32 v23, 0xbfb8aa3b, v9
	v_exp_f32_e32 v20, v20
	v_exp_f32_e32 v21, v21
	v_exp_f32_e32 v22, v22
	v_exp_f32_e32 v23, v23
	v_add_f32_e32 v20, 1.0, v20
	v_add_f32_e32 v21, 1.0, v21
	v_add_f32_e32 v22, 1.0, v22
	v_add_f32_e32 v23, 1.0, v23
	v_rcp_f32_e32 v20, v20
	v_rcp_f32_e32 v21, v21
	v_rcp_f32_e32 v22, v22
	v_rcp_f32_e32 v23, v23
	v_lshl_add_u64 v[18:19], s[34:35], 0, v[102:103]
	v_pk_mul_f32 v[6:7], v[6:7], v[20:21]
	v_mul_f32_e32 v20, 0xbfb8aa3b, v2
	v_pk_mul_f32 v[8:9], v[8:9], v[22:23]
	v_mul_f32_e32 v21, 0xbfb8aa3b, v3
	v_mul_f32_e32 v22, 0xbfb8aa3b, v4
	v_mul_f32_e32 v23, 0xbfb8aa3b, v5
	v_exp_f32_e32 v20, v20
	v_exp_f32_e32 v21, v21
	v_exp_f32_e32 v22, v22
	v_exp_f32_e32 v23, v23
	v_add_f32_e32 v20, 1.0, v20
	v_add_f32_e32 v21, 1.0, v21
	v_add_f32_e32 v22, 1.0, v22
	v_add_f32_e32 v23, 1.0, v23
	v_lshl_add_u64 v[18:19], v[18:19], 0, v[182:183]
	v_cvt_pk_bf16_f32 v10, v14, v15
	v_cvt_pk_bf16_f32 v11, v16, v17
	v_rcp_f32_e32 v20, v20
	v_rcp_f32_e32 v21, v21
	v_rcp_f32_e32 v22, v22
	v_rcp_f32_e32 v23, v23
	global_store_dwordx4 v[18:19], v[10:13], off
	v_lshlrev_b32_e32 v14, 16, v76
	v_and_b32_e32 v15, 0xffff0000, v76
	v_lshlrev_b32_e32 v10, 16, v74
	v_and_b32_e32 v11, 0xffff0000, v74
	v_lshlrev_b32_e32 v16, 16, v77
	v_and_b32_e32 v17, 0xffff0000, v77
	v_lshlrev_b32_e32 v12, 16, v75
	v_and_b32_e32 v13, 0xffff0000, v75
	v_sub_f32_e32 v11, v11, v180
	v_sub_f32_e32 v10, v10, v180
	v_sub_f32_e32 v15, v15, v180
	v_sub_f32_e32 v14, v14, v180
	v_sub_f32_e32 v17, v17, v180
	v_sub_f32_e32 v16, v16, v180
	v_sub_f32_e32 v13, v13, v180
	v_sub_f32_e32 v12, v12, v180
	v_pk_mul_f32 v[10:11], v[180:181], v[10:11] op_sel:[1,0]
	v_pk_mul_f32 v[16:17], v[180:181], v[16:17] op_sel:[1,0]
	v_pk_mul_f32 v[14:15], v[180:181], v[14:15] op_sel:[1,0]
	v_pk_mul_f32 v[12:13], v[180:181], v[12:13] op_sel:[1,0]
	v_pk_mul_f32 v[10:11], v[70:71], v[10:11]
	v_pk_mul_f32 v[14:15], v[66:67], v[14:15]
	v_pk_mul_f32 v[16:17], v[68:69], v[16:17]
	v_pk_mul_f32 v[2:3], v[2:3], v[20:21]
	v_pk_mul_f32 v[4:5], v[4:5], v[22:23]
	v_pk_mul_f32 v[12:13], v[72:73], v[12:13]
	v_pk_mul_f32 v[6:7], v[6:7], v[10:11]
	v_pk_mul_f32 v[10:11], v[4:5], v[16:17]
	v_pk_mul_f32 v[4:5], v[2:3], v[14:15]
	v_pk_mul_f32 v[8:9], v[8:9], v[12:13]
	v_cvt_pk_bf16_f32 v2, v6, v7
	v_cvt_pk_bf16_f32 v4, v4, v5
	v_cvt_pk_bf16_f32 v5, v10, v11
	s_nop 0
	v_cvt_pk_bf16_f32 v3, v8, v9
	global_store_dwordx4 v[18:19], v[2:5], off offset:256
	s_and_b64 vcc, exec, s[2:3]
	s_mov_b32 s12, s8
	s_mov_b32 s52, s64
	s_mov_b64 s[16:17], s[4:5]
	s_mov_b64 s[14:15], s[10:11]
	s_cbranch_vccz .LBB0_470
	s_waitcnt vmcnt(0)
	s_cmpk_gt_u32 s1, 0xff
	s_cbranch_scc1 .LBB0_479
	s_barrier

; #define PG8_STAGE(bufoff, gbase, voff) do { _Pragma("unroll") for (int _i = 0; _i < 2; ++_i) \
;         __builtin_amdgcn_global_load_lds((const unsigned*)((const char*)(gbase) + (voff)[_i]), (LAS unsigned*)(lds + (bufoff) + ldsw + _i * 8192), 16, 0, 0); } while (0)
; #define PG8_LDA(dst, b, h) do { _Pragma("unroll") for (int m = 0; m < 4; ++m) _Pragma("unroll") for (int k = 0; k < 2; ++k) dst[m][k] = *(const LAS bf16x8*)(lds + PG8_SA(b, h) + aoff + m * 2048 + k * 1024); } while (0)
; #define PG8_LDB(dst, b, h) do { _Pragma("unroll") for (int n = 0; n < 2; ++n) _Pragma("unroll") for (int k = 0; k < 2; ++k) dst[n][k] = *(const LAS bf16x8*)(lds + PG8_SB(b, h) + boff + n * 2048 + k * 1024); } while (0)
; #define PG8_MMA(ai, bj, At, Bt) do { __builtin_amdgcn_s_setprio(1); _Pragma("unroll") for (int m = 0; m < 4; ++m) _Pragma("unroll") for (int n = 0; n < 2; ++n) _Pragma("unroll") for (int k = 0; k < 2; ++k) \
;         acc[ai][bj][m][n] = __builtin_amdgcn_mfma_f32_16x16x32_bf16(Bt[n][k], At[m][k], acc[ai][bj][m][n], 0, 0, 0); __builtin_amdgcn_s_setprio(0); } while (0)
; #define PG8_WAIT_L(n) asm volatile("s_waitcnt lgkmcnt(" #n ")" ::: "memory")
; #define PG8_BAR __builtin_amdgcn_s_barrier()
; #define PG8_SCHED __builtin_amdgcn_sched_barrier(0)
; template <class Epi>
; __device__ __forceinline__ void gemm_phase(LAS unsigned char* lds, const Gemm g, const Epi& E) {
;     ...
;         for (int t = 0; t < nt; t += 2) {
;             const bool last = (t == nt - 2);
;             const char* a1 = cA + (size_t)(t + 1) * kstep;
;             const char* a2 = last ? nA : cA + (size_t)(t + 2) * kstep; const char* b2 = last ? nB : cB + (size_t)(t + 2) * kstep;
;             const char* a3 = a2 + kstep; const char* b3 = b2 + kstep;
;             PG8_LDB(B0, 0, 0); PG8_SCHED; PG8_LDA(At, 0, 0); PG8_STAGE(PG8_SA(1, 1), a1 + hstepA, voffA);
;             PG8_WAIT_L(8); PG8_BAR; PG8_WAIT_L(0); PG8_MMA(0, 0, At, B0); PG8_BAR; PG8_SCHED;
;             PG8_LDB(B1, 0, 1); PG8_STAGE(PG8_SB(0, 0), b2, voffB);
;             PG8_BAR; PG8_WAIT_L(0); PG8_MMA(0, 1, At, B1); PG8_BAR;
;             PG8_LDA(At, 0, 1); PG8_STAGE(PG8_SA(0, 0), a2, voffA);
;             PG8_BAR; PG8_WAIT_L(0); PG8_MMA(1, 0, At, B0); PG8_BAR; PG8_SCHED;
.LBB0_495:
	s_add_u32 s14, s12, 0xfff80080
	s_addc_u32 s15, s13, -1
	s_add_i32 s66, 0, 0x10000
	v_add_u32_e32 v142, s66, v159
	ds_read_b128 v[130:133], v142
	ds_read_b128 v[134:137], v142 offset:1024
	ds_read_b128 v[138:141], v142 offset:2048
	ds_read_b128 v[142:145], v142 offset:3072
	s_cmp_eq_u32 s65, 28
	s_cselect_b32 s17, s9, s15
	s_cselect_b32 s16, s8, s14
	s_cselect_b32 s15, s5, s64
	s_cselect_b32 s14, s4, s7
	v_lshl_add_u64 v[192:193], s[12:13], 0, v[150:151]
	s_add_i32 m0, s11, 0xc000
	ds_read_b128 v[154:157], v160
	ds_read_b128 v[162:165], v160 offset:1024
	ds_read_b128 v[166:169], v160 offset:2048
	ds_read_b128 v[170:173], v160 offset:3072
	ds_read_b128 v[174:177], v160 offset:4096
	ds_read_b128 v[180:183], v160 offset:5120
	ds_read_b128 v[184:187], v160 offset:6144
	ds_read_b128 v[188:191], v160 offset:7168
	global_load_lds_dwordx4 v[192:193], off
	v_lshl_add_u64 v[192:193], s[12:13], 0, v[152:153]
	s_add_i32 m0, s11, 0xe000
	s_nop 0
	global_load_lds_dwordx4 v[192:193], off
	s_waitcnt lgkmcnt(8)
	s_barrier
	s_waitcnt lgkmcnt(0)
	v_mfma_f32_16x16x32_bf16 v[126:129], v[130:133], v[154:157], v[126:129]
	v_mfma_f32_16x16x32_bf16 v[122:125], v[138:141], v[154:157], v[122:125]
	v_mfma_f32_16x16x32_bf16 v[114:117], v[130:133], v[166:169], v[114:117]
	v_mfma_f32_16x16x32_bf16 v[106:109], v[138:141], v[166:169], v[106:109]
	v_mfma_f32_16x16x32_bf16 v[102:105], v[130:133], v[174:177], v[102:105]
	v_mfma_f32_16x16x32_bf16 v[90:93], v[138:141], v[174:177], v[90:93]
	v_mfma_f32_16x16x32_bf16 v[86:89], v[130:133], v[184:187], v[86:89]
	v_mfma_f32_16x16x32_bf16 v[74:77], v[138:141], v[184:187], v[74:77]
	v_mfma_f32_16x16x32_bf16 v[126:129], v[134:137], v[162:165], v[126:129]
	v_mfma_f32_16x16x32_bf16 v[122:125], v[142:145], v[162:165], v[122:125]
	v_mfma_f32_16x16x32_bf16 v[114:117], v[134:137], v[170:173], v[114:117]
	v_mfma_f32_16x16x32_bf16 v[106:109], v[142:145], v[170:173], v[106:109]
	v_mfma_f32_16x16x32_bf16 v[102:105], v[134:137], v[180:183], v[102:105]
	v_mfma_f32_16x16x32_bf16 v[90:93], v[142:145], v[180:183], v[90:93]
	v_mfma_f32_16x16x32_bf16 v[86:89], v[134:137], v[188:191], v[86:89]
	v_mfma_f32_16x16x32_bf16 v[74:77], v[142:145], v[188:191], v[74:77]
	s_barrier
	s_add_i32 s68, 0, 0x14000
	s_add_i32 s66, s66, s25
	v_add_u32_e32 v161, s68, v159
	v_lshl_add_u64 v[208:209], s[14:15], 0, v[148:149]
	s_mov_b32 m0, s66
	ds_read_b128 v[192:195], v161
	ds_read_b128 v[196:199], v161 offset:1024
	ds_read_b128 v[200:203], v161 offset:2048
	ds_read_b128 v[204:207], v161 offset:3072
	global_load_lds_dwordx4 v[208:209], off
	v_lshl_add_u64 v[226:227], s[14:15], 0, v[146:147]
	s_add_i32 m0, s66, 0x2000
	s_nop 0
	global_load_lds_dwordx4 v[226:227], off
	s_nop 1
	s_mov_b32 m0, s11
	v_lshl_add_u64 v[228:229], s[16:17], 0, v[148:149]
	s_barrier
	s_waitcnt lgkmcnt(0)
	v_mfma_f32_16x16x32_bf16 v[118:121], v[192:195], v[154:157], v[118:121]
	v_mfma_f32_16x16x32_bf16 v[110:113], v[200:203], v[154:157], v[110:113]
	v_mfma_f32_16x16x32_bf16 v[98:101], v[192:195], v[166:169], v[98:101]
	v_mfma_f32_16x16x32_bf16 v[94:97], v[200:203], v[166:169], v[94:97]
	v_mfma_f32_16x16x32_bf16 v[82:85], v[192:195], v[174:177], v[82:85]
	v_mfma_f32_16x16x32_bf16 v[78:81], v[200:203], v[174:177], v[78:81]
	v_mfma_f32_16x16x32_bf16 v[70:73], v[192:195], v[184:187], v[70:73]
	v_mfma_f32_16x16x32_bf16 v[66:69], v[200:203], v[184:187], v[66:69]
	v_mfma_f32_16x16x32_bf16 v[118:121], v[196:199], v[162:165], v[118:121]
	v_mfma_f32_16x16x32_bf16 v[110:113], v[204:207], v[162:165], v[110:113]
	v_mfma_f32_16x16x32_bf16 v[98:101], v[196:199], v[170:173], v[98:101]
	v_mfma_f32_16x16x32_bf16 v[94:97], v[204:207], v[170:173], v[94:97]
	v_mfma_f32_16x16x32_bf16 v[82:85], v[196:199], v[180:183], v[82:85]
	v_mfma_f32_16x16x32_bf16 v[78:81], v[204:207], v[180:183], v[78:81]
	v_mfma_f32_16x16x32_bf16 v[70:73], v[196:199], v[188:191], v[70:73]
	v_mfma_f32_16x16x32_bf16 v[66:69], v[204:207], v[188:191], v[66:69]
	s_barrier
	ds_read_b128 v[154:157], v160 offset:16384
	ds_read_b128 v[162:165], v160 offset:17408
	ds_read_b128 v[166:169], v160 offset:18432
	ds_read_b128 v[170:173], v160 offset:19456
	ds_read_b128 v[174:177], v160 offset:20480
	ds_read_b128 v[180:183], v160 offset:21504
	ds_read_b128 v[184:187], v160 offset:22528
	ds_read_b128 v[188:191], v160 offset:23552
	global_load_lds_dwordx4 v[228:229], off
	v_lshl_add_u64 v[230:231], s[16:17], 0, v[146:147]
	s_mov_b32 m0, s31
	s_nop 0
	global_load_lds_dwordx4 v[230:231], off
	s_barrier
	s_waitcnt lgkmcnt(0)
	v_mfma_f32_16x16x32_bf16 v[62:65], v[130:133], v[154:157], v[62:65]
	v_mfma_f32_16x16x32_bf16 v[58:61], v[138:141], v[154:157], v[58:61]
	v_mfma_f32_16x16x32_bf16 v[54:57], v[130:133], v[166:169], v[54:57]
	v_mfma_f32_16x16x32_bf16 v[42:45], v[138:141], v[166:169], v[42:45]
	v_mfma_f32_16x16x32_bf16 v[38:41], v[130:133], v[174:177], v[38:41]
	v_mfma_f32_16x16x32_bf16 v[26:29], v[138:141], v[174:177], v[26:29]
	v_mfma_f32_16x16x32_bf16 v[22:25], v[130:133], v[184:187], v[22:25]
	v_mfma_f32_16x16x32_bf16 v[10:13], v[138:141], v[184:187], v[10:13]
	v_mfma_f32_16x16x32_bf16 v[62:65], v[134:137], v[162:165], v[62:65]
	v_mfma_f32_16x16x32_bf16 v[58:61], v[142:145], v[162:165], v[58:61]
	v_mfma_f32_16x16x32_bf16 v[54:57], v[134:137], v[170:173], v[54:57]
	v_mfma_f32_16x16x32_bf16 v[42:45], v[142:145], v[170:173], v[42:45]
	v_mfma_f32_16x16x32_bf16 v[38:41], v[134:137], v[180:183], v[38:41]
	v_mfma_f32_16x16x32_bf16 v[26:29], v[142:145], v[180:183], v[26:29]
	v_mfma_f32_16x16x32_bf16 v[22:25], v[134:137], v[188:191], v[22:25]
	v_mfma_f32_16x16x32_bf16 v[10:13], v[142:145], v[188:191], v[10:13]
	s_barrier
; #define PG8_STAGE(bufoff, gbase, voff) do { _Pragma("unroll") for (int _i = 0; _i < 2; ++_i) \
;         __builtin_amdgcn_global_load_lds((const unsigned*)((const char*)(gbase) + (voff)[_i]), (LAS unsigned*)(lds + (bufoff) + ldsw + _i * 8192), 16, 0, 0); } while (0)
; #define PG8_LDA(dst, b, h) do { _Pragma("unroll") for (int m = 0; m < 4; ++m) _Pragma("unroll") for (int k = 0; k < 2; ++k) dst[m][k] = *(const LAS bf16x8*)(lds + PG8_SA(b, h) + aoff + m * 2048 + k * 1024); } while (0)
; #define PG8_LDB(dst, b, h) do { _Pragma("unroll") for (int n = 0; n < 2; ++n) _Pragma("unroll") for (int k = 0; k < 2; ++k) dst[n][k] = *(const LAS bf16x8*)(lds + PG8_SB(b, h) + boff + n * 2048 + k * 1024); } while (0)
; #define PG8_MMA(ai, bj, At, Bt) do { __builtin_amdgcn_s_setprio(1); _Pragma("unroll") for (int m = 0; m < 4; ++m) _Pragma("unroll") for (int n = 0; n < 2; ++n) _Pragma("unroll") for (int k = 0; k < 2; ++k) \
;         acc[ai][bj][m][n] = __builtin_amdgcn_mfma_f32_16x16x32_bf16(Bt[n][k], At[m][k], acc[ai][bj][m][n], 0, 0, 0); __builtin_amdgcn_s_setprio(0); } while (0)
; #define PG8_WAIT_V(n) asm volatile("s_waitcnt vmcnt(" #n ")" ::: "memory")
; #define PG8_WAIT_L(n) asm volatile("s_waitcnt lgkmcnt(" #n ")" ::: "memory")
; #define PG8_BAR __builtin_amdgcn_s_barrier()
; #define PG8_SCHED __builtin_amdgcn_sched_barrier(0)
; template <class Epi>
; __device__ __forceinline__ void gemm_phase(LAS unsigned char* lds, const Gemm g, const Epi& E) {
;     ...
;             PG8_BAR; PG8_WAIT_L(0); PG8_MMA(1, 0, At, B0); PG8_BAR; PG8_SCHED;
;             PG8_STAGE(PG8_SB(0, 1), b2 + hstepB, voffB);
;             PG8_WAIT_V(6); PG8_BAR; PG8_MMA(1, 1, At, B1); PG8_BAR;
;             PG8_LDB(B0, 1, 0); PG8_SCHED; PG8_LDA(At, 1, 0); PG8_STAGE(PG8_SA(0, 1), a2 + hstepA, voffA);
;             PG8_WAIT_L(8); PG8_BAR; PG8_WAIT_L(0); PG8_MMA(0, 0, At, B0); PG8_BAR; PG8_SCHED;
;             PG8_LDB(B1, 1, 1); PG8_STAGE(PG8_SB(1, 0), b3, voffB);
;             PG8_BAR; PG8_WAIT_L(0); PG8_MMA(0, 1, At, B1); PG8_BAR;
	s_add_u32 s66, s14, 0x80000
	s_addc_u32 s67, s15, 0
	s_add_i32 s68, s68, s25
	v_lshl_add_u64 v[130:131], s[66:67], 0, v[148:149]
	s_mov_b32 m0, s68
	s_nop 0
	global_load_lds_dwordx4 v[130:131], off
	v_lshl_add_u64 v[130:131], s[66:67], 0, v[146:147]
	s_add_i32 m0, s68, 0x2000
	s_nop 0
	global_load_lds_dwordx4 v[130:131], off
	s_add_i32 s66, 0, 0x18000
	v_add_u32_e32 v142, s66, v159
	s_waitcnt vmcnt(6)
	s_barrier
	v_mfma_f32_16x16x32_bf16 v[50:53], v[192:195], v[154:157], v[50:53]
	v_mfma_f32_16x16x32_bf16 v[46:49], v[200:203], v[154:157], v[46:49]
	v_mfma_f32_16x16x32_bf16 v[34:37], v[192:195], v[166:169], v[34:37]
	v_mfma_f32_16x16x32_bf16 v[30:33], v[200:203], v[166:169], v[30:33]
	v_mfma_f32_16x16x32_bf16 v[18:21], v[192:195], v[174:177], v[18:21]
	v_mfma_f32_16x16x32_bf16 v[14:17], v[200:203], v[174:177], v[14:17]
	v_mfma_f32_16x16x32_bf16 v[6:9], v[192:195], v[184:187], v[6:9]
	v_mfma_f32_16x16x32_bf16 v[2:5], v[200:203], v[184:187], v[2:5]
	v_mfma_f32_16x16x32_bf16 v[50:53], v[196:199], v[162:165], v[50:53]
	v_mfma_f32_16x16x32_bf16 v[46:49], v[204:207], v[162:165], v[46:49]
	v_mfma_f32_16x16x32_bf16 v[34:37], v[196:199], v[170:173], v[34:37]
	v_mfma_f32_16x16x32_bf16 v[30:33], v[204:207], v[170:173], v[30:33]
	v_mfma_f32_16x16x32_bf16 v[18:21], v[196:199], v[180:183], v[18:21]
	v_mfma_f32_16x16x32_bf16 v[14:17], v[204:207], v[180:183], v[14:17]
	v_mfma_f32_16x16x32_bf16 v[6:9], v[196:199], v[188:191], v[6:9]
	v_mfma_f32_16x16x32_bf16 v[2:5], v[204:207], v[188:191], v[2:5]
	s_barrier
	ds_read_b128 v[130:133], v142
	ds_read_b128 v[134:137], v142 offset:1024
	ds_read_b128 v[138:141], v142 offset:2048
	ds_read_b128 v[142:145], v142 offset:3072
	s_add_u32 s16, s16, 0x80000
	s_addc_u32 s17, s17, 0
	s_mov_b32 m0, s36
	v_lshl_add_u64 v[192:193], s[16:17], 0, v[148:149]
	ds_read_b128 v[154:157], v160 offset:32768
	ds_read_b128 v[162:165], v160 offset:33792
	ds_read_b128 v[166:169], v160 offset:34816
	ds_read_b128 v[170:173], v160 offset:35840
	ds_read_b128 v[174:177], v160 offset:36864
	ds_read_b128 v[180:183], v160 offset:37888
	ds_read_b128 v[184:187], v160 offset:38912
	ds_read_b128 v[188:191], v160 offset:39936
	global_load_lds_dwordx4 v[192:193], off
	v_lshl_add_u64 v[192:193], s[16:17], 0, v[146:147]
	s_mov_b32 m0, s44
	s_nop 0
	global_load_lds_dwordx4 v[192:193], off
	s_waitcnt lgkmcnt(8)
	s_barrier
	s_waitcnt lgkmcnt(0)
	v_mfma_f32_16x16x32_bf16 v[126:129], v[130:133], v[154:157], v[126:129]
	v_mfma_f32_16x16x32_bf16 v[122:125], v[138:141], v[154:157], v[122:125]
	v_mfma_f32_16x16x32_bf16 v[114:117], v[130:133], v[166:169], v[114:117]
	v_mfma_f32_16x16x32_bf16 v[106:109], v[138:141], v[166:169], v[106:109]
	v_mfma_f32_16x16x32_bf16 v[102:105], v[130:133], v[174:177], v[102:105]
	v_mfma_f32_16x16x32_bf16 v[90:93], v[138:141], v[174:177], v[90:93]
	v_mfma_f32_16x16x32_bf16 v[86:89], v[130:133], v[184:187], v[86:89]
	v_mfma_f32_16x16x32_bf16 v[74:77], v[138:141], v[184:187], v[74:77]
	v_mfma_f32_16x16x32_bf16 v[126:129], v[134:137], v[162:165], v[126:129]
	v_mfma_f32_16x16x32_bf16 v[122:125], v[142:145], v[162:165], v[122:125]
	v_mfma_f32_16x16x32_bf16 v[114:117], v[134:137], v[170:173], v[114:117]
	v_mfma_f32_16x16x32_bf16 v[106:109], v[142:145], v[170:173], v[106:109]
	v_mfma_f32_16x16x32_bf16 v[102:105], v[134:137], v[180:183], v[102:105]
	v_mfma_f32_16x16x32_bf16 v[90:93], v[142:145], v[180:183], v[90:93]
	v_mfma_f32_16x16x32_bf16 v[86:89], v[134:137], v[188:191], v[86:89]
	v_mfma_f32_16x16x32_bf16 v[74:77], v[142:145], v[188:191], v[74:77]
	s_barrier
	s_add_i32 s16, 0, 0x1c000
	s_add_i32 s17, s66, s25
	v_add_u32_e32 v161, s16, v159
	v_lshl_add_u64 v[208:209], v[208:209], 0, s[86:87]
	s_mov_b32 m0, s17
	ds_read_b128 v[192:195], v161
	ds_read_b128 v[196:199], v161 offset:1024
	ds_read_b128 v[200:203], v161 offset:2048
	ds_read_b128 v[204:207], v161 offset:3072
	global_load_lds_dwordx4 v[208:209], off
	v_lshl_add_u64 v[208:209], v[226:227], 0, s[86:87]
	s_add_i32 m0, s17, 0x2000
	s_nop 0
	global_load_lds_dwordx4 v[208:209], off
	s_nop 1
	s_mov_b32 m0, s53
	v_lshl_add_u64 v[208:209], v[228:229], 0, s[86:87]
	s_barrier
	s_waitcnt lgkmcnt(0)
	v_mfma_f32_16x16x32_bf16 v[118:121], v[192:195], v[154:157], v[118:121]
	v_mfma_f32_16x16x32_bf16 v[110:113], v[200:203], v[154:157], v[110:113]
	v_mfma_f32_16x16x32_bf16 v[98:101], v[192:195], v[166:169], v[98:101]
	v_mfma_f32_16x16x32_bf16 v[94:97], v[200:203], v[166:169], v[94:97]
	v_mfma_f32_16x16x32_bf16 v[82:85], v[192:195], v[174:177], v[82:85]
	v_mfma_f32_16x16x32_bf16 v[78:81], v[200:203], v[174:177], v[78:81]
	v_mfma_f32_16x16x32_bf16 v[70:73], v[192:195], v[184:187], v[70:73]
	v_mfma_f32_16x16x32_bf16 v[66:69], v[200:203], v[184:187], v[66:69]
	v_mfma_f32_16x16x32_bf16 v[118:121], v[196:199], v[162:165], v[118:121]
	v_mfma_f32_16x16x32_bf16 v[110:113], v[204:207], v[162:165], v[110:113]
	v_mfma_f32_16x16x32_bf16 v[98:101], v[196:199], v[170:173], v[98:101]
	v_mfma_f32_16x16x32_bf16 v[94:97], v[204:207], v[170:173], v[94:97]
	v_mfma_f32_16x16x32_bf16 v[82:85], v[196:199], v[180:183], v[82:85]
	v_mfma_f32_16x16x32_bf16 v[78:81], v[204:207], v[180:183], v[78:81]
	v_mfma_f32_16x16x32_bf16 v[70:73], v[196:199], v[188:191], v[70:73]
	v_mfma_f32_16x16x32_bf16 v[66:69], v[204:207], v[188:191], v[66:69]
	s_barrier
	ds_read_b128 v[154:157], v160 offset:49152
	ds_read_b128 v[162:165], v160 offset:50176
	ds_read_b128 v[166:169], v160 offset:51200
	ds_read_b128 v[170:173], v160 offset:52224
	ds_read_b128 v[174:177], v160 offset:53248
	ds_read_b128 v[180:183], v160 offset:54272
	ds_read_b128 v[184:187], v160 offset:55296
	ds_read_b128 v[188:191], v160 offset:56320
	global_load_lds_dwordx4 v[208:209], off
	v_lshl_add_u64 v[208:209], v[230:231], 0, s[86:87]
	s_mov_b32 m0, s58
	s_nop 0
	global_load_lds_dwordx4 v[208:209], off
	s_barrier
; #define PG8_STAGE(bufoff, gbase, voff) do { _Pragma("unroll") for (int _i = 0; _i < 2; ++_i) \
;         __builtin_amdgcn_global_load_lds((const unsigned*)((const char*)(gbase) + (voff)[_i]), (LAS unsigned*)(lds + (bufoff) + ldsw + _i * 8192), 16, 0, 0); } while (0)
; #define PG8_LDA(dst, b, h) do { _Pragma("unroll") for (int m = 0; m < 4; ++m) _Pragma("unroll") for (int k = 0; k < 2; ++k) dst[m][k] = *(const LAS bf16x8*)(lds + PG8_SA(b, h) + aoff + m * 2048 + k * 1024); } while (0)
; #define PG8_WAIT_V(n) asm volatile("s_waitcnt vmcnt(" #n ")" ::: "memory")
; #define PG8_WAIT_L(n) asm volatile("s_waitcnt lgkmcnt(" #n ")" ::: "memory")
; #define PG8_BAR __builtin_amdgcn_s_barrier()
; template <class Epi>
; __device__ __forceinline__ void gemm_phase(LAS unsigned char* lds, const Gemm g, const Epi& E) {
;     ...
;             PG8_BAR; PG8_WAIT_L(0); PG8_MMA(0, 1, At, B1); PG8_BAR;
;             PG8_LDA(At, 1, 1); PG8_STAGE(PG8_SA(1, 0), a3, voffA);
;             PG8_BAR; PG8_WAIT_L(0); PG8_MMA(1, 0, At, B0); PG8_BAR; PG8_SCHED;
;             PG8_STAGE(PG8_SB(1, 1), b3 + hstepB, voffB);
;             PG8_WAIT_V(6); PG8_BAR; PG8_MMA(1, 1, At, B1); PG8_BAR;
;         }
;     __device__ __forceinline__ void operator()(const AccT& acc, const Unit& u, int wr, int wc, int fr, int fq) const {
;         asm volatile("" : "+v"(fr), "+v"(fq));
;         const int gpm = mapA.src(u.pm);
;         const int mb = gpm < 32 ? 32 : (gpm - 32) >> 3;
;         const int row0 = gpm * 256 + wr * 64 + fr, col0 = u.pn * 256 + wc * 32 + 4 * fq;
;         const float* gp = modl + ((size_t)mb * 6 + gi) * 1024;
;         f32x4 gv[2][2];
; #pragma unroll
;         for (int bj = 0; bj < 2; ++bj)
; #pragma unroll
;             for (int n = 0; n < 2; ++n) { gv[bj][n] = *(const f32x4*)(gp + col0 + bj * 128 + n * 16); if (scale) gv[bj][n] = gv[bj][n] * *(const f32x4*)(scale + col0 + bj * 128 + n * 16); }
;         const float* sbase = (gpm < 32 ? Xc : Xl) + (size_t)row0 * 1024 + col0;
; #pragma unroll
;         for (int ai = 0; ai < 2; ++ai) {
;             f32x4 xo[4][2][2];
; #pragma unroll
;             for (int m = 0; m < 4; ++m)
; #pragma unroll
;                 for (int bj = 0; bj < 2; ++bj)
; #pragma unroll
;                     for (int n = 0; n < 2; ++n) xo[m][bj][n] = *(const f32x4*)(sbase + (size_t)(ai * 128 + m * 16) * 1024 + bj * 128 + n * 16);
	s_waitcnt lgkmcnt(0)
	v_mfma_f32_16x16x32_bf16 v[62:65], v[130:133], v[154:157], v[62:65]
	v_mfma_f32_16x16x32_bf16 v[58:61], v[138:141], v[154:157], v[58:61]
	v_mfma_f32_16x16x32_bf16 v[54:57], v[130:133], v[166:169], v[54:57]
	v_mfma_f32_16x16x32_bf16 v[42:45], v[138:141], v[166:169], v[42:45]
	v_mfma_f32_16x16x32_bf16 v[38:41], v[130:133], v[174:177], v[38:41]
	v_mfma_f32_16x16x32_bf16 v[26:29], v[138:141], v[174:177], v[26:29]
	v_mfma_f32_16x16x32_bf16 v[22:25], v[130:133], v[184:187], v[22:25]
	v_mfma_f32_16x16x32_bf16 v[10:13], v[138:141], v[184:187], v[10:13]
	v_mfma_f32_16x16x32_bf16 v[62:65], v[134:137], v[162:165], v[62:65]
	v_mfma_f32_16x16x32_bf16 v[58:61], v[142:145], v[162:165], v[58:61]
	v_mfma_f32_16x16x32_bf16 v[54:57], v[134:137], v[170:173], v[54:57]
	v_mfma_f32_16x16x32_bf16 v[42:45], v[142:145], v[170:173], v[42:45]
	v_mfma_f32_16x16x32_bf16 v[38:41], v[134:137], v[180:183], v[38:41]
	v_mfma_f32_16x16x32_bf16 v[26:29], v[142:145], v[180:183], v[26:29]
	v_mfma_f32_16x16x32_bf16 v[22:25], v[134:137], v[188:191], v[22:25]
	v_mfma_f32_16x16x32_bf16 v[10:13], v[142:145], v[188:191], v[10:13]
	s_barrier
	s_add_u32 s14, s14, 0x80080
	s_addc_u32 s15, s15, 0
	s_add_i32 s16, s16, s25
	v_lshl_add_u64 v[130:131], s[14:15], 0, v[148:149]
	s_mov_b32 m0, s16
	s_nop 0
	global_load_lds_dwordx4 v[130:131], off
	v_lshl_add_u64 v[130:131], s[14:15], 0, v[146:147]
	s_add_i32 m0, s16, 0x2000
	s_nop 0
	global_load_lds_dwordx4 v[130:131], off
	s_add_i32 s65, s65, 2
	s_add_u32 s12, s12, 0x100
	s_addc_u32 s13, s13, 0
	s_add_u32 s7, s7, 0x100
	s_addc_u32 s64, s64, 0
	s_cmp_gt_u32 s65, 29
	s_waitcnt vmcnt(6)
	s_barrier
	v_mfma_f32_16x16x32_bf16 v[50:53], v[192:195], v[154:157], v[50:53]
	v_mfma_f32_16x16x32_bf16 v[46:49], v[200:203], v[154:157], v[46:49]
	v_mfma_f32_16x16x32_bf16 v[34:37], v[192:195], v[166:169], v[34:37]
	v_mfma_f32_16x16x32_bf16 v[30:33], v[200:203], v[166:169], v[30:33]
	v_mfma_f32_16x16x32_bf16 v[18:21], v[192:195], v[174:177], v[18:21]
	v_mfma_f32_16x16x32_bf16 v[14:17], v[200:203], v[174:177], v[14:17]
	v_mfma_f32_16x16x32_bf16 v[6:9], v[192:195], v[184:187], v[6:9]
	v_mfma_f32_16x16x32_bf16 v[2:5], v[200:203], v[184:187], v[2:5]
	v_mfma_f32_16x16x32_bf16 v[50:53], v[196:199], v[162:165], v[50:53]
	v_mfma_f32_16x16x32_bf16 v[46:49], v[204:207], v[162:165], v[46:49]
	v_mfma_f32_16x16x32_bf16 v[34:37], v[196:199], v[170:173], v[34:37]
	v_mfma_f32_16x16x32_bf16 v[30:33], v[204:207], v[170:173], v[30:33]
	v_mfma_f32_16x16x32_bf16 v[18:21], v[196:199], v[180:183], v[18:21]
	v_mfma_f32_16x16x32_bf16 v[14:17], v[204:207], v[180:183], v[14:17]
	v_mfma_f32_16x16x32_bf16 v[6:9], v[196:199], v[188:191], v[6:9]
	v_mfma_f32_16x16x32_bf16 v[2:5], v[204:207], v[188:191], v[2:5]
	s_barrier
	s_cbranch_scc0 .LBB0_495
	v_readlane_b32 s7, v255, 27
	s_cmp_ge_i32 s61, s7
	s_cselect_b32 s7, s29, 0
	s_add_i32 s7, s61, s7
	s_cmp_lt_i32 s7, 32
	v_mov_b32_e32 v156, v158
	v_mov_b32_e32 v130, v1
	s_cselect_b64 s[12:13], -1, 0
	s_sub_i32 s14, s7, 32
	s_lshl_b32 s10, s10, 8
	s_ashr_i32 s14, s14, 3
	s_or_b32 s10, s10, s52
	v_lshl_add_u32 v130, v130, 2, s10
	s_mul_i32 s10, s14, 6
	s_and_b64 s[14:15], s[12:13], exec
	s_cselect_b32 s14, 0xc0, s10
	s_ashr_i32 s15, s14, 31
	s_lshl_b64 s[14:15], s[14:15], 12
	s_add_u32 s14, s88, s14
	s_addc_u32 s15, s89, s15
	s_lshl_b32 s7, s7, 8
	s_add_i32 s7, s7, s50
	v_ashrrev_i32_e32 v131, 31, v130
	v_add_u32_e32 v156, s7, v156
	s_and_b64 s[12:13], s[12:13], exec
	v_readlane_b32 s7, v255, 16
	v_readlane_b32 s10, v255, 18
	v_lshlrev_b64 v[154:155], 2, v[130:131]
	s_cselect_b32 s13, s7, s10
	v_readlane_b32 s7, v255, 17
	v_readlane_b32 s10, v255, 19
	v_ashrrev_i32_e32 v157, 31, v156
	v_lshl_add_u64 v[130:131], s[14:15], 0, v[154:155]
	s_mov_b64 s[14:15], 0x2000
	s_cselect_b32 s12, s7, s10
	v_lshlrev_b64 v[208:209], 12, v[156:157]
	v_lshl_add_u64 v[132:133], v[130:131], 0, s[14:15]
	v_add_co_u32_e32 v130, vcc, s71, v130
	v_lshl_add_u64 v[156:157], s[12:13], 0, v[208:209]
	s_nop 0
	v_addc_co_u32_e32 v131, vcc, 0, v131, vcc
	v_lshl_add_u64 v[156:157], v[156:157], 0, v[154:155]
	v_add_co_u32_e32 v192, vcc, s45, v156
	global_load_dwordx4 v[138:141], v[132:133], off offset:64
	global_load_dwordx4 v[134:137], v[132:133], off offset:512
	global_load_dwordx4 v[142:145], v[130:131], off
	s_nop 0
	global_load_dwordx4 v[130:133], v[132:133], off offset:576
	v_addc_co_u32_e32 v193, vcc, 0, v157, vcc
	v_add_co_u32_e32 v226, vcc, s19, v156
	global_load_dwordx4 v[162:165], v[156:157], off
	global_load_dwordx4 v[166:169], v[156:157], off offset:64
	global_load_dwordx4 v[170:173], v[156:157], off offset:512
	global_load_dwordx4 v[174:177], v[156:157], off offset:576
	v_addc_co_u32_e32 v227, vcc, 0, v157, vcc
	v_add_co_u32_e32 v242, vcc, s69, v156
	global_load_dwordx4 v[180:183], v[192:193], off
	global_load_dwordx4 v[184:187], v[192:193], off offset:64
	global_load_dwordx4 v[188:191], v[192:193], off offset:512
	s_nop 0
	global_load_dwordx4 v[192:195], v[192:193], off offset:576
	v_addc_co_u32_e32 v243, vcc, 0, v157, vcc
	global_load_dwordx4 v[196:199], v[226:227], off
	global_load_dwordx4 v[200:203], v[226:227], off offset:64
	global_load_dwordx4 v[204:207], v[226:227], off offset:512
	s_nop 0
	global_load_dwordx4 v[226:229], v[226:227], off offset:576
	s_nop 0
	global_load_dwordx4 v[230:233], v[242:243], off
	global_load_dwordx4 v[234:237], v[242:243], off offset:64
	global_load_dwordx4 v[238:241], v[242:243], off offset:512
	s_nop 0
	global_load_dwordx4 v[242:245], v[242:243], off offset:576
	v_readlane_b32 s12, v254, 0
	v_readlane_b32 s13, v254, 1
	s_waitcnt vmcnt(0)
;     __device__ __forceinline__ void operator()(const AccT& acc, const Unit& u, int wr, int wc, int fr, int fq) const {
;     ...
;                     for (int n = 0; n < 2; ++n) xo[m][bj][n] = *(const f32x4*)(sbase + (size_t)(ai * 128 + m * 16) * 1024 + bj * 128 + n * 16);
;             __builtin_amdgcn_sched_barrier(0);
; #pragma unroll
;             for (int m = 0; m < 4; ++m) { float* rowp = X + (size_t)(row0 + ai * 128 + m * 16) * 1024 + col0;
; #pragma unroll
;                 for (int bj = 0; bj < 2; ++bj)
; #pragma unroll
;                     for (int n = 0; n < 2; ++n) *(f32x4*)(rowp + bj * 128 + n * 16) = xo[m][bj][n] + gv[bj][n] * acc[ai][bj][m][n]; }
	v_pk_fma_f32 v[112:113], v[112:113], v[132:133], v[176:177]
	v_pk_fma_f32 v[110:111], v[110:111], v[130:131], v[174:175]
	v_lshl_add_u64 v[208:209], s[12:13], 0, v[208:209]
	v_lshl_add_u64 v[154:155], v[208:209], 0, v[154:155]
	v_pk_fma_f32 v[120:121], v[120:121], v[136:137], v[172:173]
	v_pk_fma_f32 v[118:119], v[118:119], v[134:135], v[170:171]
	global_store_dwordx4 v[154:155], v[110:113], off offset:576
	global_store_dwordx4 v[154:155], v[118:121], off offset:512
	v_pk_fma_f32 v[100:101], v[100:101], v[136:137], v[190:191]
	v_pk_fma_f32 v[110:111], v[114:115], v[142:143], v[180:181]
	v_add_co_u32_e32 v114, vcc, s45, v154
	v_lshl_add_u64 v[118:119], v[154:155], 0, s[84:85]
	s_nop 0
	v_addc_co_u32_e32 v115, vcc, 0, v155, vcc
	v_pk_fma_f32 v[98:99], v[98:99], v[134:135], v[188:189]
	global_store_dwordx4 v[118:119], v[98:101], off offset:512
	v_pk_fma_f32 v[84:85], v[84:85], v[136:137], v[206:207]
	v_pk_fma_f32 v[82:83], v[82:83], v[134:135], v[204:205]
	v_add_co_u32_e32 v100, vcc, s19, v154
	v_lshl_add_u64 v[98:99], v[154:155], 0, s[82:83]
	s_nop 0
	v_addc_co_u32_e32 v101, vcc, 0, v155, vcc
	v_pk_fma_f32 v[96:97], v[96:97], v[132:133], v[194:195]
	v_pk_fma_f32 v[94:95], v[94:95], v[130:131], v[192:193]
	global_store_dwordx4 v[98:99], v[82:85], off offset:512
	v_pk_fma_f32 v[80:81], v[80:81], v[132:133], v[228:229]
	v_pk_fma_f32 v[78:79], v[78:79], v[130:131], v[226:227]
	s_mov_b64 s[12:13], 0x30000
	v_add_co_u32_e32 v84, vcc, s69, v154
	v_pk_fma_f32 v[128:129], v[128:129], v[144:145], v[164:165]
	v_pk_fma_f32 v[126:127], v[126:127], v[142:143], v[162:163]
	v_pk_fma_f32 v[124:125], v[124:125], v[140:141], v[168:169]
	v_pk_fma_f32 v[122:123], v[122:123], v[138:139], v[166:167]
	v_pk_fma_f32 v[112:113], v[116:117], v[144:145], v[182:183]
	v_pk_fma_f32 v[108:109], v[108:109], v[140:141], v[186:187]
	v_pk_fma_f32 v[106:107], v[106:107], v[138:139], v[184:185]
	global_store_dwordx4 v[118:119], v[94:97], off offset:576
	v_pk_fma_f32 v[92:93], v[92:93], v[140:141], v[202:203]
	v_pk_fma_f32 v[90:91], v[90:91], v[138:139], v[200:201]
	v_pk_fma_f32 v[96:97], v[104:105], v[144:145], v[198:199]
	v_pk_fma_f32 v[94:95], v[102:103], v[142:143], v[196:197]
	global_store_dwordx4 v[98:99], v[78:81], off offset:576
	v_lshl_add_u64 v[82:83], v[154:155], 0, s[12:13]
	v_addc_co_u32_e32 v85, vcc, 0, v155, vcc
	v_pk_fma_f32 v[80:81], v[88:89], v[144:145], v[232:233]
	v_pk_fma_f32 v[78:79], v[86:87], v[142:143], v[230:231]
	v_pk_fma_f32 v[76:77], v[76:77], v[140:141], v[236:237]
	v_pk_fma_f32 v[74:75], v[74:75], v[138:139], v[234:235]
	v_pk_fma_f32 v[72:73], v[72:73], v[136:137], v[240:241]
	v_pk_fma_f32 v[70:71], v[70:71], v[134:135], v[238:239]
	v_pk_fma_f32 v[68:69], v[68:69], v[132:133], v[244:245]
	v_pk_fma_f32 v[66:67], v[66:67], v[130:131], v[242:243]
	global_store_dwordx4 v[154:155], v[126:129], off
	global_store_dwordx4 v[154:155], v[122:125], off offset:64
	global_store_dwordx4 v[114:115], v[110:113], off
	global_store_dwordx4 v[118:119], v[106:109], off offset:64
	global_store_dwordx4 v[100:101], v[94:97], off
	global_store_dwordx4 v[98:99], v[90:93], off offset:64
	global_store_dwordx4 v[84:85], v[78:81], off
	global_store_dwordx4 v[82:83], v[74:77], off offset:64
	global_store_dwordx4 v[82:83], v[70:73], off offset:512
	global_store_dwordx4 v[82:83], v[66:69], off offset:576
	s_mov_b32 s7, 0x80000
	v_add_co_u32_e32 v78, vcc, s7, v156
	s_mov_b32 s10, 0x90000
	s_nop 0
	v_addc_co_u32_e32 v79, vcc, 0, v157, vcc
	v_add_co_u32_e32 v94, vcc, s10, v156
	s_mov_b32 s12, 0xa0000
	s_nop 0
	v_addc_co_u32_e32 v95, vcc, 0, v157, vcc
	v_add_co_u32_e32 v110, vcc, s12, v156
	s_mov_b32 s13, 0xb0000
	s_nop 0
	v_addc_co_u32_e32 v111, vcc, 0, v157, vcc
	v_add_co_u32_e32 v126, vcc, s13, v156
	global_load_dwordx4 v[66:69], v[78:79], off
	global_load_dwordx4 v[70:73], v[78:79], off offset:64
	global_load_dwordx4 v[74:77], v[78:79], off offset:512
	s_nop 0
	global_load_dwordx4 v[78:81], v[78:79], off offset:576
	v_addc_co_u32_e32 v127, vcc, 0, v157, vcc
	global_load_dwordx4 v[82:85], v[94:95], off
	global_load_dwordx4 v[86:89], v[94:95], off offset:64
	global_load_dwordx4 v[90:93], v[94:95], off offset:512
	s_nop 0
	global_load_dwordx4 v[94:97], v[94:95], off offset:576
	s_nop 0
	global_load_dwordx4 v[98:101], v[110:111], off
	global_load_dwordx4 v[102:105], v[110:111], off offset:64
	global_load_dwordx4 v[106:109], v[110:111], off offset:512
	s_nop 0
	global_load_dwordx4 v[110:113], v[110:111], off offset:576
	s_nop 0
	global_load_dwordx4 v[114:117], v[126:127], off
	global_load_dwordx4 v[118:121], v[126:127], off offset:64
	global_load_dwordx4 v[122:125], v[126:127], off offset:512
	s_nop 0
	global_load_dwordx4 v[126:129], v[126:127], off offset:576
	s_mov_b64 s[14:15], 0x80000
	s_waitcnt vmcnt(0)
; template <class Epi>
; __device__ __forceinline__ void gemm_phase(LAS unsigned char* lds, const Gemm g, const Epi& E) {
;     ...
;         E(acc, cur, wr, wc, fr, fq);
;         if (!has_next) break;
; #pragma unroll
;         for (int a = 0; a < 2; ++a)
; #pragma unroll
;             for (int b = 0; b < 2; ++b)
; #pragma unroll
;                 for (int m = 0; m < 4; ++m)
; #pragma unroll
;                     for (int n = 0; n < 2; ++n) acc[a][b][m][n] = (f32x4){0.f, 0.f, 0.f, 0.f};
;         cur = nxt; cA = nA; cB = nB; ++ui;
;     }
;     __device__ __forceinline__ void operator()(const AccT& acc, const Unit& u, int wr, int wc, int fr, int fq) const {
;     ...
;             for (int m = 0; m < 4; ++m) { float* rowp = X + (size_t)(row0 + ai * 128 + m * 16) * 1024 + col0;
; #pragma unroll
;                 for (int bj = 0; bj < 2; ++bj)
; #pragma unroll
;                     for (int n = 0; n < 2; ++n) *(f32x4*)(rowp + bj * 128 + n * 16) = xo[m][bj][n] + gv[bj][n] * acc[ai][bj][m][n]; }
	v_pk_fma_f32 v[62:63], v[62:63], v[142:143], v[66:67]
	v_add_co_u32_e32 v66, vcc, s7, v154
	v_lshl_add_u64 v[156:157], v[154:155], 0, s[14:15]
	s_nop 0
	v_addc_co_u32_e32 v67, vcc, 0, v155, vcc
	v_pk_fma_f32 v[52:53], v[52:53], v[136:137], v[76:77]
	v_pk_fma_f32 v[50:51], v[50:51], v[134:135], v[74:75]
	global_store_dwordx4 v[156:157], v[50:53], off offset:512
	s_mov_b64 s[14:15], 0x90000
	v_pk_fma_f32 v[36:37], v[36:37], v[136:137], v[92:93]
	v_add_co_u32_e32 v52, vcc, s10, v154
	v_lshl_add_u64 v[50:51], v[154:155], 0, s[14:15]
	s_nop 0
	v_addc_co_u32_e32 v53, vcc, 0, v155, vcc
	v_pk_fma_f32 v[34:35], v[34:35], v[134:135], v[90:91]
	global_store_dwordx4 v[50:51], v[34:37], off offset:512
	s_mov_b64 s[14:15], 0xa0000
	v_pk_fma_f32 v[20:21], v[20:21], v[136:137], v[108:109]
	v_add_co_u32_e32 v36, vcc, s12, v154
	v_lshl_add_u64 v[34:35], v[154:155], 0, s[14:15]
	s_nop 0
	v_addc_co_u32_e32 v37, vcc, 0, v155, vcc
	v_pk_fma_f32 v[18:19], v[18:19], v[134:135], v[106:107]
	v_pk_fma_f32 v[48:49], v[48:49], v[132:133], v[80:81]
	v_pk_fma_f32 v[46:47], v[46:47], v[130:131], v[78:79]
	v_pk_fma_f32 v[32:33], v[32:33], v[132:133], v[96:97]
	v_pk_fma_f32 v[30:31], v[30:31], v[130:131], v[94:95]
	global_store_dwordx4 v[34:35], v[18:21], off offset:512
	v_pk_fma_f32 v[16:17], v[16:17], v[132:133], v[112:113]
	v_pk_fma_f32 v[14:15], v[14:15], v[130:131], v[110:111]
	s_mov_b64 s[14:15], 0xb0000
	v_add_co_u32_e32 v20, vcc, s13, v154
	v_pk_fma_f32 v[64:65], v[64:65], v[144:145], v[68:69]
	v_pk_fma_f32 v[60:61], v[60:61], v[140:141], v[72:73]
	v_pk_fma_f32 v[58:59], v[58:59], v[138:139], v[70:71]
	global_store_dwordx4 v[156:157], v[46:49], off offset:576
	v_pk_fma_f32 v[44:45], v[44:45], v[140:141], v[88:89]
	v_pk_fma_f32 v[42:43], v[42:43], v[138:139], v[86:87]
	v_pk_fma_f32 v[48:49], v[56:57], v[144:145], v[84:85]
	v_pk_fma_f32 v[46:47], v[54:55], v[142:143], v[82:83]
	global_store_dwordx4 v[50:51], v[30:33], off offset:576
	v_pk_fma_f32 v[28:29], v[28:29], v[140:141], v[104:105]
	v_pk_fma_f32 v[26:27], v[26:27], v[138:139], v[102:103]
	v_pk_fma_f32 v[32:33], v[40:41], v[144:145], v[100:101]
	v_pk_fma_f32 v[30:31], v[38:39], v[142:143], v[98:99]
	global_store_dwordx4 v[34:35], v[14:17], off offset:576
	v_lshl_add_u64 v[18:19], v[154:155], 0, s[14:15]
	v_addc_co_u32_e32 v21, vcc, 0, v155, vcc
	v_pk_fma_f32 v[16:17], v[24:25], v[144:145], v[116:117]
	v_pk_fma_f32 v[14:15], v[22:23], v[142:143], v[114:115]
	v_pk_fma_f32 v[12:13], v[12:13], v[140:141], v[120:121]
	v_pk_fma_f32 v[10:11], v[10:11], v[138:139], v[118:119]
	v_pk_fma_f32 v[8:9], v[8:9], v[136:137], v[124:125]
	v_pk_fma_f32 v[6:7], v[6:7], v[134:135], v[122:123]
	v_pk_fma_f32 v[4:5], v[4:5], v[132:133], v[128:129]
	v_pk_fma_f32 v[2:3], v[2:3], v[130:131], v[126:127]
	global_store_dwordx4 v[66:67], v[62:65], off
	global_store_dwordx4 v[156:157], v[58:61], off offset:64
	global_store_dwordx4 v[52:53], v[46:49], off
	global_store_dwordx4 v[50:51], v[42:45], off offset:64
	global_store_dwordx4 v[36:37], v[30:33], off
	global_store_dwordx4 v[34:35], v[26:29], off offset:64
	global_store_dwordx4 v[20:21], v[14:17], off
	global_store_dwordx4 v[18:19], v[10:13], off offset:64
	global_store_dwordx4 v[18:19], v[6:9], off offset:512
	global_store_dwordx4 v[18:19], v[2:5], off offset:576
	s_and_b64 vcc, exec, s[2:3]
	s_mov_b32 s10, s6
	s_mov_b32 s61, s60
	s_mov_b64 s[14:15], s[4:5]
	s_mov_b64 s[12:13], s[8:9]
	s_cbranch_vccz .LBB0_490
	s_waitcnt vmcnt(0)
	s_cmpk_gt_u32 s1, 0xff
	s_cbranch_scc1 .LBB0_499
	s_barrier

; #define PG8_STAGE(bufoff, gbase, voff) do { _Pragma("unroll") for (int _i = 0; _i < 2; ++_i) \
;         __builtin_amdgcn_global_load_lds((const unsigned*)((const char*)(gbase) + (voff)[_i]), (LAS unsigned*)(lds + (bufoff) + ldsw + _i * 8192), 16, 0, 0); } while (0)
; #define PG8_LDA(dst, b, h) do { _Pragma("unroll") for (int m = 0; m < 4; ++m) _Pragma("unroll") for (int k = 0; k < 2; ++k) dst[m][k] = *(const LAS bf16x8*)(lds + PG8_SA(b, h) + aoff + m * 2048 + k * 1024); } while (0)
; #define PG8_LDB(dst, b, h) do { _Pragma("unroll") for (int n = 0; n < 2; ++n) _Pragma("unroll") for (int k = 0; k < 2; ++k) dst[n][k] = *(const LAS bf16x8*)(lds + PG8_SB(b, h) + boff + n * 2048 + k * 1024); } while (0)
; #define PG8_MMA(ai, bj, At, Bt) do { __builtin_amdgcn_s_setprio(1); _Pragma("unroll") for (int m = 0; m < 4; ++m) _Pragma("unroll") for (int n = 0; n < 2; ++n) _Pragma("unroll") for (int k = 0; k < 2; ++k) \
;         acc[ai][bj][m][n] = __builtin_amdgcn_mfma_f32_16x16x32_bf16(Bt[n][k], At[m][k], acc[ai][bj][m][n], 0, 0, 0); __builtin_amdgcn_s_setprio(0); } while (0)
; #define PG8_WAIT_L(n) asm volatile("s_waitcnt lgkmcnt(" #n ")" ::: "memory")
; #define PG8_BAR __builtin_amdgcn_s_barrier()
; #define PG8_SCHED __builtin_amdgcn_sched_barrier(0)
; template <class Epi>
; __device__ __forceinline__ void gemm_phase(LAS unsigned char* lds, const Gemm g, const Epi& E) {
;     ...
;         for (int t = 0; t < nt; t += 2) {
;             const bool last = (t == nt - 2);
;             const char* a1 = cA + (size_t)(t + 1) * kstep;
;             const char* a2 = last ? nA : cA + (size_t)(t + 2) * kstep; const char* b2 = last ? nB : cB + (size_t)(t + 2) * kstep;
;             const char* a3 = a2 + kstep; const char* b3 = b2 + kstep;
;             PG8_LDB(B0, 0, 0); PG8_SCHED; PG8_LDA(At, 0, 0); PG8_STAGE(PG8_SA(1, 1), a1 + hstepA, voffA);
;             PG8_WAIT_L(8); PG8_BAR; PG8_WAIT_L(0); PG8_MMA(0, 0, At, B0); PG8_BAR; PG8_SCHED;
;             PG8_LDB(B1, 0, 1); PG8_STAGE(PG8_SB(0, 0), b2, voffB);
;             PG8_BAR; PG8_WAIT_L(0); PG8_MMA(0, 1, At, B1); PG8_BAR;
;             PG8_LDA(At, 0, 1); PG8_STAGE(PG8_SA(0, 0), a2, voffA);
;             PG8_BAR; PG8_WAIT_L(0); PG8_MMA(1, 0, At, B0); PG8_BAR; PG8_SCHED;
.LBB0_525:
	s_add_u32 s14, s12, 0xfffc0080
	s_addc_u32 s15, s13, -1
	s_add_i32 s26, 0, 0x10000
	v_add_u32_e32 v149, s26, v147
	ds_read_b128 v[142:145], v149
	ds_read_b128 v[150:153], v149 offset:1024
	ds_read_b128 v[154:157], v149 offset:2048
	ds_read_b128 v[158:161], v149 offset:3072
	s_cmp_eq_u32 s66, 12
	s_cselect_b32 s17, s9, s15
	s_cselect_b32 s16, s8, s14
	s_cselect_b32 s15, s5, s65
	s_cselect_b32 s14, s4, s7
	v_lshl_add_u64 v[196:197], s[12:13], 0, v[138:139]
	s_add_i32 m0, s11, 0xc000
	ds_read_b128 v[162:165], v148
	ds_read_b128 v[166:169], v148 offset:1024
	ds_read_b128 v[170:173], v148 offset:2048
	ds_read_b128 v[174:177], v148 offset:3072
	ds_read_b128 v[180:183], v148 offset:4096
	ds_read_b128 v[184:187], v148 offset:5120
	ds_read_b128 v[188:191], v148 offset:6144
	ds_read_b128 v[192:195], v148 offset:7168
	global_load_lds_dwordx4 v[196:197], off
	v_lshl_add_u64 v[196:197], s[12:13], 0, v[140:141]
	s_add_i32 m0, s11, 0xe000
	s_nop 0
	global_load_lds_dwordx4 v[196:197], off
	s_waitcnt lgkmcnt(8)
	s_barrier
	s_waitcnt lgkmcnt(0)
	v_mfma_f32_16x16x32_bf16 v[126:129], v[142:145], v[162:165], v[126:129]
	v_mfma_f32_16x16x32_bf16 v[118:121], v[154:157], v[162:165], v[118:121]
	v_mfma_f32_16x16x32_bf16 v[110:113], v[142:145], v[170:173], v[110:113]
	v_mfma_f32_16x16x32_bf16 v[102:105], v[154:157], v[170:173], v[102:105]
	v_mfma_f32_16x16x32_bf16 v[94:97], v[142:145], v[180:183], v[94:97]
	v_mfma_f32_16x16x32_bf16 v[86:89], v[154:157], v[180:183], v[86:89]
	v_mfma_f32_16x16x32_bf16 v[78:81], v[142:145], v[188:191], v[78:81]
	v_mfma_f32_16x16x32_bf16 v[70:73], v[154:157], v[188:191], v[70:73]
	v_mfma_f32_16x16x32_bf16 v[126:129], v[150:153], v[166:169], v[126:129]
	v_mfma_f32_16x16x32_bf16 v[118:121], v[158:161], v[166:169], v[118:121]
	v_mfma_f32_16x16x32_bf16 v[110:113], v[150:153], v[174:177], v[110:113]
	v_mfma_f32_16x16x32_bf16 v[102:105], v[158:161], v[174:177], v[102:105]
	v_mfma_f32_16x16x32_bf16 v[94:97], v[150:153], v[184:187], v[94:97]
	v_mfma_f32_16x16x32_bf16 v[86:89], v[158:161], v[184:187], v[86:89]
	v_mfma_f32_16x16x32_bf16 v[78:81], v[150:153], v[192:195], v[78:81]
	v_mfma_f32_16x16x32_bf16 v[70:73], v[158:161], v[192:195], v[70:73]
	s_barrier
	s_add_i32 s27, 0, 0x14000
	s_add_i32 s26, s26, s25
	v_add_u32_e32 v149, s27, v147
	v_lshl_add_u64 v[208:209], s[14:15], 0, v[134:135]
	s_mov_b32 m0, s26
	ds_read_b128 v[196:199], v149
	ds_read_b128 v[200:203], v149 offset:1024
	ds_read_b128 v[204:207], v149 offset:2048
	ds_read_b128 v[226:229], v149 offset:3072
	global_load_lds_dwordx4 v[208:209], off
	v_lshl_add_u64 v[230:231], s[14:15], 0, v[130:131]
	s_add_i32 m0, s26, 0x2000
	s_nop 0
	global_load_lds_dwordx4 v[230:231], off
	s_nop 1
	s_mov_b32 m0, s11
	v_lshl_add_u64 v[232:233], s[16:17], 0, v[136:137]
	s_barrier
	s_waitcnt lgkmcnt(0)
	v_mfma_f32_16x16x32_bf16 v[122:125], v[196:199], v[162:165], v[122:125]
	v_mfma_f32_16x16x32_bf16 v[114:117], v[204:207], v[162:165], v[114:117]
	v_mfma_f32_16x16x32_bf16 v[106:109], v[196:199], v[170:173], v[106:109]
	v_mfma_f32_16x16x32_bf16 v[98:101], v[204:207], v[170:173], v[98:101]
	v_mfma_f32_16x16x32_bf16 v[90:93], v[196:199], v[180:183], v[90:93]
	v_mfma_f32_16x16x32_bf16 v[82:85], v[204:207], v[180:183], v[82:85]
	v_mfma_f32_16x16x32_bf16 v[74:77], v[196:199], v[188:191], v[74:77]
	v_mfma_f32_16x16x32_bf16 v[66:69], v[204:207], v[188:191], v[66:69]
	v_mfma_f32_16x16x32_bf16 v[122:125], v[200:203], v[166:169], v[122:125]
	v_mfma_f32_16x16x32_bf16 v[114:117], v[226:229], v[166:169], v[114:117]
	v_mfma_f32_16x16x32_bf16 v[106:109], v[200:203], v[174:177], v[106:109]
	v_mfma_f32_16x16x32_bf16 v[98:101], v[226:229], v[174:177], v[98:101]
	v_mfma_f32_16x16x32_bf16 v[90:93], v[200:203], v[184:187], v[90:93]
	v_mfma_f32_16x16x32_bf16 v[82:85], v[226:229], v[184:187], v[82:85]
	v_mfma_f32_16x16x32_bf16 v[74:77], v[200:203], v[192:195], v[74:77]
	v_mfma_f32_16x16x32_bf16 v[66:69], v[226:229], v[192:195], v[66:69]
	s_barrier
	ds_read_b128 v[162:165], v148 offset:16384
	ds_read_b128 v[166:169], v148 offset:17408
	ds_read_b128 v[170:173], v148 offset:18432
	ds_read_b128 v[174:177], v148 offset:19456
	ds_read_b128 v[180:183], v148 offset:20480
	ds_read_b128 v[184:187], v148 offset:21504
	ds_read_b128 v[188:191], v148 offset:22528
	ds_read_b128 v[192:195], v148 offset:23552
	global_load_lds_dwordx4 v[232:233], off
	v_lshl_add_u64 v[234:235], s[16:17], 0, v[132:133]
	s_mov_b32 m0, s36
	s_nop 0
	global_load_lds_dwordx4 v[234:235], off
	s_barrier
	s_waitcnt lgkmcnt(0)
	v_mfma_f32_16x16x32_bf16 v[62:65], v[142:145], v[162:165], v[62:65]
	v_mfma_f32_16x16x32_bf16 v[54:57], v[154:157], v[162:165], v[54:57]
	v_mfma_f32_16x16x32_bf16 v[46:49], v[142:145], v[170:173], v[46:49]
	v_mfma_f32_16x16x32_bf16 v[38:41], v[154:157], v[170:173], v[38:41]
	v_mfma_f32_16x16x32_bf16 v[30:33], v[142:145], v[180:183], v[30:33]
	v_mfma_f32_16x16x32_bf16 v[22:25], v[154:157], v[180:183], v[22:25]
	v_mfma_f32_16x16x32_bf16 v[14:17], v[142:145], v[188:191], v[14:17]
	v_mfma_f32_16x16x32_bf16 v[6:9], v[154:157], v[188:191], v[6:9]
	v_mfma_f32_16x16x32_bf16 v[62:65], v[150:153], v[166:169], v[62:65]
	v_mfma_f32_16x16x32_bf16 v[54:57], v[158:161], v[166:169], v[54:57]
	v_mfma_f32_16x16x32_bf16 v[46:49], v[150:153], v[174:177], v[46:49]
	v_mfma_f32_16x16x32_bf16 v[38:41], v[158:161], v[174:177], v[38:41]
	v_mfma_f32_16x16x32_bf16 v[30:33], v[150:153], v[184:187], v[30:33]
	v_mfma_f32_16x16x32_bf16 v[22:25], v[158:161], v[184:187], v[22:25]
	v_mfma_f32_16x16x32_bf16 v[14:17], v[150:153], v[192:195], v[14:17]
	v_mfma_f32_16x16x32_bf16 v[6:9], v[158:161], v[192:195], v[6:9]
	s_barrier
; #define PG8_STAGE(bufoff, gbase, voff) do { _Pragma("unroll") for (int _i = 0; _i < 2; ++_i) \
;         __builtin_amdgcn_global_load_lds((const unsigned*)((const char*)(gbase) + (voff)[_i]), (LAS unsigned*)(lds + (bufoff) + ldsw + _i * 8192), 16, 0, 0); } while (0)
; #define PG8_LDA(dst, b, h) do { _Pragma("unroll") for (int m = 0; m < 4; ++m) _Pragma("unroll") for (int k = 0; k < 2; ++k) dst[m][k] = *(const LAS bf16x8*)(lds + PG8_SA(b, h) + aoff + m * 2048 + k * 1024); } while (0)
; #define PG8_LDB(dst, b, h) do { _Pragma("unroll") for (int n = 0; n < 2; ++n) _Pragma("unroll") for (int k = 0; k < 2; ++k) dst[n][k] = *(const LAS bf16x8*)(lds + PG8_SB(b, h) + boff + n * 2048 + k * 1024); } while (0)
; #define PG8_MMA(ai, bj, At, Bt) do { __builtin_amdgcn_s_setprio(1); _Pragma("unroll") for (int m = 0; m < 4; ++m) _Pragma("unroll") for (int n = 0; n < 2; ++n) _Pragma("unroll") for (int k = 0; k < 2; ++k) \
;         acc[ai][bj][m][n] = __builtin_amdgcn_mfma_f32_16x16x32_bf16(Bt[n][k], At[m][k], acc[ai][bj][m][n], 0, 0, 0); __builtin_amdgcn_s_setprio(0); } while (0)
; #define PG8_WAIT_V(n) asm volatile("s_waitcnt vmcnt(" #n ")" ::: "memory")
; #define PG8_WAIT_L(n) asm volatile("s_waitcnt lgkmcnt(" #n ")" ::: "memory")
; #define PG8_BAR __builtin_amdgcn_s_barrier()
; #define PG8_SCHED __builtin_amdgcn_sched_barrier(0)
; template <class Epi>
; __device__ __forceinline__ void gemm_phase(LAS unsigned char* lds, const Gemm g, const Epi& E) {
;     ...
;             PG8_STAGE(PG8_SB(0, 1), b2 + hstepB, voffB);
;             PG8_WAIT_V(6); PG8_BAR; PG8_MMA(1, 1, At, B1); PG8_BAR;
;             PG8_LDB(B0, 1, 0); PG8_SCHED; PG8_LDA(At, 1, 0); PG8_STAGE(PG8_SA(0, 1), a2 + hstepA, voffA);
;             PG8_WAIT_L(8); PG8_BAR; PG8_WAIT_L(0); PG8_MMA(0, 0, At, B0); PG8_BAR; PG8_SCHED;
;             PG8_LDB(B1, 1, 1); PG8_STAGE(PG8_SB(1, 0), b3, voffB);
;             PG8_BAR; PG8_WAIT_L(0); PG8_MMA(0, 1, At, B1); PG8_BAR;
;             PG8_LDA(At, 1, 1); PG8_STAGE(PG8_SA(1, 0), a3, voffA);
	s_add_u32 s68, s14, 0x40000
	s_addc_u32 s69, s15, 0
	s_add_i32 s26, s27, s25
	v_lshl_add_u64 v[142:143], s[68:69], 0, v[134:135]
	s_mov_b32 m0, s26
	s_nop 0
	global_load_lds_dwordx4 v[142:143], off
	v_lshl_add_u64 v[142:143], s[68:69], 0, v[130:131]
	s_add_i32 m0, s26, 0x2000
	s_nop 0
	global_load_lds_dwordx4 v[142:143], off
	s_add_i32 s26, 0, 0x18000
	v_add_u32_e32 v149, s26, v147
	s_waitcnt vmcnt(6)
	s_barrier
	v_mfma_f32_16x16x32_bf16 v[58:61], v[196:199], v[162:165], v[58:61]
	v_mfma_f32_16x16x32_bf16 v[50:53], v[204:207], v[162:165], v[50:53]
	v_mfma_f32_16x16x32_bf16 v[42:45], v[196:199], v[170:173], v[42:45]
	v_mfma_f32_16x16x32_bf16 v[34:37], v[204:207], v[170:173], v[34:37]
	v_mfma_f32_16x16x32_bf16 v[26:29], v[196:199], v[180:183], v[26:29]
	v_mfma_f32_16x16x32_bf16 v[18:21], v[204:207], v[180:183], v[18:21]
	v_mfma_f32_16x16x32_bf16 v[10:13], v[196:199], v[188:191], v[10:13]
	v_mfma_f32_16x16x32_bf16 v[2:5], v[204:207], v[188:191], v[2:5]
	v_mfma_f32_16x16x32_bf16 v[58:61], v[200:203], v[166:169], v[58:61]
	v_mfma_f32_16x16x32_bf16 v[50:53], v[226:229], v[166:169], v[50:53]
	v_mfma_f32_16x16x32_bf16 v[42:45], v[200:203], v[174:177], v[42:45]
	v_mfma_f32_16x16x32_bf16 v[34:37], v[226:229], v[174:177], v[34:37]
	v_mfma_f32_16x16x32_bf16 v[26:29], v[200:203], v[184:187], v[26:29]
	v_mfma_f32_16x16x32_bf16 v[18:21], v[226:229], v[184:187], v[18:21]
	v_mfma_f32_16x16x32_bf16 v[10:13], v[200:203], v[192:195], v[10:13]
	v_mfma_f32_16x16x32_bf16 v[2:5], v[226:229], v[192:195], v[2:5]
	s_barrier
	ds_read_b128 v[142:145], v149
	ds_read_b128 v[150:153], v149 offset:1024
	ds_read_b128 v[154:157], v149 offset:2048
	ds_read_b128 v[158:161], v149 offset:3072
	s_add_u32 s16, s16, 0x40000
	s_addc_u32 s17, s17, 0
	s_mov_b32 m0, s44
	v_lshl_add_u64 v[196:197], s[16:17], 0, v[136:137]
	ds_read_b128 v[162:165], v148 offset:32768
	ds_read_b128 v[166:169], v148 offset:33792
	ds_read_b128 v[170:173], v148 offset:34816
	ds_read_b128 v[174:177], v148 offset:35840
	ds_read_b128 v[180:183], v148 offset:36864
	ds_read_b128 v[184:187], v148 offset:37888
	ds_read_b128 v[188:191], v148 offset:38912
	ds_read_b128 v[192:195], v148 offset:39936
	global_load_lds_dwordx4 v[196:197], off
	v_lshl_add_u64 v[196:197], s[16:17], 0, v[132:133]
	s_mov_b32 m0, s50
	s_nop 0
	global_load_lds_dwordx4 v[196:197], off
	s_waitcnt lgkmcnt(8)
	s_barrier
	s_waitcnt lgkmcnt(0)
	v_mfma_f32_16x16x32_bf16 v[126:129], v[142:145], v[162:165], v[126:129]
	v_mfma_f32_16x16x32_bf16 v[118:121], v[154:157], v[162:165], v[118:121]
	v_mfma_f32_16x16x32_bf16 v[110:113], v[142:145], v[170:173], v[110:113]
	v_mfma_f32_16x16x32_bf16 v[102:105], v[154:157], v[170:173], v[102:105]
	v_mfma_f32_16x16x32_bf16 v[94:97], v[142:145], v[180:183], v[94:97]
	v_mfma_f32_16x16x32_bf16 v[86:89], v[154:157], v[180:183], v[86:89]
	v_mfma_f32_16x16x32_bf16 v[78:81], v[142:145], v[188:191], v[78:81]
	v_mfma_f32_16x16x32_bf16 v[70:73], v[154:157], v[188:191], v[70:73]
	v_mfma_f32_16x16x32_bf16 v[126:129], v[150:153], v[166:169], v[126:129]
	v_mfma_f32_16x16x32_bf16 v[118:121], v[158:161], v[166:169], v[118:121]
	v_mfma_f32_16x16x32_bf16 v[110:113], v[150:153], v[174:177], v[110:113]
	v_mfma_f32_16x16x32_bf16 v[102:105], v[158:161], v[174:177], v[102:105]
	v_mfma_f32_16x16x32_bf16 v[94:97], v[150:153], v[184:187], v[94:97]
	v_mfma_f32_16x16x32_bf16 v[86:89], v[158:161], v[184:187], v[86:89]
	v_mfma_f32_16x16x32_bf16 v[78:81], v[150:153], v[192:195], v[78:81]
	v_mfma_f32_16x16x32_bf16 v[70:73], v[158:161], v[192:195], v[70:73]
	s_barrier
	s_add_i32 s16, 0, 0x1c000
	s_add_i32 s17, s26, s25
	v_add_u32_e32 v149, s16, v147
	v_lshl_add_u64 v[208:209], v[208:209], 0, s[86:87]
	s_mov_b32 m0, s17
	ds_read_b128 v[196:199], v149
	ds_read_b128 v[200:203], v149 offset:1024
	ds_read_b128 v[204:207], v149 offset:2048
	ds_read_b128 v[226:229], v149 offset:3072
	global_load_lds_dwordx4 v[208:209], off
	v_lshl_add_u64 v[208:209], v[230:231], 0, s[86:87]
	s_add_i32 m0, s17, 0x2000
	s_nop 0
	global_load_lds_dwordx4 v[208:209], off
	s_nop 1
	s_mov_b32 m0, s58
	v_lshl_add_u64 v[208:209], v[232:233], 0, s[86:87]
	s_barrier
	s_waitcnt lgkmcnt(0)
	v_mfma_f32_16x16x32_bf16 v[122:125], v[196:199], v[162:165], v[122:125]
	v_mfma_f32_16x16x32_bf16 v[114:117], v[204:207], v[162:165], v[114:117]
	v_mfma_f32_16x16x32_bf16 v[106:109], v[196:199], v[170:173], v[106:109]
	v_mfma_f32_16x16x32_bf16 v[98:101], v[204:207], v[170:173], v[98:101]
	v_mfma_f32_16x16x32_bf16 v[90:93], v[196:199], v[180:183], v[90:93]
	v_mfma_f32_16x16x32_bf16 v[82:85], v[204:207], v[180:183], v[82:85]
	v_mfma_f32_16x16x32_bf16 v[74:77], v[196:199], v[188:191], v[74:77]
	v_mfma_f32_16x16x32_bf16 v[66:69], v[204:207], v[188:191], v[66:69]
	v_mfma_f32_16x16x32_bf16 v[122:125], v[200:203], v[166:169], v[122:125]
	v_mfma_f32_16x16x32_bf16 v[114:117], v[226:229], v[166:169], v[114:117]
	v_mfma_f32_16x16x32_bf16 v[106:109], v[200:203], v[174:177], v[106:109]
	v_mfma_f32_16x16x32_bf16 v[98:101], v[226:229], v[174:177], v[98:101]
	v_mfma_f32_16x16x32_bf16 v[90:93], v[200:203], v[184:187], v[90:93]
	v_mfma_f32_16x16x32_bf16 v[82:85], v[226:229], v[184:187], v[82:85]
	v_mfma_f32_16x16x32_bf16 v[74:77], v[200:203], v[192:195], v[74:77]
	v_mfma_f32_16x16x32_bf16 v[66:69], v[226:229], v[192:195], v[66:69]
	s_barrier
	ds_read_b128 v[162:165], v148 offset:49152
	ds_read_b128 v[166:169], v148 offset:50176
	ds_read_b128 v[170:173], v148 offset:51200
	ds_read_b128 v[174:177], v148 offset:52224
	ds_read_b128 v[180:183], v148 offset:53248
	ds_read_b128 v[184:187], v148 offset:54272
	ds_read_b128 v[188:191], v148 offset:55296
	ds_read_b128 v[192:195], v148 offset:56320
	global_load_lds_dwordx4 v[208:209], off
	v_lshl_add_u64 v[208:209], v[234:235], 0, s[86:87]
	s_mov_b32 m0, s59
	s_nop 0
	global_load_lds_dwordx4 v[208:209], off
	s_barrier
; __device__ __forceinline__ unsigned cvt_pk_bf16(float lo, float hi) { unsigned r; asm("v_cvt_pk_bf16_f32 %0, %1, %2" : "=v"(r) : "v"(lo), "v"(hi)); return r; }
; #define PG8_STAGE(bufoff, gbase, voff) do { _Pragma("unroll") for (int _i = 0; _i < 2; ++_i) \
;         __builtin_amdgcn_global_load_lds((const unsigned*)((const char*)(gbase) + (voff)[_i]), (LAS unsigned*)(lds + (bufoff) + ldsw + _i * 8192), 16, 0, 0); } while (0)
; #define PG8_MMA(ai, bj, At, Bt) do { __builtin_amdgcn_s_setprio(1); _Pragma("unroll") for (int m = 0; m < 4; ++m) _Pragma("unroll") for (int n = 0; n < 2; ++n) _Pragma("unroll") for (int k = 0; k < 2; ++k) \
;         acc[ai][bj][m][n] = __builtin_amdgcn_mfma_f32_16x16x32_bf16(Bt[n][k], At[m][k], acc[ai][bj][m][n], 0, 0, 0); __builtin_amdgcn_s_setprio(0); } while (0)
; #define PG8_WAIT_V(n) asm volatile("s_waitcnt vmcnt(" #n ")" ::: "memory")
; #define PG8_WAIT_L(n) asm volatile("s_waitcnt lgkmcnt(" #n ")" ::: "memory")
; #define PG8_BAR __builtin_amdgcn_s_barrier()
; #define PG8_SCHED __builtin_amdgcn_sched_barrier(0)
; template <class Epi>
; __device__ __forceinline__ void gemm_phase(LAS unsigned char* lds, const Gemm g, const Epi& E) {
;     ...
;             PG8_BAR; PG8_WAIT_L(0); PG8_MMA(1, 0, At, B0); PG8_BAR; PG8_SCHED;
;             PG8_STAGE(PG8_SB(1, 1), b3 + hstepB, voffB);
;             PG8_WAIT_V(6); PG8_BAR; PG8_MMA(1, 1, At, B1); PG8_BAR;
;     __device__ __forceinline__ void operator()(const AccT& acc, const Unit& u, int wr, int wc, int fr, int fq) const {
;     ...
;         const int gpm = mapA.src(u.pm);
;         const int row0 = gpm * 256 + wr * 64 + fr, col0 = u.pn * 128 + wc * 32 + 8 * fq;
; #pragma unroll
;         for (int ai = 0; ai < 2; ++ai)
; #pragma unroll
;             for (int m = 0; m < 4; ++m) { bf16_t* rowp = U + (size_t)(row0 + ai * 128 + m * 16) * HID + col0;
;                 const f32x4 s0 = silu4(acc[ai][0][m][0]) * acc[ai][1][m][0], s1 = silu4(acc[ai][0][m][1]) * acc[ai][1][m][1];
;                 u32x4 w; w.x = cvt_pk_bf16(s0[0], s0[1]); w.y = cvt_pk_bf16(s0[2], s0[3]); w.z = cvt_pk_bf16(s1[0], s1[1]); w.w = cvt_pk_bf16(s1[2], s1[3]);
;                 *(u32x4*)rowp = w; }
	s_waitcnt lgkmcnt(0)
	v_mfma_f32_16x16x32_bf16 v[62:65], v[142:145], v[162:165], v[62:65]
	v_mfma_f32_16x16x32_bf16 v[54:57], v[154:157], v[162:165], v[54:57]
	v_mfma_f32_16x16x32_bf16 v[46:49], v[142:145], v[170:173], v[46:49]
	v_mfma_f32_16x16x32_bf16 v[38:41], v[154:157], v[170:173], v[38:41]
	v_mfma_f32_16x16x32_bf16 v[30:33], v[142:145], v[180:183], v[30:33]
	v_mfma_f32_16x16x32_bf16 v[22:25], v[154:157], v[180:183], v[22:25]
	v_mfma_f32_16x16x32_bf16 v[14:17], v[142:145], v[188:191], v[14:17]
	v_mfma_f32_16x16x32_bf16 v[6:9], v[154:157], v[188:191], v[6:9]
	v_mfma_f32_16x16x32_bf16 v[62:65], v[150:153], v[166:169], v[62:65]
	v_mfma_f32_16x16x32_bf16 v[54:57], v[158:161], v[166:169], v[54:57]
	v_mfma_f32_16x16x32_bf16 v[46:49], v[150:153], v[174:177], v[46:49]
	v_mfma_f32_16x16x32_bf16 v[38:41], v[158:161], v[174:177], v[38:41]
	v_mfma_f32_16x16x32_bf16 v[30:33], v[150:153], v[184:187], v[30:33]
	v_mfma_f32_16x16x32_bf16 v[22:25], v[158:161], v[184:187], v[22:25]
	v_mfma_f32_16x16x32_bf16 v[14:17], v[150:153], v[192:195], v[14:17]
	v_mfma_f32_16x16x32_bf16 v[6:9], v[158:161], v[192:195], v[6:9]
	s_barrier
	s_add_u32 s14, s14, 0x40080
	s_addc_u32 s15, s15, 0
	s_add_i32 s16, s16, s25
	v_lshl_add_u64 v[142:143], s[14:15], 0, v[134:135]
	s_mov_b32 m0, s16
	s_nop 0
	global_load_lds_dwordx4 v[142:143], off
	v_lshl_add_u64 v[142:143], s[14:15], 0, v[130:131]
	s_add_i32 m0, s16, 0x2000
	s_nop 0
	global_load_lds_dwordx4 v[142:143], off
	s_add_i32 s66, s66, 2
	s_add_u32 s12, s12, 0x100
	s_addc_u32 s13, s13, 0
	s_add_u32 s7, s7, 0x100
	s_addc_u32 s65, s65, 0
	s_cmp_gt_u32 s66, 13
	s_waitcnt vmcnt(6)
	s_barrier
	v_mfma_f32_16x16x32_bf16 v[58:61], v[196:199], v[162:165], v[58:61]
	v_mfma_f32_16x16x32_bf16 v[50:53], v[204:207], v[162:165], v[50:53]
	v_mfma_f32_16x16x32_bf16 v[42:45], v[196:199], v[170:173], v[42:45]
	v_mfma_f32_16x16x32_bf16 v[34:37], v[204:207], v[170:173], v[34:37]
	v_mfma_f32_16x16x32_bf16 v[26:29], v[196:199], v[180:183], v[26:29]
	v_mfma_f32_16x16x32_bf16 v[18:21], v[204:207], v[180:183], v[18:21]
	v_mfma_f32_16x16x32_bf16 v[10:13], v[196:199], v[188:191], v[10:13]
	v_mfma_f32_16x16x32_bf16 v[2:5], v[204:207], v[188:191], v[2:5]
	v_mfma_f32_16x16x32_bf16 v[58:61], v[200:203], v[166:169], v[58:61]
	v_mfma_f32_16x16x32_bf16 v[50:53], v[226:229], v[166:169], v[50:53]
	v_mfma_f32_16x16x32_bf16 v[42:45], v[200:203], v[174:177], v[42:45]
	v_mfma_f32_16x16x32_bf16 v[34:37], v[226:229], v[174:177], v[34:37]
	v_mfma_f32_16x16x32_bf16 v[26:29], v[200:203], v[184:187], v[26:29]
	v_mfma_f32_16x16x32_bf16 v[18:21], v[226:229], v[184:187], v[18:21]
	v_mfma_f32_16x16x32_bf16 v[10:13], v[200:203], v[192:195], v[10:13]
	v_mfma_f32_16x16x32_bf16 v[2:5], v[226:229], v[192:195], v[2:5]
	s_barrier
	s_cbranch_scc0 .LBB0_525
	v_mul_f32_e32 v152, 0xbfb8aa3b, v126
	v_mul_f32_e32 v153, 0xbfb8aa3b, v127
	v_mul_f32_e32 v154, 0xbfb8aa3b, v128
	v_mul_f32_e32 v155, 0xbfb8aa3b, v129
	v_exp_f32_e32 v152, v152
	v_exp_f32_e32 v153, v153
	v_exp_f32_e32 v154, v154
	v_exp_f32_e32 v155, v155
	v_add_f32_e32 v152, 1.0, v152
	v_add_f32_e32 v153, 1.0, v153
	v_add_f32_e32 v154, 1.0, v154
	v_add_f32_e32 v155, 1.0, v155
	v_rcp_f32_e32 v152, v152
	v_rcp_f32_e32 v153, v153
	v_rcp_f32_e32 v154, v154
	v_rcp_f32_e32 v155, v155
	v_readlane_b32 s7, v255, 27
	v_pk_mul_f32 v[126:127], v[126:127], v[152:153]
	s_cmp_ge_i32 s64, s7
	v_pk_mul_f32 v[128:129], v[128:129], v[154:155]
	v_pk_mul_f32 v[122:123], v[126:127], v[122:123]
	v_pk_mul_f32 v[124:125], v[128:129], v[124:125]
	v_mul_f32_e32 v126, 0xbfb8aa3b, v118
	v_mul_f32_e32 v127, 0xbfb8aa3b, v119
	v_mul_f32_e32 v128, 0xbfb8aa3b, v120
	v_mul_f32_e32 v129, 0xbfb8aa3b, v121
	v_exp_f32_e32 v126, v126
	v_exp_f32_e32 v127, v127
	v_exp_f32_e32 v128, v128
	v_exp_f32_e32 v129, v129
	v_add_f32_e32 v126, 1.0, v126
	v_add_f32_e32 v127, 1.0, v127
	v_add_f32_e32 v128, 1.0, v128
	v_add_f32_e32 v129, 1.0, v129
	s_cselect_b32 s7, s31, 0
	v_rcp_f32_e32 v126, v126
	v_rcp_f32_e32 v127, v127
	v_rcp_f32_e32 v128, v128
	v_rcp_f32_e32 v129, v129
	s_add_i32 s7, s64, s7
	s_lshl_b32 s10, s10, 7
	v_mov_b32_e32 v142, v146
	v_mov_b32_e32 v143, v1
	s_lshl_b32 s7, s7, 8
	s_or_b32 s10, s10, s53
	s_add_i32 s7, s7, s52
	v_lshl_add_u32 v144, v143, 3, s10
	v_add_u32_e32 v149, s7, v142
	v_ashrrev_i32_e32 v145, 31, v144
	v_mov_b64_e32 v[142:143], s[34:35]
	s_movk_i32 s7, 0x1600
	v_pk_mul_f32 v[118:119], v[118:119], v[126:127]
	v_pk_mul_f32 v[120:121], v[120:121], v[128:129]
	v_mad_i64_i32 v[150:151], s[12:13], v149, s7, v[142:143]
	v_lshlrev_b64 v[144:145], 1, v[144:145]
	v_pk_mul_f32 v[120:121], v[120:121], v[116:117]
	v_pk_mul_f32 v[116:117], v[118:119], v[114:115]
	v_lshl_add_u64 v[150:151], v[150:151], 0, v[144:145]
	v_cvt_pk_bf16_f32 v116, v116, v117
	v_cvt_pk_bf16_f32 v117, v120, v121
	v_cvt_pk_bf16_f32 v114, v122, v123
	v_cvt_pk_bf16_f32 v115, v124, v125
	global_store_dwordx4 v[150:151], v[114:117], off
	v_mul_f32_e32 v118, 0xbfb8aa3b, v112
	v_mul_f32_e32 v119, 0xbfb8aa3b, v113
	v_mul_f32_e32 v116, 0xbfb8aa3b, v110
	v_mul_f32_e32 v117, 0xbfb8aa3b, v111
	v_exp_f32_e32 v116, v116
	v_exp_f32_e32 v117, v117
	v_exp_f32_e32 v118, v118
	v_exp_f32_e32 v119, v119
	v_add_f32_e32 v116, 1.0, v116
	v_add_f32_e32 v117, 1.0, v117
	v_add_f32_e32 v118, 1.0, v118
	v_add_f32_e32 v119, 1.0, v119
	v_rcp_f32_e32 v116, v116
	v_rcp_f32_e32 v117, v117
	v_rcp_f32_e32 v118, v118
	v_rcp_f32_e32 v119, v119
	v_add_u32_e32 v114, 16, v149
	v_pk_mul_f32 v[110:111], v[110:111], v[116:117]
	v_mad_i64_i32 v[114:115], s[12:13], v114, s7, v[142:143]
	v_pk_mul_f32 v[112:113], v[112:113], v[118:119]
	v_pk_mul_f32 v[106:107], v[110:111], v[106:107]
	v_pk_mul_f32 v[108:109], v[112:113], v[108:109]
; __device__ __forceinline__ unsigned cvt_pk_bf16(float lo, float hi) { unsigned r; asm("v_cvt_pk_bf16_f32 %0, %1, %2" : "=v"(r) : "v"(lo), "v"(hi)); return r; }
;     __device__ __forceinline__ void operator()(const AccT& acc, const Unit& u, int wr, int wc, int fr, int fq) const {
;     ...
; #pragma unroll
;         for (int ai = 0; ai < 2; ++ai)
; #pragma unroll
;             for (int m = 0; m < 4; ++m) { bf16_t* rowp = U + (size_t)(row0 + ai * 128 + m * 16) * HID + col0;
;                 const f32x4 s0 = silu4(acc[ai][0][m][0]) * acc[ai][1][m][0], s1 = silu4(acc[ai][0][m][1]) * acc[ai][1][m][1];
;                 u32x4 w; w.x = cvt_pk_bf16(s0[0], s0[1]); w.y = cvt_pk_bf16(s0[2], s0[3]); w.z = cvt_pk_bf16(s1[0], s1[1]); w.w = cvt_pk_bf16(s1[2], s1[3]);
;                 *(u32x4*)rowp = w; }
	v_mul_f32_e32 v110, 0xbfb8aa3b, v102
	v_mul_f32_e32 v111, 0xbfb8aa3b, v103
	v_mul_f32_e32 v112, 0xbfb8aa3b, v104
	v_mul_f32_e32 v113, 0xbfb8aa3b, v105
	v_exp_f32_e32 v110, v110
	v_exp_f32_e32 v111, v111
	v_exp_f32_e32 v112, v112
	v_exp_f32_e32 v113, v113
	v_add_f32_e32 v110, 1.0, v110
	v_add_f32_e32 v111, 1.0, v111
	v_add_f32_e32 v112, 1.0, v112
	v_add_f32_e32 v113, 1.0, v113
	v_rcp_f32_e32 v110, v110
	v_rcp_f32_e32 v111, v111
	v_rcp_f32_e32 v112, v112
	v_rcp_f32_e32 v113, v113
	v_lshl_add_u64 v[114:115], v[114:115], 0, v[144:145]
	v_pk_mul_f32 v[102:103], v[102:103], v[110:111]
	s_and_b64 vcc, exec, s[2:3]
	v_pk_mul_f32 v[104:105], v[104:105], v[112:113]
	s_mov_b32 s10, s6
	v_pk_mul_f32 v[104:105], v[104:105], v[100:101]
	v_pk_mul_f32 v[100:101], v[102:103], v[98:99]
	v_cvt_pk_bf16_f32 v98, v106, v107
	v_cvt_pk_bf16_f32 v99, v108, v109
	v_mul_f32_e32 v102, 0xbfb8aa3b, v96
	v_cvt_pk_bf16_f32 v100, v100, v101
	v_cvt_pk_bf16_f32 v101, v104, v105
	global_store_dwordx4 v[114:115], v[98:101], off
	v_mul_f32_e32 v103, 0xbfb8aa3b, v97
	v_exp_f32_e32 v102, v102
	v_mul_f32_e32 v100, 0xbfb8aa3b, v94
	v_mul_f32_e32 v101, 0xbfb8aa3b, v95
	v_exp_f32_e32 v100, v100
	v_exp_f32_e32 v101, v101
	v_exp_f32_e32 v103, v103
	v_add_f32_e32 v102, 1.0, v102
	v_add_f32_e32 v100, 1.0, v100
	v_add_f32_e32 v101, 1.0, v101
	v_add_f32_e32 v103, 1.0, v103
	v_rcp_f32_e32 v100, v100
	v_rcp_f32_e32 v101, v101
	v_rcp_f32_e32 v102, v102
	v_rcp_f32_e32 v103, v103
	v_add_u32_e32 v98, 32, v149
	v_pk_mul_f32 v[94:95], v[94:95], v[100:101]
	v_mad_i64_i32 v[98:99], s[12:13], v98, s7, v[142:143]
	v_pk_mul_f32 v[96:97], v[96:97], v[102:103]
	v_pk_mul_f32 v[90:91], v[94:95], v[90:91]
	v_pk_mul_f32 v[92:93], v[96:97], v[92:93]
	v_mul_f32_e32 v94, 0xbfb8aa3b, v86
	v_mul_f32_e32 v95, 0xbfb8aa3b, v87
	v_mul_f32_e32 v96, 0xbfb8aa3b, v88
	v_mul_f32_e32 v97, 0xbfb8aa3b, v89
	v_exp_f32_e32 v94, v94
	v_exp_f32_e32 v95, v95
	v_exp_f32_e32 v96, v96
	v_exp_f32_e32 v97, v97
	v_add_f32_e32 v94, 1.0, v94
	v_add_f32_e32 v95, 1.0, v95
	v_add_f32_e32 v96, 1.0, v96
	v_add_f32_e32 v97, 1.0, v97
	v_rcp_f32_e32 v94, v94
	v_rcp_f32_e32 v95, v95
	v_rcp_f32_e32 v96, v96
	v_rcp_f32_e32 v97, v97
	v_lshl_add_u64 v[98:99], v[98:99], 0, v[144:145]
	v_pk_mul_f32 v[86:87], v[86:87], v[94:95]
	s_mov_b32 s64, s61
	v_pk_mul_f32 v[88:89], v[88:89], v[96:97]
	s_mov_b64 s[14:15], s[4:5]
	v_pk_mul_f32 v[88:89], v[88:89], v[84:85]
	v_pk_mul_f32 v[84:85], v[86:87], v[82:83]
	v_cvt_pk_bf16_f32 v82, v90, v91
	v_cvt_pk_bf16_f32 v83, v92, v93
	v_mul_f32_e32 v86, 0xbfb8aa3b, v80
	v_cvt_pk_bf16_f32 v84, v84, v85
	v_cvt_pk_bf16_f32 v85, v88, v89
	global_store_dwordx4 v[98:99], v[82:85], off
	v_mul_f32_e32 v87, 0xbfb8aa3b, v81
	v_exp_f32_e32 v86, v86
	v_mul_f32_e32 v84, 0xbfb8aa3b, v78
	v_mul_f32_e32 v85, 0xbfb8aa3b, v79
	v_exp_f32_e32 v84, v84
	v_exp_f32_e32 v85, v85
	v_exp_f32_e32 v87, v87
	v_add_f32_e32 v86, 1.0, v86
	v_add_f32_e32 v84, 1.0, v84
	v_add_f32_e32 v85, 1.0, v85
	v_add_f32_e32 v87, 1.0, v87
	v_rcp_f32_e32 v84, v84
	v_rcp_f32_e32 v85, v85
	v_rcp_f32_e32 v86, v86
	v_rcp_f32_e32 v87, v87
	v_add_u32_e32 v82, 48, v149
	v_pk_mul_f32 v[78:79], v[78:79], v[84:85]
	v_mad_i64_i32 v[82:83], s[12:13], v82, s7, v[142:143]
	v_pk_mul_f32 v[80:81], v[80:81], v[86:87]
	v_pk_mul_f32 v[74:75], v[78:79], v[74:75]
	v_pk_mul_f32 v[76:77], v[80:81], v[76:77]
	v_mul_f32_e32 v78, 0xbfb8aa3b, v70
	v_mul_f32_e32 v79, 0xbfb8aa3b, v71
	v_mul_f32_e32 v80, 0xbfb8aa3b, v72
	v_mul_f32_e32 v81, 0xbfb8aa3b, v73
	v_exp_f32_e32 v78, v78
	v_exp_f32_e32 v79, v79
	v_exp_f32_e32 v80, v80
	v_exp_f32_e32 v81, v81
	v_add_f32_e32 v78, 1.0, v78
	v_add_f32_e32 v79, 1.0, v79
	v_add_f32_e32 v80, 1.0, v80
	v_add_f32_e32 v81, 1.0, v81
	v_rcp_f32_e32 v78, v78
	v_rcp_f32_e32 v79, v79
	v_rcp_f32_e32 v80, v80
	v_rcp_f32_e32 v81, v81
	v_lshl_add_u64 v[82:83], v[82:83], 0, v[144:145]
	v_pk_mul_f32 v[70:71], v[70:71], v[78:79]
	s_mov_b64 s[68:69], 0x1000
	v_pk_mul_f32 v[72:73], v[72:73], v[80:81]
	s_nop 0
	v_pk_mul_f32 v[72:73], v[72:73], v[68:69]
	v_pk_mul_f32 v[68:69], v[70:71], v[66:67]
	v_cvt_pk_bf16_f32 v66, v74, v75
	v_cvt_pk_bf16_f32 v67, v76, v77
	v_mul_f32_e32 v70, 0xbfb8aa3b, v64
	v_cvt_pk_bf16_f32 v68, v68, v69
	v_cvt_pk_bf16_f32 v69, v72, v73
	global_store_dwordx4 v[82:83], v[66:69], off
	v_mul_f32_e32 v71, 0xbfb8aa3b, v65
	v_exp_f32_e32 v70, v70
	v_mul_f32_e32 v68, 0xbfb8aa3b, v62
	v_mul_f32_e32 v69, 0xbfb8aa3b, v63
	v_exp_f32_e32 v68, v68
	v_exp_f32_e32 v69, v69
	v_exp_f32_e32 v71, v71
	v_add_f32_e32 v70, 1.0, v70
	v_add_f32_e32 v68, 1.0, v68
	v_add_f32_e32 v69, 1.0, v69
	v_add_f32_e32 v71, 1.0, v71
	v_rcp_f32_e32 v68, v68
	v_rcp_f32_e32 v69, v69
	v_rcp_f32_e32 v70, v70
	v_rcp_f32_e32 v71, v71
	v_add_u32_e32 v66, 0x80, v149
	v_pk_mul_f32 v[62:63], v[62:63], v[68:69]
	v_mad_i64_i32 v[66:67], s[12:13], v66, s7, v[142:143]
	v_pk_mul_f32 v[64:65], v[64:65], v[70:71]
	v_pk_mul_f32 v[58:59], v[62:63], v[58:59]
	v_pk_mul_f32 v[60:61], v[64:65], v[60:61]
	v_mul_f32_e32 v62, 0xbfb8aa3b, v54
	v_mul_f32_e32 v63, 0xbfb8aa3b, v55
	v_mul_f32_e32 v64, 0xbfb8aa3b, v56
	v_mul_f32_e32 v65, 0xbfb8aa3b, v57
	v_exp_f32_e32 v62, v62
	v_exp_f32_e32 v63, v63
	v_exp_f32_e32 v64, v64
	v_exp_f32_e32 v65, v65
	v_add_f32_e32 v62, 1.0, v62
	v_add_f32_e32 v63, 1.0, v63
	v_add_f32_e32 v64, 1.0, v64
	v_add_f32_e32 v65, 1.0, v65
	v_rcp_f32_e32 v62, v62
; __device__ __forceinline__ unsigned cvt_pk_bf16(float lo, float hi) { unsigned r; asm("v_cvt_pk_bf16_f32 %0, %1, %2" : "=v"(r) : "v"(lo), "v"(hi)); return r; }
; #define PG8_WAIT_V(n) asm volatile("s_waitcnt vmcnt(" #n ")" ::: "memory")
; #define PG8_BAR __builtin_amdgcn_s_barrier()
; template <class Epi>
; __device__ __forceinline__ void gemm_phase(LAS unsigned char* lds, const Gemm g, const Epi& E) {
;     ...
;     PG8_WAIT_V(0);
;     if (wr == 0) PG8_BAR;
;     PG8_BAR;
;     __device__ __forceinline__ void operator()(const AccT& acc, const Unit& u, int wr, int wc, int fr, int fq) const {
;     ...
;             for (int m = 0; m < 4; ++m) { bf16_t* rowp = U + (size_t)(row0 + ai * 128 + m * 16) * HID + col0;
;                 const f32x4 s0 = silu4(acc[ai][0][m][0]) * acc[ai][1][m][0], s1 = silu4(acc[ai][0][m][1]) * acc[ai][1][m][1];
;                 u32x4 w; w.x = cvt_pk_bf16(s0[0], s0[1]); w.y = cvt_pk_bf16(s0[2], s0[3]); w.z = cvt_pk_bf16(s1[0], s1[1]); w.w = cvt_pk_bf16(s1[2], s1[3]);
;                 *(u32x4*)rowp = w; }
	v_rcp_f32_e32 v63, v63
	v_rcp_f32_e32 v64, v64
	v_rcp_f32_e32 v65, v65
	v_lshl_add_u64 v[66:67], v[66:67], 0, v[144:145]
	v_pk_mul_f32 v[54:55], v[54:55], v[62:63]
	v_pk_mul_f32 v[56:57], v[56:57], v[64:65]
	s_nop 0
	v_pk_mul_f32 v[56:57], v[56:57], v[52:53]
	v_pk_mul_f32 v[52:53], v[54:55], v[50:51]
	v_cvt_pk_bf16_f32 v50, v58, v59
	v_cvt_pk_bf16_f32 v51, v60, v61
	v_mul_f32_e32 v54, 0xbfb8aa3b, v48
	v_cvt_pk_bf16_f32 v52, v52, v53
	v_cvt_pk_bf16_f32 v53, v56, v57
	global_store_dwordx4 v[66:67], v[50:53], off
	v_mul_f32_e32 v55, 0xbfb8aa3b, v49
	v_exp_f32_e32 v54, v54
	v_mul_f32_e32 v52, 0xbfb8aa3b, v46
	v_mul_f32_e32 v53, 0xbfb8aa3b, v47
	v_exp_f32_e32 v52, v52
	v_exp_f32_e32 v53, v53
	v_exp_f32_e32 v55, v55
	v_add_f32_e32 v54, 1.0, v54
	v_add_f32_e32 v52, 1.0, v52
	v_add_f32_e32 v53, 1.0, v53
	v_add_f32_e32 v55, 1.0, v55
	v_rcp_f32_e32 v52, v52
	v_rcp_f32_e32 v53, v53
	v_rcp_f32_e32 v54, v54
	v_rcp_f32_e32 v55, v55
	v_add_u32_e32 v50, 0x90, v149
	v_pk_mul_f32 v[46:47], v[46:47], v[52:53]
	v_mad_i64_i32 v[50:51], s[12:13], v50, s7, v[142:143]
	v_pk_mul_f32 v[48:49], v[48:49], v[54:55]
	v_pk_mul_f32 v[42:43], v[46:47], v[42:43]
	v_pk_mul_f32 v[44:45], v[48:49], v[44:45]
	v_mul_f32_e32 v46, 0xbfb8aa3b, v38
	v_mul_f32_e32 v47, 0xbfb8aa3b, v39
	v_mul_f32_e32 v48, 0xbfb8aa3b, v40
	v_mul_f32_e32 v49, 0xbfb8aa3b, v41
	v_exp_f32_e32 v46, v46
	v_exp_f32_e32 v47, v47
	v_exp_f32_e32 v48, v48
	v_exp_f32_e32 v49, v49
	v_add_f32_e32 v46, 1.0, v46
	v_add_f32_e32 v47, 1.0, v47
	v_add_f32_e32 v48, 1.0, v48
	v_add_f32_e32 v49, 1.0, v49
	v_rcp_f32_e32 v46, v46
	v_rcp_f32_e32 v47, v47
	v_rcp_f32_e32 v48, v48
	v_rcp_f32_e32 v49, v49
	v_lshl_add_u64 v[50:51], v[50:51], 0, v[144:145]
	v_pk_mul_f32 v[38:39], v[38:39], v[46:47]
	v_pk_mul_f32 v[40:41], v[40:41], v[48:49]
	s_nop 0
	v_pk_mul_f32 v[40:41], v[40:41], v[36:37]
	v_pk_mul_f32 v[36:37], v[38:39], v[34:35]
	v_cvt_pk_bf16_f32 v34, v42, v43
	v_cvt_pk_bf16_f32 v35, v44, v45
	v_mul_f32_e32 v38, 0xbfb8aa3b, v32
	v_cvt_pk_bf16_f32 v36, v36, v37
	v_cvt_pk_bf16_f32 v37, v40, v41
	global_store_dwordx4 v[50:51], v[34:37], off
	v_mul_f32_e32 v39, 0xbfb8aa3b, v33
	v_exp_f32_e32 v38, v38
	v_mul_f32_e32 v36, 0xbfb8aa3b, v30
	v_mul_f32_e32 v37, 0xbfb8aa3b, v31
	v_exp_f32_e32 v36, v36
	v_exp_f32_e32 v37, v37
	v_exp_f32_e32 v39, v39
	v_add_f32_e32 v38, 1.0, v38
	v_add_f32_e32 v36, 1.0, v36
	v_add_f32_e32 v37, 1.0, v37
	v_add_f32_e32 v39, 1.0, v39
	v_rcp_f32_e32 v36, v36
	v_rcp_f32_e32 v37, v37
	v_rcp_f32_e32 v38, v38
	v_rcp_f32_e32 v39, v39
	v_add_u32_e32 v34, 0xa0, v149
	v_pk_mul_f32 v[30:31], v[30:31], v[36:37]
	v_mad_i64_i32 v[34:35], s[12:13], v34, s7, v[142:143]
	v_pk_mul_f32 v[32:33], v[32:33], v[38:39]
	v_pk_mul_f32 v[26:27], v[30:31], v[26:27]
	v_pk_mul_f32 v[28:29], v[32:33], v[28:29]
	v_mul_f32_e32 v30, 0xbfb8aa3b, v22
	v_mul_f32_e32 v31, 0xbfb8aa3b, v23
	v_mul_f32_e32 v32, 0xbfb8aa3b, v24
	v_mul_f32_e32 v33, 0xbfb8aa3b, v25
	v_exp_f32_e32 v30, v30
	v_exp_f32_e32 v31, v31
	v_exp_f32_e32 v32, v32
	v_exp_f32_e32 v33, v33
	v_add_f32_e32 v30, 1.0, v30
	v_add_f32_e32 v31, 1.0, v31
	v_add_f32_e32 v32, 1.0, v32
	v_add_f32_e32 v33, 1.0, v33
	v_rcp_f32_e32 v30, v30
	v_rcp_f32_e32 v31, v31
	v_rcp_f32_e32 v32, v32
	v_rcp_f32_e32 v33, v33
	v_lshl_add_u64 v[34:35], v[34:35], 0, v[144:145]
	v_pk_mul_f32 v[22:23], v[22:23], v[30:31]
	v_pk_mul_f32 v[24:25], v[24:25], v[32:33]
	s_nop 0
	v_pk_mul_f32 v[24:25], v[24:25], v[20:21]
	v_pk_mul_f32 v[20:21], v[22:23], v[18:19]
	v_cvt_pk_bf16_f32 v18, v26, v27
	v_cvt_pk_bf16_f32 v19, v28, v29
	v_mul_f32_e32 v22, 0xbfb8aa3b, v16
	v_cvt_pk_bf16_f32 v20, v20, v21
	v_cvt_pk_bf16_f32 v21, v24, v25
	global_store_dwordx4 v[34:35], v[18:21], off
	v_mul_f32_e32 v23, 0xbfb8aa3b, v17
	v_exp_f32_e32 v22, v22
	v_mul_f32_e32 v20, 0xbfb8aa3b, v14
	v_mul_f32_e32 v21, 0xbfb8aa3b, v15
	v_exp_f32_e32 v20, v20
	v_exp_f32_e32 v21, v21
	v_exp_f32_e32 v23, v23
	v_add_f32_e32 v22, 1.0, v22
	v_add_f32_e32 v20, 1.0, v20
	v_add_f32_e32 v21, 1.0, v21
	v_add_f32_e32 v23, 1.0, v23
	v_rcp_f32_e32 v20, v20
	v_rcp_f32_e32 v21, v21
	v_rcp_f32_e32 v22, v22
	v_rcp_f32_e32 v23, v23
	v_add_u32_e32 v18, 0xb0, v149
	v_pk_mul_f32 v[14:15], v[14:15], v[20:21]
	v_mad_i64_i32 v[18:19], s[12:13], v18, s7, v[142:143]
	v_pk_mul_f32 v[16:17], v[16:17], v[22:23]
	v_pk_mul_f32 v[10:11], v[14:15], v[10:11]
	v_pk_mul_f32 v[12:13], v[16:17], v[12:13]
	v_mul_f32_e32 v14, 0xbfb8aa3b, v6
	v_mul_f32_e32 v15, 0xbfb8aa3b, v7
	v_mul_f32_e32 v16, 0xbfb8aa3b, v8
	v_mul_f32_e32 v17, 0xbfb8aa3b, v9
	v_exp_f32_e32 v14, v14
	v_exp_f32_e32 v15, v15
	v_exp_f32_e32 v16, v16
	v_exp_f32_e32 v17, v17
	v_add_f32_e32 v14, 1.0, v14
	v_add_f32_e32 v15, 1.0, v15
	v_add_f32_e32 v16, 1.0, v16
	v_add_f32_e32 v17, 1.0, v17
	v_rcp_f32_e32 v14, v14
	v_rcp_f32_e32 v15, v15
	v_rcp_f32_e32 v16, v16
	v_rcp_f32_e32 v17, v17
	v_lshl_add_u64 v[18:19], v[18:19], 0, v[144:145]
	v_pk_mul_f32 v[6:7], v[6:7], v[14:15]
	s_mov_b64 s[12:13], s[8:9]
	v_pk_mul_f32 v[8:9], v[8:9], v[16:17]
	s_nop 0
	v_pk_mul_f32 v[8:9], v[8:9], v[4:5]
	v_pk_mul_f32 v[4:5], v[6:7], v[2:3]
	v_cvt_pk_bf16_f32 v2, v10, v11
	v_cvt_pk_bf16_f32 v3, v12, v13
	s_nop 0
	v_cvt_pk_bf16_f32 v4, v4, v5
	v_cvt_pk_bf16_f32 v5, v8, v9
	global_store_dwordx4 v[18:19], v[2:5], off
	s_cbranch_vccz .LBB0_520
	s_waitcnt vmcnt(0)
	s_cmpk_gt_u32 s1, 0xff
	s_cbranch_scc1 .LBB0_529
	s_barrier

; #define PG8_STAGE(bufoff, gbase, voff) do { _Pragma("unroll") for (int _i = 0; _i < 2; ++_i) \
;         __builtin_amdgcn_global_load_lds((const unsigned*)((const char*)(gbase) + (voff)[_i]), (LAS unsigned*)(lds + (bufoff) + ldsw + _i * 8192), 16, 0, 0); } while (0)
; #define PG8_LDA(dst, b, h) do { _Pragma("unroll") for (int m = 0; m < 4; ++m) _Pragma("unroll") for (int k = 0; k < 2; ++k) dst[m][k] = *(const LAS bf16x8*)(lds + PG8_SA(b, h) + aoff + m * 2048 + k * 1024); } while (0)
; #define PG8_LDB(dst, b, h) do { _Pragma("unroll") for (int n = 0; n < 2; ++n) _Pragma("unroll") for (int k = 0; k < 2; ++k) dst[n][k] = *(const LAS bf16x8*)(lds + PG8_SB(b, h) + boff + n * 2048 + k * 1024); } while (0)
; #define PG8_MMA(ai, bj, At, Bt) do { __builtin_amdgcn_s_setprio(1); _Pragma("unroll") for (int m = 0; m < 4; ++m) _Pragma("unroll") for (int n = 0; n < 2; ++n) _Pragma("unroll") for (int k = 0; k < 2; ++k) \
;         acc[ai][bj][m][n] = __builtin_amdgcn_mfma_f32_16x16x32_bf16(Bt[n][k], At[m][k], acc[ai][bj][m][n], 0, 0, 0); __builtin_amdgcn_s_setprio(0); } while (0)
; #define PG8_WAIT_L(n) asm volatile("s_waitcnt lgkmcnt(" #n ")" ::: "memory")
; #define PG8_BAR __builtin_amdgcn_s_barrier()
; #define PG8_SCHED __builtin_amdgcn_sched_barrier(0)
; template <class Epi>
; __device__ __forceinline__ void gemm_phase(LAS unsigned char* lds, const Gemm g, const Epi& E) {
;     ...
;             const bool last = (t == nt - 2);
;             const char* a1 = cA + (size_t)(t + 1) * kstep;
;             const char* a2 = last ? nA : cA + (size_t)(t + 2) * kstep; const char* b2 = last ? nB : cB + (size_t)(t + 2) * kstep;
;             const char* a3 = a2 + kstep; const char* b3 = b2 + kstep;
;             PG8_LDB(B0, 0, 0); PG8_SCHED; PG8_LDA(At, 0, 0); PG8_STAGE(PG8_SA(1, 1), a1 + hstepA, voffA);
;             PG8_WAIT_L(8); PG8_BAR; PG8_WAIT_L(0); PG8_MMA(0, 0, At, B0); PG8_BAR; PG8_SCHED;
;             PG8_LDB(B1, 0, 1); PG8_STAGE(PG8_SB(0, 0), b2, voffB);
;             PG8_BAR; PG8_WAIT_L(0); PG8_MMA(0, 1, At, B1); PG8_BAR;
;             PG8_LDA(At, 0, 1); PG8_STAGE(PG8_SA(0, 0), a2, voffA);
;             PG8_BAR; PG8_WAIT_L(0); PG8_MMA(1, 0, At, B0); PG8_BAR; PG8_SCHED;
.LBB0_547:
	s_add_u32 s10, s8, 0x100
	s_addc_u32 s11, s9, 0
	s_add_i32 s26, 0, 0x10000
	v_add_u32_e32 v142, s26, v157
	ds_read_b128 v[130:133], v142
	ds_read_b128 v[134:137], v142 offset:1024
	ds_read_b128 v[138:141], v142 offset:2048
	ds_read_b128 v[142:145], v142 offset:3072
	s_cmp_eq_u32 s67, 40
	s_cselect_b32 s15, s5, s11
	s_cselect_b32 s14, s4, s10
	s_cselect_b32 s13, s7, s66
	s_cselect_b32 s12, s6, s65
	v_lshl_add_u64 v[154:155], s[8:9], 0, v[150:151]
	s_add_i32 m0, s29, 0xc000
	ds_read_b128 v[160:163], v158
	ds_read_b128 v[164:167], v158 offset:1024
	ds_read_b128 v[168:171], v158 offset:2048
	ds_read_b128 v[172:175], v158 offset:3072
	ds_read_b128 v[180:183], v158 offset:4096
	ds_read_b128 v[184:187], v158 offset:5120
	ds_read_b128 v[188:191], v158 offset:6144
	ds_read_b128 v[192:195], v158 offset:7168
	global_load_lds_dwordx4 v[154:155], off
	v_lshl_add_u64 v[154:155], s[8:9], 0, v[152:153]
	s_add_i32 m0, s29, 0xe000
	s_nop 0
	global_load_lds_dwordx4 v[154:155], off
	s_waitcnt lgkmcnt(8)
	s_barrier
	s_waitcnt lgkmcnt(0)
	v_mfma_f32_16x16x32_bf16 v[126:129], v[130:133], v[160:163], v[126:129]
	v_mfma_f32_16x16x32_bf16 v[122:125], v[138:141], v[160:163], v[122:125]
	v_mfma_f32_16x16x32_bf16 v[118:121], v[130:133], v[168:171], v[118:121]
	v_mfma_f32_16x16x32_bf16 v[110:113], v[138:141], v[168:171], v[110:113]
	v_mfma_f32_16x16x32_bf16 v[102:105], v[130:133], v[180:183], v[102:105]
	v_mfma_f32_16x16x32_bf16 v[94:97], v[138:141], v[180:183], v[94:97]
	v_mfma_f32_16x16x32_bf16 v[86:89], v[130:133], v[188:191], v[86:89]
	v_mfma_f32_16x16x32_bf16 v[78:81], v[138:141], v[188:191], v[78:81]
	v_mfma_f32_16x16x32_bf16 v[126:129], v[134:137], v[164:167], v[126:129]
	v_mfma_f32_16x16x32_bf16 v[122:125], v[142:145], v[164:167], v[122:125]
	v_mfma_f32_16x16x32_bf16 v[118:121], v[134:137], v[172:175], v[118:121]
	v_mfma_f32_16x16x32_bf16 v[110:113], v[142:145], v[172:175], v[110:113]
	v_mfma_f32_16x16x32_bf16 v[102:105], v[134:137], v[184:187], v[102:105]
	v_mfma_f32_16x16x32_bf16 v[94:97], v[142:145], v[184:187], v[94:97]
	v_mfma_f32_16x16x32_bf16 v[86:89], v[134:137], v[192:195], v[86:89]
	v_mfma_f32_16x16x32_bf16 v[78:81], v[142:145], v[192:195], v[78:81]
	s_barrier
	s_add_i32 s27, 0, 0x14000
	v_add_u32_e32 v154, s27, v157
	s_add_i32 s8, s26, s18
	ds_read_b128 v[196:199], v154
	ds_read_b128 v[200:203], v154 offset:1024
	ds_read_b128 v[204:207], v154 offset:2048
	ds_read_b128 v[226:229], v154 offset:3072
	v_lshl_add_u64 v[154:155], s[12:13], 0, v[148:149]
	s_mov_b32 m0, s8
	v_lshl_add_u64 v[176:177], s[12:13], 0, v[146:147]
	global_load_lds_dwordx4 v[154:155], off
	s_add_i32 m0, s8, 0x2000
	s_nop 0
	global_load_lds_dwordx4 v[176:177], off
	s_nop 1
	s_mov_b32 m0, s29
	v_lshl_add_u64 v[208:209], s[14:15], 0, v[148:149]
	s_barrier
	s_waitcnt lgkmcnt(0)
	v_mfma_f32_16x16x32_bf16 v[114:117], v[196:199], v[160:163], v[114:117]
	v_mfma_f32_16x16x32_bf16 v[106:109], v[204:207], v[160:163], v[106:109]
	v_mfma_f32_16x16x32_bf16 v[98:101], v[196:199], v[168:171], v[98:101]
	v_mfma_f32_16x16x32_bf16 v[90:93], v[204:207], v[168:171], v[90:93]
	v_mfma_f32_16x16x32_bf16 v[82:85], v[196:199], v[180:183], v[82:85]
	v_mfma_f32_16x16x32_bf16 v[74:77], v[204:207], v[180:183], v[74:77]
	v_mfma_f32_16x16x32_bf16 v[70:73], v[196:199], v[188:191], v[70:73]
	v_mfma_f32_16x16x32_bf16 v[66:69], v[204:207], v[188:191], v[66:69]
	v_mfma_f32_16x16x32_bf16 v[114:117], v[200:203], v[164:167], v[114:117]
	v_mfma_f32_16x16x32_bf16 v[106:109], v[226:229], v[164:167], v[106:109]
	v_mfma_f32_16x16x32_bf16 v[98:101], v[200:203], v[172:175], v[98:101]
	v_mfma_f32_16x16x32_bf16 v[90:93], v[226:229], v[172:175], v[90:93]
	v_mfma_f32_16x16x32_bf16 v[82:85], v[200:203], v[184:187], v[82:85]
	v_mfma_f32_16x16x32_bf16 v[74:77], v[226:229], v[184:187], v[74:77]
	v_mfma_f32_16x16x32_bf16 v[70:73], v[200:203], v[192:195], v[70:73]
	v_mfma_f32_16x16x32_bf16 v[66:69], v[226:229], v[192:195], v[66:69]
	s_barrier
	ds_read_b128 v[160:163], v158 offset:16384
	ds_read_b128 v[164:167], v158 offset:17408
	ds_read_b128 v[168:171], v158 offset:18432
	ds_read_b128 v[172:175], v158 offset:19456
	ds_read_b128 v[180:183], v158 offset:20480
	ds_read_b128 v[184:187], v158 offset:21504
	ds_read_b128 v[188:191], v158 offset:22528
	ds_read_b128 v[192:195], v158 offset:23552
	global_load_lds_dwordx4 v[208:209], off
	v_lshl_add_u64 v[230:231], s[14:15], 0, v[146:147]
	s_mov_b32 m0, s30
	s_nop 0
	global_load_lds_dwordx4 v[230:231], off
	s_barrier
	s_waitcnt lgkmcnt(0)
	v_mfma_f32_16x16x32_bf16 v[62:65], v[130:133], v[160:163], v[62:65]
	v_mfma_f32_16x16x32_bf16 v[58:61], v[138:141], v[160:163], v[58:61]
	v_mfma_f32_16x16x32_bf16 v[54:57], v[130:133], v[168:171], v[54:57]
	v_mfma_f32_16x16x32_bf16 v[46:49], v[138:141], v[168:171], v[46:49]
	v_mfma_f32_16x16x32_bf16 v[38:41], v[130:133], v[180:183], v[38:41]
	v_mfma_f32_16x16x32_bf16 v[30:33], v[138:141], v[180:183], v[30:33]
	v_mfma_f32_16x16x32_bf16 v[22:25], v[130:133], v[188:191], v[22:25]
	v_mfma_f32_16x16x32_bf16 v[14:17], v[138:141], v[188:191], v[14:17]
	v_mfma_f32_16x16x32_bf16 v[62:65], v[134:137], v[164:167], v[62:65]
	v_mfma_f32_16x16x32_bf16 v[58:61], v[142:145], v[164:167], v[58:61]
	v_mfma_f32_16x16x32_bf16 v[54:57], v[134:137], v[172:175], v[54:57]
	v_mfma_f32_16x16x32_bf16 v[46:49], v[142:145], v[172:175], v[46:49]
	v_mfma_f32_16x16x32_bf16 v[38:41], v[134:137], v[184:187], v[38:41]
	v_mfma_f32_16x16x32_bf16 v[30:33], v[142:145], v[184:187], v[30:33]
	v_mfma_f32_16x16x32_bf16 v[22:25], v[134:137], v[192:195], v[22:25]
	v_mfma_f32_16x16x32_bf16 v[14:17], v[142:145], v[192:195], v[14:17]
	s_barrier
; #define PG8_STAGE(bufoff, gbase, voff) do { _Pragma("unroll") for (int _i = 0; _i < 2; ++_i) \
;         __builtin_amdgcn_global_load_lds((const unsigned*)((const char*)(gbase) + (voff)[_i]), (LAS unsigned*)(lds + (bufoff) + ldsw + _i * 8192), 16, 0, 0); } while (0)
; #define PG8_LDA(dst, b, h) do { _Pragma("unroll") for (int m = 0; m < 4; ++m) _Pragma("unroll") for (int k = 0; k < 2; ++k) dst[m][k] = *(const LAS bf16x8*)(lds + PG8_SA(b, h) + aoff + m * 2048 + k * 1024); } while (0)
; #define PG8_LDB(dst, b, h) do { _Pragma("unroll") for (int n = 0; n < 2; ++n) _Pragma("unroll") for (int k = 0; k < 2; ++k) dst[n][k] = *(const LAS bf16x8*)(lds + PG8_SB(b, h) + boff + n * 2048 + k * 1024); } while (0)
; #define PG8_MMA(ai, bj, At, Bt) do { __builtin_amdgcn_s_setprio(1); _Pragma("unroll") for (int m = 0; m < 4; ++m) _Pragma("unroll") for (int n = 0; n < 2; ++n) _Pragma("unroll") for (int k = 0; k < 2; ++k) \
;         acc[ai][bj][m][n] = __builtin_amdgcn_mfma_f32_16x16x32_bf16(Bt[n][k], At[m][k], acc[ai][bj][m][n], 0, 0, 0); __builtin_amdgcn_s_setprio(0); } while (0)
; #define PG8_WAIT_V(n) asm volatile("s_waitcnt vmcnt(" #n ")" ::: "memory")
; #define PG8_WAIT_L(n) asm volatile("s_waitcnt lgkmcnt(" #n ")" ::: "memory")
; #define PG8_BAR __builtin_amdgcn_s_barrier()
; #define PG8_SCHED __builtin_amdgcn_sched_barrier(0)
; template <class Epi>
; __device__ __forceinline__ void gemm_phase(LAS unsigned char* lds, const Gemm g, const Epi& E) {
;     ...
;             PG8_STAGE(PG8_SB(0, 1), b2 + hstepB, voffB);
;             PG8_WAIT_V(6); PG8_BAR; PG8_MMA(1, 1, At, B1); PG8_BAR;
;             PG8_LDB(B0, 1, 0); PG8_SCHED; PG8_LDA(At, 1, 0); PG8_STAGE(PG8_SA(0, 1), a2 + hstepA, voffA);
;             PG8_WAIT_L(8); PG8_BAR; PG8_WAIT_L(0); PG8_MMA(0, 0, At, B0); PG8_BAR; PG8_SCHED;
;             PG8_LDB(B1, 1, 1); PG8_STAGE(PG8_SB(1, 0), b3, voffB);
;             PG8_BAR; PG8_WAIT_L(0); PG8_MMA(0, 1, At, B1); PG8_BAR;
;             PG8_LDA(At, 1, 1); PG8_STAGE(PG8_SA(1, 0), a3, voffA);
	s_add_u32 s8, s12, 0xb0000
	s_addc_u32 s9, s13, 0
	s_add_i32 s26, s27, s18
	v_lshl_add_u64 v[130:131], s[8:9], 0, v[148:149]
	s_mov_b32 m0, s26
	s_nop 0
	global_load_lds_dwordx4 v[130:131], off
	v_lshl_add_u64 v[130:131], s[8:9], 0, v[146:147]
	s_add_i32 m0, s26, 0x2000
	s_nop 0
	global_load_lds_dwordx4 v[130:131], off
	s_add_i32 s26, 0, 0x18000
	v_add_u32_e32 v142, s26, v157
	s_waitcnt vmcnt(6)
	s_barrier
	v_mfma_f32_16x16x32_bf16 v[50:53], v[196:199], v[160:163], v[50:53]
	v_mfma_f32_16x16x32_bf16 v[42:45], v[204:207], v[160:163], v[42:45]
	v_mfma_f32_16x16x32_bf16 v[34:37], v[196:199], v[168:171], v[34:37]
	v_mfma_f32_16x16x32_bf16 v[26:29], v[204:207], v[168:171], v[26:29]
	v_mfma_f32_16x16x32_bf16 v[18:21], v[196:199], v[180:183], v[18:21]
	v_mfma_f32_16x16x32_bf16 v[10:13], v[204:207], v[180:183], v[10:13]
	v_mfma_f32_16x16x32_bf16 v[6:9], v[196:199], v[188:191], v[6:9]
	v_mfma_f32_16x16x32_bf16 v[2:5], v[204:207], v[188:191], v[2:5]
	v_mfma_f32_16x16x32_bf16 v[50:53], v[200:203], v[164:167], v[50:53]
	v_mfma_f32_16x16x32_bf16 v[42:45], v[226:229], v[164:167], v[42:45]
	v_mfma_f32_16x16x32_bf16 v[34:37], v[200:203], v[172:175], v[34:37]
	v_mfma_f32_16x16x32_bf16 v[26:29], v[226:229], v[172:175], v[26:29]
	v_mfma_f32_16x16x32_bf16 v[18:21], v[200:203], v[184:187], v[18:21]
	v_mfma_f32_16x16x32_bf16 v[10:13], v[226:229], v[184:187], v[10:13]
	v_mfma_f32_16x16x32_bf16 v[6:9], v[200:203], v[192:195], v[6:9]
	v_mfma_f32_16x16x32_bf16 v[2:5], v[226:229], v[192:195], v[2:5]
	s_barrier
	ds_read_b128 v[130:133], v142
	ds_read_b128 v[134:137], v142 offset:1024
	ds_read_b128 v[138:141], v142 offset:2048
	ds_read_b128 v[142:145], v142 offset:3072
	s_add_u32 s8, s14, 0xb0000
	s_addc_u32 s9, s15, 0
	s_mov_b32 m0, s31
	v_lshl_add_u64 v[196:197], s[8:9], 0, v[148:149]
	ds_read_b128 v[160:163], v158 offset:32768
	ds_read_b128 v[164:167], v158 offset:33792
	ds_read_b128 v[168:171], v158 offset:34816
	ds_read_b128 v[172:175], v158 offset:35840
	ds_read_b128 v[180:183], v158 offset:36864
	ds_read_b128 v[184:187], v158 offset:37888
	ds_read_b128 v[188:191], v158 offset:38912
	ds_read_b128 v[192:195], v158 offset:39936
	global_load_lds_dwordx4 v[196:197], off
	v_lshl_add_u64 v[196:197], s[8:9], 0, v[146:147]
	s_mov_b32 m0, s36
	s_nop 0
	global_load_lds_dwordx4 v[196:197], off
	s_waitcnt lgkmcnt(8)
	s_barrier
	s_waitcnt lgkmcnt(0)
	v_mfma_f32_16x16x32_bf16 v[126:129], v[130:133], v[160:163], v[126:129]
	v_mfma_f32_16x16x32_bf16 v[122:125], v[138:141], v[160:163], v[122:125]
	v_mfma_f32_16x16x32_bf16 v[118:121], v[130:133], v[168:171], v[118:121]
	v_mfma_f32_16x16x32_bf16 v[110:113], v[138:141], v[168:171], v[110:113]
	v_mfma_f32_16x16x32_bf16 v[102:105], v[130:133], v[180:183], v[102:105]
	v_mfma_f32_16x16x32_bf16 v[94:97], v[138:141], v[180:183], v[94:97]
	v_mfma_f32_16x16x32_bf16 v[86:89], v[130:133], v[188:191], v[86:89]
	v_mfma_f32_16x16x32_bf16 v[78:81], v[138:141], v[188:191], v[78:81]
	v_mfma_f32_16x16x32_bf16 v[126:129], v[134:137], v[164:167], v[126:129]
	v_mfma_f32_16x16x32_bf16 v[122:125], v[142:145], v[164:167], v[122:125]
	v_mfma_f32_16x16x32_bf16 v[118:121], v[134:137], v[172:175], v[118:121]
	v_mfma_f32_16x16x32_bf16 v[110:113], v[142:145], v[172:175], v[110:113]
	v_mfma_f32_16x16x32_bf16 v[102:105], v[134:137], v[184:187], v[102:105]
	v_mfma_f32_16x16x32_bf16 v[94:97], v[142:145], v[184:187], v[94:97]
	v_mfma_f32_16x16x32_bf16 v[86:89], v[134:137], v[192:195], v[86:89]
	v_mfma_f32_16x16x32_bf16 v[78:81], v[142:145], v[192:195], v[78:81]
	s_barrier
	s_add_i32 s14, 0, 0x1c000
	s_add_i32 s8, s26, s18
	v_add_u32_e32 v159, s14, v157
	v_lshl_add_u64 v[154:155], v[154:155], 0, s[86:87]
	s_mov_b32 m0, s8
	ds_read_b128 v[196:199], v159
	ds_read_b128 v[200:203], v159 offset:1024
	ds_read_b128 v[204:207], v159 offset:2048
	ds_read_b128 v[226:229], v159 offset:3072
	global_load_lds_dwordx4 v[154:155], off
	v_lshl_add_u64 v[154:155], v[176:177], 0, s[86:87]
	s_add_i32 m0, s8, 0x2000
	s_nop 0
	global_load_lds_dwordx4 v[154:155], off
	s_nop 1
	s_mov_b32 m0, s52
	v_lshl_add_u64 v[154:155], v[208:209], 0, s[86:87]
	s_barrier
	s_waitcnt lgkmcnt(0)
	v_mfma_f32_16x16x32_bf16 v[114:117], v[196:199], v[160:163], v[114:117]
	v_mfma_f32_16x16x32_bf16 v[106:109], v[204:207], v[160:163], v[106:109]
	v_mfma_f32_16x16x32_bf16 v[98:101], v[196:199], v[168:171], v[98:101]
	v_mfma_f32_16x16x32_bf16 v[90:93], v[204:207], v[168:171], v[90:93]
	v_mfma_f32_16x16x32_bf16 v[82:85], v[196:199], v[180:183], v[82:85]
	v_mfma_f32_16x16x32_bf16 v[74:77], v[204:207], v[180:183], v[74:77]
	v_mfma_f32_16x16x32_bf16 v[70:73], v[196:199], v[188:191], v[70:73]
	v_mfma_f32_16x16x32_bf16 v[66:69], v[204:207], v[188:191], v[66:69]
	v_mfma_f32_16x16x32_bf16 v[114:117], v[200:203], v[164:167], v[114:117]
	v_mfma_f32_16x16x32_bf16 v[106:109], v[226:229], v[164:167], v[106:109]
	v_mfma_f32_16x16x32_bf16 v[98:101], v[200:203], v[172:175], v[98:101]
	v_mfma_f32_16x16x32_bf16 v[90:93], v[226:229], v[172:175], v[90:93]
	v_mfma_f32_16x16x32_bf16 v[82:85], v[200:203], v[184:187], v[82:85]
	v_mfma_f32_16x16x32_bf16 v[74:77], v[226:229], v[184:187], v[74:77]
	v_mfma_f32_16x16x32_bf16 v[70:73], v[200:203], v[192:195], v[70:73]
	v_mfma_f32_16x16x32_bf16 v[66:69], v[226:229], v[192:195], v[66:69]
	s_barrier
	ds_read_b128 v[160:163], v158 offset:49152
	ds_read_b128 v[164:167], v158 offset:50176
	ds_read_b128 v[168:171], v158 offset:51200
	ds_read_b128 v[172:175], v158 offset:52224
	ds_read_b128 v[180:183], v158 offset:53248
	ds_read_b128 v[184:187], v158 offset:54272
	ds_read_b128 v[188:191], v158 offset:55296
	ds_read_b128 v[192:195], v158 offset:56320
	global_load_lds_dwordx4 v[154:155], off
	v_lshl_add_u64 v[154:155], v[230:231], 0, s[86:87]
	s_mov_b32 m0, s53
	s_nop 0
	global_load_lds_dwordx4 v[154:155], off
	s_barrier
; #define PG8_STAGE(bufoff, gbase, voff) do { _Pragma("unroll") for (int _i = 0; _i < 2; ++_i) \
;         __builtin_amdgcn_global_load_lds((const unsigned*)((const char*)(gbase) + (voff)[_i]), (LAS unsigned*)(lds + (bufoff) + ldsw + _i * 8192), 16, 0, 0); } while (0)
; #define PG8_WAIT_V(n) asm volatile("s_waitcnt vmcnt(" #n ")" ::: "memory")
; #define PG8_WAIT_L(n) asm volatile("s_waitcnt lgkmcnt(" #n ")" ::: "memory")
; #define PG8_BAR __builtin_amdgcn_s_barrier()
; #define PG8_SCHED __builtin_amdgcn_sched_barrier(0)
; template <class Epi>
; __device__ __forceinline__ void gemm_phase(LAS unsigned char* lds, const Gemm g, const Epi& E) {
;     ...
;             PG8_BAR; PG8_WAIT_L(0); PG8_MMA(1, 0, At, B0); PG8_BAR; PG8_SCHED;
;             PG8_STAGE(PG8_SB(1, 1), b3 + hstepB, voffB);
;             PG8_WAIT_V(6); PG8_BAR; PG8_MMA(1, 1, At, B1); PG8_BAR;
;     __device__ __forceinline__ void operator()(const AccT& acc, const Unit& u, int wr, int wc, int fr, int fq) const {
;     ...
;         const int gpm = mapA.src(u.pm);
;         const int mb = gpm < 32 ? 32 : (gpm - 32) >> 3;
;         const int row0 = gpm * 256 + wr * 64 + fr, col0 = u.pn * 256 + wc * 32 + 4 * fq;
;         const float* gp = modl + ((size_t)mb * 6 + gi) * 1024;
;         f32x4 gv[2][2];
; #pragma unroll
;         for (int bj = 0; bj < 2; ++bj)
; #pragma unroll
;             for (int n = 0; n < 2; ++n) { gv[bj][n] = *(const f32x4*)(gp + col0 + bj * 128 + n * 16); if (scale) gv[bj][n] = gv[bj][n] * *(const f32x4*)(scale + col0 + bj * 128 + n * 16); }
;         const float* sbase = (gpm < 32 ? Xc : Xl) + (size_t)row0 * 1024 + col0;
; #pragma unroll
;         for (int ai = 0; ai < 2; ++ai) {
;             f32x4 xo[4][2][2];
; #pragma unroll
;             for (int m = 0; m < 4; ++m)
; #pragma unroll
;                 for (int bj = 0; bj < 2; ++bj)
; #pragma unroll
;                     for (int n = 0; n < 2; ++n) xo[m][bj][n] = *(const f32x4*)(sbase + (size_t)(ai * 128 + m * 16) * 1024 + bj * 128 + n * 16);
;             __builtin_amdgcn_sched_barrier(0);
; #pragma unroll
;             for (int m = 0; m < 4; ++m) { float* rowp = X + (size_t)(row0 + ai * 128 + m * 16) * 1024 + col0;
; #pragma unroll
;                 for (int bj = 0; bj < 2; ++bj)
; #pragma unroll
;                     for (int n = 0; n < 2; ++n) *(f32x4*)(rowp + bj * 128 + n * 16) = xo[m][bj][n] + gv[bj][n] * acc[ai][bj][m][n]; }
	s_waitcnt lgkmcnt(0)
	v_mfma_f32_16x16x32_bf16 v[62:65], v[130:133], v[160:163], v[62:65]
	v_mfma_f32_16x16x32_bf16 v[58:61], v[138:141], v[160:163], v[58:61]
	v_mfma_f32_16x16x32_bf16 v[54:57], v[130:133], v[168:171], v[54:57]
	v_mfma_f32_16x16x32_bf16 v[46:49], v[138:141], v[168:171], v[46:49]
	v_mfma_f32_16x16x32_bf16 v[38:41], v[130:133], v[180:183], v[38:41]
	v_mfma_f32_16x16x32_bf16 v[30:33], v[138:141], v[180:183], v[30:33]
	v_mfma_f32_16x16x32_bf16 v[22:25], v[130:133], v[188:191], v[22:25]
	v_mfma_f32_16x16x32_bf16 v[14:17], v[138:141], v[188:191], v[14:17]
	v_mfma_f32_16x16x32_bf16 v[62:65], v[134:137], v[164:167], v[62:65]
	v_mfma_f32_16x16x32_bf16 v[58:61], v[142:145], v[164:167], v[58:61]
	v_mfma_f32_16x16x32_bf16 v[54:57], v[134:137], v[172:175], v[54:57]
	v_mfma_f32_16x16x32_bf16 v[46:49], v[142:145], v[172:175], v[46:49]
	v_mfma_f32_16x16x32_bf16 v[38:41], v[134:137], v[184:187], v[38:41]
	v_mfma_f32_16x16x32_bf16 v[30:33], v[142:145], v[184:187], v[30:33]
	v_mfma_f32_16x16x32_bf16 v[22:25], v[134:137], v[192:195], v[22:25]
	v_mfma_f32_16x16x32_bf16 v[14:17], v[142:145], v[192:195], v[14:17]
	s_barrier
	s_add_u32 s8, s12, 0xb0080
	s_addc_u32 s9, s13, 0
	s_add_i32 s12, s14, s18
	v_lshl_add_u64 v[130:131], s[8:9], 0, v[148:149]
	s_mov_b32 m0, s12
	s_nop 0
	global_load_lds_dwordx4 v[130:131], off
	v_lshl_add_u64 v[130:131], s[8:9], 0, v[146:147]
	s_add_i32 m0, s12, 0x2000
	s_nop 0
	global_load_lds_dwordx4 v[130:131], off
	s_waitcnt vmcnt(6)
	s_barrier
	v_mfma_f32_16x16x32_bf16 v[50:53], v[196:199], v[160:163], v[50:53]
	v_mfma_f32_16x16x32_bf16 v[42:45], v[204:207], v[160:163], v[42:45]
	v_mfma_f32_16x16x32_bf16 v[34:37], v[196:199], v[168:171], v[34:37]
	v_mfma_f32_16x16x32_bf16 v[26:29], v[204:207], v[168:171], v[26:29]
	v_mfma_f32_16x16x32_bf16 v[18:21], v[196:199], v[180:183], v[18:21]
	v_mfma_f32_16x16x32_bf16 v[10:13], v[204:207], v[180:183], v[10:13]
	v_mfma_f32_16x16x32_bf16 v[6:9], v[196:199], v[188:191], v[6:9]
	v_mfma_f32_16x16x32_bf16 v[2:5], v[204:207], v[188:191], v[2:5]
	v_mfma_f32_16x16x32_bf16 v[50:53], v[200:203], v[164:167], v[50:53]
	v_mfma_f32_16x16x32_bf16 v[42:45], v[226:229], v[164:167], v[42:45]
	v_mfma_f32_16x16x32_bf16 v[34:37], v[200:203], v[172:175], v[34:37]
	v_mfma_f32_16x16x32_bf16 v[26:29], v[226:229], v[172:175], v[26:29]
	v_mfma_f32_16x16x32_bf16 v[18:21], v[200:203], v[184:187], v[18:21]
	v_mfma_f32_16x16x32_bf16 v[10:13], v[226:229], v[184:187], v[10:13]
	v_mfma_f32_16x16x32_bf16 v[6:9], v[200:203], v[192:195], v[6:9]
	v_mfma_f32_16x16x32_bf16 v[2:5], v[226:229], v[192:195], v[2:5]
	s_add_i32 s67, s67, 2
	s_add_u32 s65, s65, 0x100
	s_addc_u32 s66, s66, 0
	s_cmp_gt_u32 s67, 41
	s_mov_b64 s[8:9], s[10:11]
	s_barrier
	s_cbranch_scc0 .LBB0_547
	v_readlane_b32 s8, v255, 27
	s_cmp_ge_i32 s64, s8
	s_cselect_b32 s8, s25, 0
	s_add_i32 s10, s64, s8
	s_sub_i32 s8, s10, 32
	s_lshl_b32 s9, s61, 8
	s_ashr_i32 s8, s8, 3
	s_or_b32 s9, s9, s50
	v_mov_b32_e32 v130, v1
	v_mov_b32_e32 v159, v156
	s_mul_i32 s8, s8, 6
	s_cmp_gt_i32 s10, 31
	s_cselect_b32 s8, s8, 0xc0
	v_lshl_add_u32 v130, v130, 2, s9
	s_ashr_i32 s9, s8, 31
	s_lshl_b64 s[8:9], s[8:9], 12
	v_readlane_b32 s12, v255, 14
	v_readlane_b32 s13, v255, 15
	s_add_u32 s8, s12, s8
	v_ashrrev_i32_e32 v131, 31, v130
	s_addc_u32 s9, s13, s9
	v_lshlrev_b64 v[154:155], 2, v[130:131]
	v_lshl_add_u64 v[130:131], s[8:9], 0, v[154:155]
	s_mov_b64 s[8:9], 0x5000
	v_lshl_add_u64 v[132:133], v[130:131], 0, s[8:9]
	s_movk_i32 s8, 0x5000
	v_add_co_u32_e32 v130, vcc, s8, v130
	s_lshl_b32 s8, s10, 8
	s_add_i32 s8, s8, s44
	v_add_u32_e32 v160, s8, v159
	v_ashrrev_i32_e32 v161, 31, v160
	v_readlane_b32 s8, v254, 0
	v_lshlrev_b64 v[160:161], 12, v[160:161]
	v_readlane_b32 s9, v254, 1
	v_addc_co_u32_e32 v131, vcc, 0, v131, vcc
	s_nop 0
	v_lshl_add_u64 v[160:161], s[8:9], 0, v[160:161]
	v_lshl_add_u64 v[154:155], v[160:161], 0, v[154:155]
	v_add_co_u32_e32 v176, vcc, s45, v154
	global_load_dwordx4 v[138:141], v[132:133], off offset:64
	global_load_dwordx4 v[134:137], v[132:133], off offset:512
	global_load_dwordx4 v[142:145], v[130:131], off
	s_nop 0
	global_load_dwordx4 v[130:133], v[132:133], off offset:576
	v_addc_co_u32_e32 v177, vcc, 0, v155, vcc
	v_add_co_u32_e32 v208, vcc, s19, v154
	global_load_dwordx4 v[160:163], v[154:155], off
	global_load_dwordx4 v[164:167], v[154:155], off offset:64
	global_load_dwordx4 v[168:171], v[154:155], off offset:512
	global_load_dwordx4 v[172:175], v[154:155], off offset:576
	v_addc_co_u32_e32 v209, vcc, 0, v155, vcc
	v_add_co_u32_e32 v246, vcc, s88, v154
	global_load_dwordx4 v[180:183], v[176:177], off
	global_load_dwordx4 v[184:187], v[176:177], off offset:64
	global_load_dwordx4 v[188:191], v[176:177], off offset:512
	global_load_dwordx4 v[192:195], v[176:177], off offset:576
	v_addc_co_u32_e32 v247, vcc, 0, v155, vcc
	global_load_dwordx4 v[196:199], v[208:209], off
	global_load_dwordx4 v[200:203], v[208:209], off offset:64
	global_load_dwordx4 v[204:207], v[208:209], off offset:512
	global_load_dwordx4 v[226:229], v[208:209], off offset:576
	global_load_dwordx4 v[230:233], v[246:247], off
	global_load_dwordx4 v[234:237], v[246:247], off offset:64
	global_load_dwordx4 v[238:241], v[246:247], off offset:512
	global_load_dwordx4 v[242:245], v[246:247], off offset:576
	s_mov_b64 s[8:9], 0x30000
	v_lshl_add_u64 v[248:249], v[154:155], 0, s[84:85]
	v_lshl_add_u64 v[250:251], v[154:155], 0, s[82:83]
	v_lshl_add_u64 v[252:253], v[154:155], 0, s[8:9]
	s_waitcnt vmcnt(0)
;     __device__ __forceinline__ void operator()(const AccT& acc, const Unit& u, int wr, int wc, int fr, int fq) const {
;     ...
;         for (int ai = 0; ai < 2; ++ai) {
;             f32x4 xo[4][2][2];
; #pragma unroll
;             for (int m = 0; m < 4; ++m)
; #pragma unroll
;                 for (int bj = 0; bj < 2; ++bj)
; #pragma unroll
;                     for (int n = 0; n < 2; ++n) xo[m][bj][n] = *(const f32x4*)(sbase + (size_t)(ai * 128 + m * 16) * 1024 + bj * 128 + n * 16);
;             __builtin_amdgcn_sched_barrier(0);
; #pragma unroll
;             for (int m = 0; m < 4; ++m) { float* rowp = X + (size_t)(row0 + ai * 128 + m * 16) * 1024 + col0;
; #pragma unroll
;                 for (int bj = 0; bj < 2; ++bj)
; #pragma unroll
;                     for (int n = 0; n < 2; ++n) *(f32x4*)(rowp + bj * 128 + n * 16) = xo[m][bj][n] + gv[bj][n] * acc[ai][bj][m][n]; }
	v_pk_fma_f32 v[108:109], v[108:109], v[132:133], v[174:175]
	v_pk_fma_f32 v[106:107], v[106:107], v[130:131], v[172:173]
	v_pk_fma_f32 v[92:93], v[92:93], v[132:133], v[194:195]
	v_pk_fma_f32 v[90:91], v[90:91], v[130:131], v[192:193]
	v_pk_fma_f32 v[76:77], v[76:77], v[132:133], v[228:229]
	v_pk_fma_f32 v[74:75], v[74:75], v[130:131], v[226:227]
	global_store_dwordx4 v[154:155], v[106:109], off offset:576
	global_store_dwordx4 v[248:249], v[90:93], off offset:576
	global_store_dwordx4 v[250:251], v[74:77], off offset:576
	v_pk_fma_f32 v[108:109], v[120:121], v[144:145], v[182:183]
	v_pk_fma_f32 v[106:107], v[118:119], v[142:143], v[180:181]
	v_pk_fma_f32 v[92:93], v[104:105], v[144:145], v[198:199]
	v_pk_fma_f32 v[90:91], v[102:103], v[142:143], v[196:197]
	v_pk_fma_f32 v[76:77], v[88:89], v[144:145], v[232:233]
	v_pk_fma_f32 v[74:75], v[86:87], v[142:143], v[230:231]
	v_pk_fma_f32 v[128:129], v[128:129], v[144:145], v[162:163]
	v_pk_fma_f32 v[126:127], v[126:127], v[142:143], v[160:161]
	v_pk_fma_f32 v[124:125], v[124:125], v[140:141], v[166:167]
	v_pk_fma_f32 v[122:123], v[122:123], v[138:139], v[164:165]
	v_pk_fma_f32 v[116:117], v[116:117], v[136:137], v[170:171]
	v_pk_fma_f32 v[114:115], v[114:115], v[134:135], v[168:169]
	global_store_dwordx4 v[176:177], v[106:109], off
	v_pk_fma_f32 v[100:101], v[100:101], v[136:137], v[190:191]
	v_pk_fma_f32 v[98:99], v[98:99], v[134:135], v[188:189]
	v_pk_fma_f32 v[108:109], v[112:113], v[140:141], v[186:187]
	v_pk_fma_f32 v[106:107], v[110:111], v[138:139], v[184:185]
	global_store_dwordx4 v[208:209], v[90:93], off
	v_pk_fma_f32 v[84:85], v[84:85], v[136:137], v[206:207]
	v_pk_fma_f32 v[82:83], v[82:83], v[134:135], v[204:205]
	v_pk_fma_f32 v[92:93], v[96:97], v[140:141], v[202:203]
	v_pk_fma_f32 v[90:91], v[94:95], v[138:139], v[200:201]
	global_store_dwordx4 v[246:247], v[74:77], off
	v_pk_fma_f32 v[72:73], v[72:73], v[136:137], v[240:241]
	v_pk_fma_f32 v[70:71], v[70:71], v[134:135], v[238:239]
	v_pk_fma_f32 v[76:77], v[80:81], v[140:141], v[236:237]
	v_pk_fma_f32 v[74:75], v[78:79], v[138:139], v[234:235]
	v_pk_fma_f32 v[68:69], v[68:69], v[132:133], v[244:245]
	v_pk_fma_f32 v[66:67], v[66:67], v[130:131], v[242:243]
	global_store_dwordx4 v[154:155], v[126:129], off
	global_store_dwordx4 v[154:155], v[122:125], off offset:64
	global_store_dwordx4 v[154:155], v[114:117], off offset:512
	global_store_dwordx4 v[248:249], v[106:109], off offset:64
	global_store_dwordx4 v[248:249], v[98:101], off offset:512
	global_store_dwordx4 v[250:251], v[90:93], off offset:64
	global_store_dwordx4 v[250:251], v[82:85], off offset:512
	global_store_dwordx4 v[252:253], v[74:77], off offset:64
	global_store_dwordx4 v[252:253], v[70:73], off offset:512
	global_store_dwordx4 v[252:253], v[66:69], off offset:576
	s_mov_b64 s[8:9], 0x80000
	v_lshl_add_u64 v[160:161], v[154:155], 0, s[8:9]
	s_mov_b32 s8, 0x80000
	v_add_co_u32_e32 v162, vcc, s8, v154
	s_mov_b64 s[8:9], 0x90000
	s_nop 0
	v_addc_co_u32_e32 v163, vcc, 0, v155, vcc
	v_lshl_add_u64 v[164:165], v[154:155], 0, s[8:9]
	s_mov_b32 s8, 0x90000
	v_add_co_u32_e32 v166, vcc, s8, v154
	s_mov_b64 s[8:9], 0xa0000
	s_nop 0
	v_addc_co_u32_e32 v167, vcc, 0, v155, vcc
	v_lshl_add_u64 v[168:169], v[154:155], 0, s[8:9]
	s_mov_b32 s8, 0xa0000
	v_add_co_u32_e32 v170, vcc, s8, v154
	s_mov_b64 s[8:9], 0xb0000
	s_nop 0
	v_addc_co_u32_e32 v171, vcc, 0, v155, vcc
	v_lshl_add_u64 v[172:173], v[154:155], 0, s[8:9]
	s_mov_b32 s8, 0xb0000
	v_add_co_u32_e32 v154, vcc, s8, v154
	global_load_dwordx4 v[66:69], v[162:163], off
	global_load_dwordx4 v[70:73], v[162:163], off offset:64
	global_load_dwordx4 v[74:77], v[162:163], off offset:512
	global_load_dwordx4 v[78:81], v[162:163], off offset:576
	v_addc_co_u32_e32 v155, vcc, 0, v155, vcc
	global_load_dwordx4 v[82:85], v[166:167], off
	global_load_dwordx4 v[86:89], v[166:167], off offset:64
	global_load_dwordx4 v[90:93], v[166:167], off offset:512
	global_load_dwordx4 v[94:97], v[166:167], off offset:576
	global_load_dwordx4 v[98:101], v[170:171], off
	global_load_dwordx4 v[102:105], v[170:171], off offset:64
	global_load_dwordx4 v[106:109], v[170:171], off offset:512
	global_load_dwordx4 v[110:113], v[170:171], off offset:576
	global_load_dwordx4 v[114:117], v[154:155], off
	global_load_dwordx4 v[118:121], v[154:155], off offset:64
	global_load_dwordx4 v[122:125], v[154:155], off offset:512
	global_load_dwordx4 v[126:129], v[154:155], off offset:576
	s_waitcnt vmcnt(0)
; #define PG8_WAIT_V(n) asm volatile("s_waitcnt vmcnt(" #n ")" ::: "memory")
; #define PG8_BAR __builtin_amdgcn_s_barrier()
; template <class Epi>
; __device__ __forceinline__ void gemm_phase(LAS unsigned char* lds, const Gemm g, const Epi& E) {
;     ...
;         E(acc, cur, wr, wc, fr, fq);
;         if (!has_next) break;
; #pragma unroll
;         for (int a = 0; a < 2; ++a)
; #pragma unroll
;             for (int b = 0; b < 2; ++b)
; #pragma unroll
;                 for (int m = 0; m < 4; ++m)
; #pragma unroll
;                     for (int n = 0; n < 2; ++n) acc[a][b][m][n] = (f32x4){0.f, 0.f, 0.f, 0.f};
;         cur = nxt; cA = nA; cB = nB; ++ui;
;     }
;     PG8_WAIT_V(0);
;     if (wr == 0) PG8_BAR;
;     __device__ __forceinline__ void operator()(const AccT& acc, const Unit& u, int wr, int wc, int fr, int fq) const {
;     ...
;             for (int m = 0; m < 4; ++m) { float* rowp = X + (size_t)(row0 + ai * 128 + m * 16) * 1024 + col0;
; #pragma unroll
;                 for (int bj = 0; bj < 2; ++bj)
; #pragma unroll
;                     for (int n = 0; n < 2; ++n) *(f32x4*)(rowp + bj * 128 + n * 16) = xo[m][bj][n] + gv[bj][n] * acc[ai][bj][m][n]; }
	v_pk_fma_f32 v[44:45], v[44:45], v[132:133], v[80:81]
	v_pk_fma_f32 v[42:43], v[42:43], v[130:131], v[78:79]
	v_pk_fma_f32 v[28:29], v[28:29], v[132:133], v[96:97]
	v_pk_fma_f32 v[26:27], v[26:27], v[130:131], v[94:95]
	v_pk_fma_f32 v[12:13], v[12:13], v[132:133], v[112:113]
	v_pk_fma_f32 v[10:11], v[10:11], v[130:131], v[110:111]
	global_store_dwordx4 v[160:161], v[42:45], off offset:576
	global_store_dwordx4 v[164:165], v[26:29], off offset:576
	global_store_dwordx4 v[168:169], v[10:13], off offset:576
	v_pk_fma_f32 v[44:45], v[56:57], v[144:145], v[84:85]
	v_pk_fma_f32 v[42:43], v[54:55], v[142:143], v[82:83]
	v_pk_fma_f32 v[28:29], v[40:41], v[144:145], v[100:101]
	v_pk_fma_f32 v[26:27], v[38:39], v[142:143], v[98:99]
	v_pk_fma_f32 v[12:13], v[24:25], v[144:145], v[116:117]
	v_pk_fma_f32 v[10:11], v[22:23], v[142:143], v[114:115]
	v_pk_fma_f32 v[64:65], v[64:65], v[144:145], v[68:69]
	v_pk_fma_f32 v[62:63], v[62:63], v[142:143], v[66:67]
	v_pk_fma_f32 v[60:61], v[60:61], v[140:141], v[72:73]
	v_pk_fma_f32 v[58:59], v[58:59], v[138:139], v[70:71]
	v_pk_fma_f32 v[52:53], v[52:53], v[136:137], v[76:77]
	v_pk_fma_f32 v[50:51], v[50:51], v[134:135], v[74:75]
	global_store_dwordx4 v[166:167], v[42:45], off
	v_pk_fma_f32 v[36:37], v[36:37], v[136:137], v[92:93]
	v_pk_fma_f32 v[34:35], v[34:35], v[134:135], v[90:91]
	v_pk_fma_f32 v[44:45], v[48:49], v[140:141], v[88:89]
	v_pk_fma_f32 v[42:43], v[46:47], v[138:139], v[86:87]
	global_store_dwordx4 v[170:171], v[26:29], off
	v_pk_fma_f32 v[20:21], v[20:21], v[136:137], v[108:109]
	v_pk_fma_f32 v[18:19], v[18:19], v[134:135], v[106:107]
	v_pk_fma_f32 v[28:29], v[32:33], v[140:141], v[104:105]
	v_pk_fma_f32 v[26:27], v[30:31], v[138:139], v[102:103]
	global_store_dwordx4 v[154:155], v[10:13], off
	v_pk_fma_f32 v[8:9], v[8:9], v[136:137], v[124:125]
	v_pk_fma_f32 v[6:7], v[6:7], v[134:135], v[122:123]
	v_pk_fma_f32 v[12:13], v[16:17], v[140:141], v[120:121]
	v_pk_fma_f32 v[10:11], v[14:15], v[138:139], v[118:119]
	v_pk_fma_f32 v[4:5], v[4:5], v[132:133], v[128:129]
	v_pk_fma_f32 v[2:3], v[2:3], v[130:131], v[126:127]
	global_store_dwordx4 v[162:163], v[62:65], off
	global_store_dwordx4 v[160:161], v[58:61], off offset:64
	global_store_dwordx4 v[160:161], v[50:53], off offset:512
	global_store_dwordx4 v[164:165], v[42:45], off offset:64
	global_store_dwordx4 v[164:165], v[34:37], off offset:512
	global_store_dwordx4 v[168:169], v[26:29], off offset:64
	global_store_dwordx4 v[168:169], v[18:21], off offset:512
	global_store_dwordx4 v[172:173], v[10:13], off offset:64
	global_store_dwordx4 v[172:173], v[6:9], off offset:512
	global_store_dwordx4 v[172:173], v[2:5], off offset:576
	s_and_b64 vcc, exec, s[2:3]
	s_mov_b32 s61, s59
	s_mov_b32 s64, s60
	s_mov_b64 s[10:11], s[6:7]
	s_mov_b64 s[8:9], s[4:5]
	s_cbranch_vccz .LBB0_540
	s_waitcnt vmcnt(0)
	s_cmpk_gt_u32 s1, 0xff
	s_movk_i32 s36, 0xf000
	s_cbranch_scc1 .LBB0_551
	s_barrier
